# census loads batched in first barrier; XCD-local seams use a monotonic-counter wait (no leader election) when the placement flag is set; inversion trimmed
# speedup vs baseline: 1.0169x; 1.0011x over previous
.LBB0_86:
	v_readlane_b32 s6, v242, 17
	s_waitcnt lgkmcnt(0)
	v_readlane_b32 s4, v242, 20
	v_readlane_b32 s5, v242, 21
	s_nop 4
	global_load_dword v0, v16, s[4:5] sc1
	v_readlane_b32 s4, v242, 22
	v_readlane_b32 s5, v242, 23
	s_nop 4
	global_load_dword v1, v16, s[4:5] sc1
	v_readlane_b32 s4, v242, 24
	v_readlane_b32 s5, v242, 25
	s_nop 4
	global_load_dword v2, v16, s[4:5] sc1
	v_readlane_b32 s4, v242, 26
	v_readlane_b32 s5, v242, 27
	s_nop 4
	global_load_dword v3, v16, s[4:5] sc1
	v_readlane_b32 s4, v242, 28
	v_readlane_b32 s5, v242, 29
	s_nop 4
	global_load_dword v4, v16, s[4:5] sc1
	v_readlane_b32 s4, v242, 30
	v_readlane_b32 s5, v242, 31
	s_nop 4
	global_load_dword v5, v16, s[4:5] sc1
	v_readlane_b32 s4, v242, 32
	v_readlane_b32 s5, v242, 33
	s_nop 4
	global_load_dword v6, v16, s[4:5] sc1
	v_readlane_b32 s4, v242, 34
	v_readlane_b32 s5, v242, 35
	s_nop 4
	global_load_dword v7, v16, s[4:5] sc1
	v_readlane_b32 s4, v242, 36
	v_readlane_b32 s5, v242, 37
	s_nop 4
	global_load_dword v8, v16, s[4:5] sc1
	v_readlane_b32 s4, v242, 38
	v_readlane_b32 s5, v242, 39
	s_nop 4
	global_load_dword v9, v16, s[4:5] sc1
	v_readlane_b32 s4, v242, 40
	v_readlane_b32 s5, v242, 41
	s_nop 4
	global_load_dword v10, v16, s[4:5] sc1
	v_readlane_b32 s4, v242, 42
	v_readlane_b32 s5, v242, 43
	s_nop 4
	global_load_dword v11, v16, s[4:5] sc1
	v_readlane_b32 s4, v242, 44
	v_readlane_b32 s5, v242, 45
	s_nop 4
	global_load_dword v12, v16, s[4:5] sc1
	v_readlane_b32 s4, v242, 46
	v_readlane_b32 s5, v242, 47
	s_nop 4
	global_load_dword v13, v16, s[4:5] sc1
	v_readlane_b32 s4, v242, 48
	v_readlane_b32 s5, v242, 49
	s_nop 4
	global_load_dword v14, v16, s[4:5] sc1
	v_readlane_b32 s4, v242, 50
	v_readlane_b32 s5, v242, 51
	s_nop 4
	global_load_dword v15, v16, s[4:5] sc1
	s_mov_b64 s[4:5], -1
	s_waitcnt vmcnt(0)
	v_add_u32_e32 v17, v1, v0
	v_add_u32_e32 v17, v17, v2
	v_add_u32_e32 v17, v17, v3
	v_add_u32_e32 v17, v17, v4
	v_add_u32_e32 v17, v17, v5
	v_add_u32_e32 v17, v17, v6
	v_add_u32_e32 v17, v17, v7
	v_add_u32_e32 v17, v17, v8
	v_add_u32_e32 v17, v17, v9
	v_add_u32_e32 v17, v17, v10
	v_add_u32_e32 v17, v17, v11
	v_add_u32_e32 v17, v17, v12
	v_add_u32_e32 v17, v17, v13
	v_add_u32_e32 v17, v17, v14
	v_add_u32_e32 v17, v17, v15
	v_cmp_eq_u32_e32 vcc, s6, v17
	s_mov_b64 s[6:7], -1
	s_cbranch_vccnz .LBB0_85
	s_and_b32 s4, s3, 0xff
	s_cmp_eq_u32 s4, 0
	s_mov_b64 s[4:5], -1
	s_mov_b64 s[8:9], -1
	s_sleep 1
	s_cbranch_scc0 .LBB0_90
	v_readlane_b32 s4, v242, 18
	v_readlane_b32 s5, v242, 19
	s_nop 4
	global_load_dword v17, v16, s[4:5] sc1
	s_waitcnt vmcnt(0)
	v_cmp_eq_u32_e32 vcc, 0, v17
	s_cbranch_vccnz .LBB0_92
	s_mov_b64 s[8:9], 0
	s_mov_b64 s[4:5], -1

.LBB0_307:
	v_mov_b32_e32 v33, s19
	v_mov_b32_e32 v193, 0
	v_lshl_add_u32 v84, v152, 1, s19
	ds_read_b128 v[74:77], v33 offset:17664
	ds_read_b128 v[78:81], v33 offset:17920
	ds_read_b128 v[86:89], v33 offset:18176
	ds_read_b128 v[90:93], v33 offset:18432
	ds_read_b128 v[154:157], v33 offset:18688
	ds_read_b128 v[180:183], v33 offset:18704
	ds_read_b128 v[184:187], v33 offset:18944
	ds_read_b128 v[188:191], v33 offset:18960
	ds_read_b128 v[198:201], v33 offset:19200
	ds_read_b128 v[202:205], v33 offset:19216
	ds_read_b128 v[206:209], v33 offset:19456
	ds_read_b128 v[210:213], v33 offset:19472
	v_mov_b64_e32 v[98:99], 0
	v_mov_b64_e32 v[100:101], 0
	v_mov_b64_e32 v[102:103], 0
	v_mov_b64_e32 v[104:105], 0
	v_mov_b64_e32 v[106:107], 0
	v_mov_b64_e32 v[108:109], 0
	v_mov_b64_e32 v[110:111], 0
	v_mov_b64_e32 v[112:113], 0
	v_mov_b64_e32 v[114:115], 0
	v_mov_b64_e32 v[116:117], 0
	v_mov_b64_e32 v[118:119], 0
	v_mov_b64_e32 v[120:121], 0
	v_mov_b64_e32 v[122:123], 0
	v_mov_b64_e32 v[124:125], 0
	v_mov_b64_e32 v[126:127], 0
	v_mov_b64_e32 v[128:129], 0
	v_mov_b64_e32 v[130:131], 0
	v_mov_b64_e32 v[132:133], 0
	v_mov_b64_e32 v[134:135], 0
	v_mov_b64_e32 v[136:137], 0
	v_mov_b64_e32 v[138:139], 0
	v_mov_b64_e32 v[140:141], 0
	v_mov_b64_e32 v[142:143], 0
	v_mov_b64_e32 v[162:163], 0
	v_mov_b64_e32 v[164:165], 0
	v_mov_b64_e32 v[166:167], 0
	v_mov_b64_e32 v[168:169], 0
	v_mov_b64_e32 v[170:171], 0
	v_mov_b64_e32 v[172:173], 0
	v_mov_b64_e32 v[174:175], 0
	v_mov_b64_e32 v[176:177], 0
	v_mov_b64_e32 v[178:179], 0
	v_cmp_eq_u32_e32 vcc, 0, v152
	s_nop 1
	v_cndmask_b32_e64 v98, 0, 1.0, vcc
	v_cmp_eq_u32_e32 vcc, 1, v152
	v_cvt_pk_bf16_f32 v25, v98, v98
	ds_write_b16 v84, v25
	v_cndmask_b32_e64 v192, 0, 1.0, vcc
	s_waitcnt lgkmcnt(12)
	v_pk_fma_f32 v[22:23], v[74:75], v[98:99], v[192:193] neg_lo:[1,0,0] neg_hi:[1,0,0]
	v_pk_fma_f32 v[30:31], v[76:77], v[100:101], 0 neg_lo:[1,0,0] neg_hi:[1,0,0]
	v_cmp_eq_u32_e32 vcc, 2, v152
	v_pk_add_f32 v[82:83], v[22:23], v[30:31]
	v_add_f32_e32 v99, v82, v83
	v_cvt_pk_bf16_f32 v25, v99, v99
	ds_write_b16 v84, v25 offset:144
	v_cndmask_b32_e64 v192, 0, 1.0, vcc
	s_waitcnt lgkmcnt(12)
	v_pk_fma_f32 v[22:23], v[78:79], v[98:99], v[192:193] neg_lo:[1,0,0] neg_hi:[1,0,0]
	v_pk_fma_f32 v[30:31], v[80:81], v[100:101], 0 neg_lo:[1,0,0] neg_hi:[1,0,0]
	v_cmp_eq_u32_e32 vcc, 3, v152
	v_pk_add_f32 v[82:83], v[22:23], v[30:31]
	v_add_f32_e32 v100, v82, v83
	v_cvt_pk_bf16_f32 v25, v100, v100
	ds_write_b16 v84, v25 offset:288
	v_cndmask_b32_e64 v192, 0, 1.0, vcc
	s_waitcnt lgkmcnt(12)
	v_pk_fma_f32 v[22:23], v[86:87], v[98:99], v[192:193] neg_lo:[1,0,0] neg_hi:[1,0,0]
	v_pk_fma_f32 v[30:31], v[88:89], v[100:101], 0 neg_lo:[1,0,0] neg_hi:[1,0,0]
	v_cmp_eq_u32_e32 vcc, 4, v152
	v_pk_add_f32 v[82:83], v[22:23], v[30:31]
	v_add_f32_e32 v101, v82, v83
	v_cvt_pk_bf16_f32 v25, v101, v101
	ds_write_b16 v84, v25 offset:432
	v_cndmask_b32_e64 v192, 0, 1.0, vcc
	s_waitcnt lgkmcnt(12)
	v_pk_fma_f32 v[22:23], v[90:91], v[98:99], v[192:193] neg_lo:[1,0,0] neg_hi:[1,0,0]
	v_pk_fma_f32 v[30:31], v[92:93], v[100:101], 0 neg_lo:[1,0,0] neg_hi:[1,0,0]
	v_cmp_eq_u32_e32 vcc, 5, v152
	v_pk_add_f32 v[82:83], v[22:23], v[30:31]
	v_add_f32_e32 v102, v82, v83
	v_cvt_pk_bf16_f32 v25, v102, v102
	ds_write_b16 v84, v25 offset:576
	v_cndmask_b32_e64 v192, 0, 1.0, vcc
	s_waitcnt lgkmcnt(11)
	v_pk_fma_f32 v[22:23], v[154:155], v[98:99], v[192:193] neg_lo:[1,0,0] neg_hi:[1,0,0]
	v_pk_fma_f32 v[30:31], v[156:157], v[100:101], 0 neg_lo:[1,0,0] neg_hi:[1,0,0]
	v_pk_fma_f32 v[22:23], v[180:181], v[102:103], v[22:23] neg_lo:[1,0,0] neg_hi:[1,0,0]
	v_pk_fma_f32 v[30:31], v[182:183], v[104:105], v[30:31] neg_lo:[1,0,0] neg_hi:[1,0,0]
	v_cmp_eq_u32_e32 vcc, 6, v152
	v_pk_add_f32 v[82:83], v[22:23], v[30:31]
	v_add_f32_e32 v103, v82, v83
	v_cvt_pk_bf16_f32 v25, v103, v103
	ds_write_b16 v84, v25 offset:720
	v_cndmask_b32_e64 v192, 0, 1.0, vcc
	s_waitcnt lgkmcnt(10)
	v_pk_fma_f32 v[22:23], v[184:185], v[98:99], v[192:193] neg_lo:[1,0,0] neg_hi:[1,0,0]
	v_pk_fma_f32 v[30:31], v[186:187], v[100:101], 0 neg_lo:[1,0,0] neg_hi:[1,0,0]
	v_pk_fma_f32 v[22:23], v[188:189], v[102:103], v[22:23] neg_lo:[1,0,0] neg_hi:[1,0,0]
	v_pk_fma_f32 v[30:31], v[190:191], v[104:105], v[30:31] neg_lo:[1,0,0] neg_hi:[1,0,0]
	v_cmp_eq_u32_e32 vcc, 7, v152
	v_pk_add_f32 v[82:83], v[22:23], v[30:31]
	v_add_f32_e32 v104, v82, v83
	v_cvt_pk_bf16_f32 v25, v104, v104
	ds_write_b16 v84, v25 offset:864
	v_cndmask_b32_e64 v192, 0, 1.0, vcc
	s_waitcnt lgkmcnt(9)
	v_pk_fma_f32 v[22:23], v[198:199], v[98:99], v[192:193] neg_lo:[1,0,0] neg_hi:[1,0,0]
	v_pk_fma_f32 v[30:31], v[200:201], v[100:101], 0 neg_lo:[1,0,0] neg_hi:[1,0,0]
	v_pk_fma_f32 v[22:23], v[202:203], v[102:103], v[22:23] neg_lo:[1,0,0] neg_hi:[1,0,0]
	v_pk_fma_f32 v[30:31], v[204:205], v[104:105], v[30:31] neg_lo:[1,0,0] neg_hi:[1,0,0]
	v_cmp_eq_u32_e32 vcc, 8, v152
	v_pk_add_f32 v[82:83], v[22:23], v[30:31]
	v_add_f32_e32 v105, v82, v83
	v_cvt_pk_bf16_f32 v25, v105, v105
	ds_write_b16 v84, v25 offset:1008
	v_cndmask_b32_e64 v192, 0, 1.0, vcc
	ds_read_b128 v[0:3], v33 offset:19712
	ds_read_b128 v[4:7], v33 offset:19728
	ds_read_b128 v[8:11], v33 offset:19744
	s_waitcnt lgkmcnt(11)
	v_pk_fma_f32 v[22:23], v[206:207], v[98:99], v[192:193] neg_lo:[1,0,0] neg_hi:[1,0,0]
	v_pk_fma_f32 v[30:31], v[208:209], v[100:101], 0 neg_lo:[1,0,0] neg_hi:[1,0,0]
	v_pk_fma_f32 v[22:23], v[210:211], v[102:103], v[22:23] neg_lo:[1,0,0] neg_hi:[1,0,0]
	v_pk_fma_f32 v[30:31], v[212:213], v[104:105], v[30:31] neg_lo:[1,0,0] neg_hi:[1,0,0]
	v_cmp_eq_u32_e32 vcc, 9, v152
	v_pk_add_f32 v[82:83], v[22:23], v[30:31]
	v_add_f32_e32 v106, v82, v83
	v_cvt_pk_bf16_f32 v25, v106, v106
	ds_write_b16 v84, v25 offset:1152
	v_cndmask_b32_e64 v192, 0, 1.0, vcc
	s_waitcnt lgkmcnt(2)
	v_pk_fma_f32 v[22:23], v[0:1], v[98:99], v[192:193] neg_lo:[1,0,0] neg_hi:[1,0,0]
	v_pk_fma_f32 v[30:31], v[2:3], v[100:101], 0 neg_lo:[1,0,0] neg_hi:[1,0,0]
	ds_read_b128 v[0:3], v33 offset:19968
	v_pk_fma_f32 v[22:23], v[4:5], v[102:103], v[22:23] neg_lo:[1,0,0] neg_hi:[1,0,0]
	v_pk_fma_f32 v[30:31], v[6:7], v[104:105], v[30:31] neg_lo:[1,0,0] neg_hi:[1,0,0]
	ds_read_b128 v[4:7], v33 offset:19984
	s_waitcnt lgkmcnt(3)
	v_pk_fma_f32 v[22:23], v[8:9], v[106:107], v[22:23] neg_lo:[1,0,0] neg_hi:[1,0,0]
	v_pk_fma_f32 v[30:31], v[10:11], v[108:109], v[30:31] neg_lo:[1,0,0] neg_hi:[1,0,0]
	ds_read_b128 v[8:11], v33 offset:20000
	v_cmp_eq_u32_e32 vcc, 10, v152
	v_pk_add_f32 v[82:83], v[22:23], v[30:31]
	v_add_f32_e32 v107, v82, v83
	v_cvt_pk_bf16_f32 v25, v107, v107
	ds_write_b16 v84, v25 offset:1296
	v_cndmask_b32_e64 v192, 0, 1.0, vcc
	s_waitcnt lgkmcnt(2)
	v_pk_fma_f32 v[22:23], v[0:1], v[98:99], v[192:193] neg_lo:[1,0,0] neg_hi:[1,0,0]
	v_pk_fma_f32 v[30:31], v[2:3], v[100:101], 0 neg_lo:[1,0,0] neg_hi:[1,0,0]
	ds_read_b128 v[0:3], v33 offset:20224
	v_pk_fma_f32 v[22:23], v[4:5], v[102:103], v[22:23] neg_lo:[1,0,0] neg_hi:[1,0,0]
	v_pk_fma_f32 v[30:31], v[6:7], v[104:105], v[30:31] neg_lo:[1,0,0] neg_hi:[1,0,0]
	ds_read_b128 v[4:7], v33 offset:20240
	s_waitcnt lgkmcnt(3)
	v_pk_fma_f32 v[22:23], v[8:9], v[106:107], v[22:23] neg_lo:[1,0,0] neg_hi:[1,0,0]
	v_pk_fma_f32 v[30:31], v[10:11], v[108:109], v[30:31] neg_lo:[1,0,0] neg_hi:[1,0,0]
	ds_read_b128 v[8:11], v33 offset:20256
	v_cmp_eq_u32_e32 vcc, 11, v152
	v_pk_add_f32 v[82:83], v[22:23], v[30:31]
	v_add_f32_e32 v108, v82, v83
	v_cvt_pk_bf16_f32 v25, v108, v108
	ds_write_b16 v84, v25 offset:1440
	v_cndmask_b32_e64 v192, 0, 1.0, vcc
	s_waitcnt lgkmcnt(2)
	v_pk_fma_f32 v[22:23], v[0:1], v[98:99], v[192:193] neg_lo:[1,0,0] neg_hi:[1,0,0]
	v_pk_fma_f32 v[30:31], v[2:3], v[100:101], 0 neg_lo:[1,0,0] neg_hi:[1,0,0]
	ds_read_b128 v[0:3], v33 offset:20480
	v_pk_fma_f32 v[22:23], v[4:5], v[102:103], v[22:23] neg_lo:[1,0,0] neg_hi:[1,0,0]
	v_pk_fma_f32 v[30:31], v[6:7], v[104:105], v[30:31] neg_lo:[1,0,0] neg_hi:[1,0,0]
	ds_read_b128 v[4:7], v33 offset:20496
	s_waitcnt lgkmcnt(3)
	v_pk_fma_f32 v[22:23], v[8:9], v[106:107], v[22:23] neg_lo:[1,0,0] neg_hi:[1,0,0]
	v_pk_fma_f32 v[30:31], v[10:11], v[108:109], v[30:31] neg_lo:[1,0,0] neg_hi:[1,0,0]
	ds_read_b128 v[8:11], v33 offset:20512
	v_cmp_eq_u32_e32 vcc, 12, v152
	v_pk_add_f32 v[82:83], v[22:23], v[30:31]
	v_add_f32_e32 v109, v82, v83
	v_cvt_pk_bf16_f32 v25, v109, v109
	ds_write_b16 v84, v25 offset:1584
	v_cndmask_b32_e64 v192, 0, 1.0, vcc
	ds_read_b128 v[12:15], v33 offset:20784
	s_waitcnt lgkmcnt(3)
	v_pk_fma_f32 v[22:23], v[0:1], v[98:99], v[192:193] neg_lo:[1,0,0] neg_hi:[1,0,0]
	v_pk_fma_f32 v[30:31], v[2:3], v[100:101], 0 neg_lo:[1,0,0] neg_hi:[1,0,0]
	ds_read_b128 v[0:3], v33 offset:20736
	v_pk_fma_f32 v[22:23], v[4:5], v[102:103], v[22:23] neg_lo:[1,0,0] neg_hi:[1,0,0]
	v_pk_fma_f32 v[30:31], v[6:7], v[104:105], v[30:31] neg_lo:[1,0,0] neg_hi:[1,0,0]
	ds_read_b128 v[4:7], v33 offset:20752
	s_waitcnt lgkmcnt(4)
	v_pk_fma_f32 v[22:23], v[8:9], v[106:107], v[22:23] neg_lo:[1,0,0] neg_hi:[1,0,0]
	v_pk_fma_f32 v[30:31], v[10:11], v[108:109], v[30:31] neg_lo:[1,0,0] neg_hi:[1,0,0]
	ds_read_b128 v[8:11], v33 offset:20768
	v_cmp_eq_u32_e32 vcc, 13, v152
	v_pk_add_f32 v[82:83], v[22:23], v[30:31]
	v_add_f32_e32 v110, v82, v83
	v_cvt_pk_bf16_f32 v25, v110, v110
	ds_write_b16 v84, v25 offset:1728
	v_cndmask_b32_e64 v192, 0, 1.0, vcc
	s_waitcnt lgkmcnt(2)
	v_pk_fma_f32 v[22:23], v[0:1], v[98:99], v[192:193] neg_lo:[1,0,0] neg_hi:[1,0,0]
	v_pk_fma_f32 v[30:31], v[2:3], v[100:101], 0 neg_lo:[1,0,0] neg_hi:[1,0,0]
	ds_read_b128 v[0:3], v33 offset:20992
	v_pk_fma_f32 v[22:23], v[4:5], v[102:103], v[22:23] neg_lo:[1,0,0] neg_hi:[1,0,0]
	v_pk_fma_f32 v[30:31], v[6:7], v[104:105], v[30:31] neg_lo:[1,0,0] neg_hi:[1,0,0]
	ds_read_b128 v[4:7], v33 offset:21008
	s_waitcnt lgkmcnt(6)
	v_pk_fma_f32 v[22:23], v[8:9], v[106:107], v[22:23] neg_lo:[1,0,0] neg_hi:[1,0,0]
	v_pk_fma_f32 v[30:31], v[10:11], v[108:109], v[30:31] neg_lo:[1,0,0] neg_hi:[1,0,0]
	ds_read_b128 v[8:11], v33 offset:21024
	v_pk_fma_f32 v[22:23], v[12:13], v[110:111], v[22:23] neg_lo:[1,0,0] neg_hi:[1,0,0]
	v_pk_fma_f32 v[30:31], v[14:15], v[112:113], v[30:31] neg_lo:[1,0,0] neg_hi:[1,0,0]
	ds_read_b128 v[12:15], v33 offset:21040
	v_cmp_eq_u32_e32 vcc, 14, v152
	v_pk_add_f32 v[82:83], v[22:23], v[30:31]
	v_add_f32_e32 v111, v82, v83
	v_cvt_pk_bf16_f32 v25, v111, v111
	ds_write_b16 v84, v25 offset:1872
	v_cndmask_b32_e64 v192, 0, 1.0, vcc
	s_waitcnt lgkmcnt(3)
	v_pk_fma_f32 v[22:23], v[0:1], v[98:99], v[192:193] neg_lo:[1,0,0] neg_hi:[1,0,0]
	v_pk_fma_f32 v[30:31], v[2:3], v[100:101], 0 neg_lo:[1,0,0] neg_hi:[1,0,0]
	ds_read_b128 v[0:3], v33 offset:21248
	v_pk_fma_f32 v[22:23], v[4:5], v[102:103], v[22:23] neg_lo:[1,0,0] neg_hi:[1,0,0]
	v_pk_fma_f32 v[30:31], v[6:7], v[104:105], v[30:31] neg_lo:[1,0,0] neg_hi:[1,0,0]
	ds_read_b128 v[4:7], v33 offset:21264
	s_waitcnt lgkmcnt(3)
	v_pk_fma_f32 v[22:23], v[8:9], v[106:107], v[22:23] neg_lo:[1,0,0] neg_hi:[1,0,0]
	v_pk_fma_f32 v[30:31], v[10:11], v[108:109], v[30:31] neg_lo:[1,0,0] neg_hi:[1,0,0]
	ds_read_b128 v[8:11], v33 offset:21280
	v_pk_fma_f32 v[22:23], v[12:13], v[110:111], v[22:23] neg_lo:[1,0,0] neg_hi:[1,0,0]
	v_pk_fma_f32 v[30:31], v[14:15], v[112:113], v[30:31] neg_lo:[1,0,0] neg_hi:[1,0,0]
	ds_read_b128 v[12:15], v33 offset:21296
	v_cmp_eq_u32_e32 vcc, 15, v152
	v_pk_add_f32 v[82:83], v[22:23], v[30:31]
	v_add_f32_e32 v112, v82, v83
	v_cvt_pk_bf16_f32 v25, v112, v112
	ds_write_b16 v84, v25 offset:2016
	v_cndmask_b32_e64 v192, 0, 1.0, vcc
	s_waitcnt lgkmcnt(3)
	v_pk_fma_f32 v[22:23], v[0:1], v[98:99], v[192:193] neg_lo:[1,0,0] neg_hi:[1,0,0]
	v_pk_fma_f32 v[30:31], v[2:3], v[100:101], 0 neg_lo:[1,0,0] neg_hi:[1,0,0]
	ds_read_b128 v[0:3], v33 offset:21504
	v_pk_fma_f32 v[22:23], v[4:5], v[102:103], v[22:23] neg_lo:[1,0,0] neg_hi:[1,0,0]
	v_pk_fma_f32 v[30:31], v[6:7], v[104:105], v[30:31] neg_lo:[1,0,0] neg_hi:[1,0,0]
	ds_read_b128 v[4:7], v33 offset:21520
	s_waitcnt lgkmcnt(3)
	v_pk_fma_f32 v[22:23], v[8:9], v[106:107], v[22:23] neg_lo:[1,0,0] neg_hi:[1,0,0]
	v_pk_fma_f32 v[30:31], v[10:11], v[108:109], v[30:31] neg_lo:[1,0,0] neg_hi:[1,0,0]
	ds_read_b128 v[8:11], v33 offset:21536
	v_pk_fma_f32 v[22:23], v[12:13], v[110:111], v[22:23] neg_lo:[1,0,0] neg_hi:[1,0,0]
	v_pk_fma_f32 v[30:31], v[14:15], v[112:113], v[30:31] neg_lo:[1,0,0] neg_hi:[1,0,0]
	ds_read_b128 v[12:15], v33 offset:21552
	v_cmp_eq_u32_e32 vcc, 16, v152
	v_pk_add_f32 v[82:83], v[22:23], v[30:31]
	v_add_f32_e32 v113, v82, v83
	v_cvt_pk_bf16_f32 v25, v113, v113
	ds_write_b16 v84, v25 offset:2160
	v_cndmask_b32_e64 v192, 0, 1.0, vcc
	ds_read_b128 v[16:19], v33 offset:21824
	s_waitcnt lgkmcnt(4)
	v_pk_fma_f32 v[22:23], v[0:1], v[98:99], v[192:193] neg_lo:[1,0,0] neg_hi:[1,0,0]
	v_pk_fma_f32 v[30:31], v[2:3], v[100:101], 0 neg_lo:[1,0,0] neg_hi:[1,0,0]
	ds_read_b128 v[0:3], v33 offset:21760
	v_pk_fma_f32 v[22:23], v[4:5], v[102:103], v[22:23] neg_lo:[1,0,0] neg_hi:[1,0,0]
	v_pk_fma_f32 v[30:31], v[6:7], v[104:105], v[30:31] neg_lo:[1,0,0] neg_hi:[1,0,0]
	ds_read_b128 v[4:7], v33 offset:21776
	s_waitcnt lgkmcnt(4)
	v_pk_fma_f32 v[22:23], v[8:9], v[106:107], v[22:23] neg_lo:[1,0,0] neg_hi:[1,0,0]
	v_pk_fma_f32 v[30:31], v[10:11], v[108:109], v[30:31] neg_lo:[1,0,0] neg_hi:[1,0,0]
	ds_read_b128 v[8:11], v33 offset:21792
	v_pk_fma_f32 v[22:23], v[12:13], v[110:111], v[22:23] neg_lo:[1,0,0] neg_hi:[1,0,0]
	v_pk_fma_f32 v[30:31], v[14:15], v[112:113], v[30:31] neg_lo:[1,0,0] neg_hi:[1,0,0]
	ds_read_b128 v[12:15], v33 offset:21808
	v_cmp_eq_u32_e32 vcc, 17, v152
	v_pk_add_f32 v[82:83], v[22:23], v[30:31]
	v_add_f32_e32 v114, v82, v83
	v_cvt_pk_bf16_f32 v25, v114, v114
	ds_write_b16 v84, v25 offset:2304
	v_cndmask_b32_e64 v192, 0, 1.0, vcc
	s_waitcnt lgkmcnt(3)
	v_pk_fma_f32 v[22:23], v[0:1], v[98:99], v[192:193] neg_lo:[1,0,0] neg_hi:[1,0,0]
	v_pk_fma_f32 v[30:31], v[2:3], v[100:101], 0 neg_lo:[1,0,0] neg_hi:[1,0,0]
	ds_read_b128 v[0:3], v33 offset:22016
	v_pk_fma_f32 v[22:23], v[4:5], v[102:103], v[22:23] neg_lo:[1,0,0] neg_hi:[1,0,0]
	v_pk_fma_f32 v[30:31], v[6:7], v[104:105], v[30:31] neg_lo:[1,0,0] neg_hi:[1,0,0]
	ds_read_b128 v[4:7], v33 offset:22032
	s_waitcnt lgkmcnt(3)
	v_pk_fma_f32 v[22:23], v[8:9], v[106:107], v[22:23] neg_lo:[1,0,0] neg_hi:[1,0,0]
	v_pk_fma_f32 v[30:31], v[10:11], v[108:109], v[30:31] neg_lo:[1,0,0] neg_hi:[1,0,0]
	ds_read_b128 v[8:11], v33 offset:22048
	v_pk_fma_f32 v[22:23], v[12:13], v[110:111], v[22:23] neg_lo:[1,0,0] neg_hi:[1,0,0]
	v_pk_fma_f32 v[30:31], v[14:15], v[112:113], v[30:31] neg_lo:[1,0,0] neg_hi:[1,0,0]
	ds_read_b128 v[12:15], v33 offset:22064
	s_waitcnt lgkmcnt(9)
	v_pk_fma_f32 v[22:23], v[16:17], v[114:115], v[22:23] neg_lo:[1,0,0] neg_hi:[1,0,0]
	v_pk_fma_f32 v[30:31], v[18:19], v[116:117], v[30:31] neg_lo:[1,0,0] neg_hi:[1,0,0]
	ds_read_b128 v[16:19], v33 offset:22080
	v_cmp_eq_u32_e32 vcc, 18, v152
	v_pk_add_f32 v[82:83], v[22:23], v[30:31]
	v_add_f32_e32 v115, v82, v83
	v_cvt_pk_bf16_f32 v25, v115, v115
	ds_write_b16 v84, v25 offset:2448
	v_cndmask_b32_e64 v192, 0, 1.0, vcc
	s_waitcnt lgkmcnt(4)
	v_pk_fma_f32 v[22:23], v[0:1], v[98:99], v[192:193] neg_lo:[1,0,0] neg_hi:[1,0,0]
	v_pk_fma_f32 v[30:31], v[2:3], v[100:101], 0 neg_lo:[1,0,0] neg_hi:[1,0,0]
	ds_read_b128 v[0:3], v33 offset:22272
	v_pk_fma_f32 v[22:23], v[4:5], v[102:103], v[22:23] neg_lo:[1,0,0] neg_hi:[1,0,0]
	v_pk_fma_f32 v[30:31], v[6:7], v[104:105], v[30:31] neg_lo:[1,0,0] neg_hi:[1,0,0]
	ds_read_b128 v[4:7], v33 offset:22288
	s_waitcnt lgkmcnt(4)
	v_pk_fma_f32 v[22:23], v[8:9], v[106:107], v[22:23] neg_lo:[1,0,0] neg_hi:[1,0,0]
	v_pk_fma_f32 v[30:31], v[10:11], v[108:109], v[30:31] neg_lo:[1,0,0] neg_hi:[1,0,0]
	ds_read_b128 v[8:11], v33 offset:22304
	v_pk_fma_f32 v[22:23], v[12:13], v[110:111], v[22:23] neg_lo:[1,0,0] neg_hi:[1,0,0]
	v_pk_fma_f32 v[30:31], v[14:15], v[112:113], v[30:31] neg_lo:[1,0,0] neg_hi:[1,0,0]
	ds_read_b128 v[12:15], v33 offset:22320
	s_waitcnt lgkmcnt(5)
	v_pk_fma_f32 v[22:23], v[16:17], v[114:115], v[22:23] neg_lo:[1,0,0] neg_hi:[1,0,0]
	v_pk_fma_f32 v[30:31], v[18:19], v[116:117], v[30:31] neg_lo:[1,0,0] neg_hi:[1,0,0]
	ds_read_b128 v[16:19], v33 offset:22336
	v_cmp_eq_u32_e32 vcc, 19, v152
	v_pk_add_f32 v[82:83], v[22:23], v[30:31]
	v_add_f32_e32 v116, v82, v83
	v_cvt_pk_bf16_f32 v25, v116, v116
	ds_write_b16 v84, v25 offset:2592
	v_cndmask_b32_e64 v192, 0, 1.0, vcc
	s_waitcnt lgkmcnt(4)
	v_pk_fma_f32 v[22:23], v[0:1], v[98:99], v[192:193] neg_lo:[1,0,0] neg_hi:[1,0,0]
	v_pk_fma_f32 v[30:31], v[2:3], v[100:101], 0 neg_lo:[1,0,0] neg_hi:[1,0,0]
	ds_read_b128 v[0:3], v33 offset:22528
	v_pk_fma_f32 v[22:23], v[4:5], v[102:103], v[22:23] neg_lo:[1,0,0] neg_hi:[1,0,0]
	v_pk_fma_f32 v[30:31], v[6:7], v[104:105], v[30:31] neg_lo:[1,0,0] neg_hi:[1,0,0]
	ds_read_b128 v[4:7], v33 offset:22544
	s_waitcnt lgkmcnt(4)
	v_pk_fma_f32 v[22:23], v[8:9], v[106:107], v[22:23] neg_lo:[1,0,0] neg_hi:[1,0,0]
	v_pk_fma_f32 v[30:31], v[10:11], v[108:109], v[30:31] neg_lo:[1,0,0] neg_hi:[1,0,0]
	ds_read_b128 v[8:11], v33 offset:22560
	v_pk_fma_f32 v[22:23], v[12:13], v[110:111], v[22:23] neg_lo:[1,0,0] neg_hi:[1,0,0]
	v_pk_fma_f32 v[30:31], v[14:15], v[112:113], v[30:31] neg_lo:[1,0,0] neg_hi:[1,0,0]
	ds_read_b128 v[12:15], v33 offset:22576
	s_waitcnt lgkmcnt(5)
	v_pk_fma_f32 v[22:23], v[16:17], v[114:115], v[22:23] neg_lo:[1,0,0] neg_hi:[1,0,0]
	v_pk_fma_f32 v[30:31], v[18:19], v[116:117], v[30:31] neg_lo:[1,0,0] neg_hi:[1,0,0]
	ds_read_b128 v[16:19], v33 offset:22592
	v_cmp_eq_u32_e32 vcc, 20, v152
	v_pk_add_f32 v[82:83], v[22:23], v[30:31]
	v_add_f32_e32 v117, v82, v83
	v_cvt_pk_bf16_f32 v25, v117, v117
	ds_write_b16 v84, v25 offset:2736
	v_cndmask_b32_e64 v192, 0, 1.0, vcc
	ds_read_b128 v[26:29], v33 offset:22864
	s_waitcnt lgkmcnt(5)
	v_pk_fma_f32 v[22:23], v[0:1], v[98:99], v[192:193] neg_lo:[1,0,0] neg_hi:[1,0,0]
	v_pk_fma_f32 v[30:31], v[2:3], v[100:101], 0 neg_lo:[1,0,0] neg_hi:[1,0,0]
	ds_read_b128 v[0:3], v33 offset:22784
	v_pk_fma_f32 v[22:23], v[4:5], v[102:103], v[22:23] neg_lo:[1,0,0] neg_hi:[1,0,0]
	v_pk_fma_f32 v[30:31], v[6:7], v[104:105], v[30:31] neg_lo:[1,0,0] neg_hi:[1,0,0]
	ds_read_b128 v[4:7], v33 offset:22800
	s_waitcnt lgkmcnt(5)
	v_pk_fma_f32 v[22:23], v[8:9], v[106:107], v[22:23] neg_lo:[1,0,0] neg_hi:[1,0,0]
	v_pk_fma_f32 v[30:31], v[10:11], v[108:109], v[30:31] neg_lo:[1,0,0] neg_hi:[1,0,0]
	ds_read_b128 v[8:11], v33 offset:22816
	v_pk_fma_f32 v[22:23], v[12:13], v[110:111], v[22:23] neg_lo:[1,0,0] neg_hi:[1,0,0]
	v_pk_fma_f32 v[30:31], v[14:15], v[112:113], v[30:31] neg_lo:[1,0,0] neg_hi:[1,0,0]
	ds_read_b128 v[12:15], v33 offset:22832
	s_waitcnt lgkmcnt(6)
	v_pk_fma_f32 v[22:23], v[16:17], v[114:115], v[22:23] neg_lo:[1,0,0] neg_hi:[1,0,0]
	v_pk_fma_f32 v[30:31], v[18:19], v[116:117], v[30:31] neg_lo:[1,0,0] neg_hi:[1,0,0]
	ds_read_b128 v[16:19], v33 offset:22848
	v_cmp_eq_u32_e32 vcc, 21, v152
	v_pk_add_f32 v[82:83], v[22:23], v[30:31]
	v_add_f32_e32 v118, v82, v83
	v_cvt_pk_bf16_f32 v25, v118, v118
	ds_write_b16 v84, v25 offset:2880
	v_cndmask_b32_e64 v192, 0, 1.0, vcc
	s_waitcnt lgkmcnt(4)
	v_pk_fma_f32 v[22:23], v[0:1], v[98:99], v[192:193] neg_lo:[1,0,0] neg_hi:[1,0,0]
	v_pk_fma_f32 v[30:31], v[2:3], v[100:101], 0 neg_lo:[1,0,0] neg_hi:[1,0,0]
	ds_read_b128 v[0:3], v33 offset:23040
	v_pk_fma_f32 v[22:23], v[4:5], v[102:103], v[22:23] neg_lo:[1,0,0] neg_hi:[1,0,0]
	v_pk_fma_f32 v[30:31], v[6:7], v[104:105], v[30:31] neg_lo:[1,0,0] neg_hi:[1,0,0]
	ds_read_b128 v[4:7], v33 offset:23056
	s_waitcnt lgkmcnt(4)
	v_pk_fma_f32 v[22:23], v[8:9], v[106:107], v[22:23] neg_lo:[1,0,0] neg_hi:[1,0,0]
	v_pk_fma_f32 v[30:31], v[10:11], v[108:109], v[30:31] neg_lo:[1,0,0] neg_hi:[1,0,0]
	ds_read_b128 v[8:11], v33 offset:23072
	v_pk_fma_f32 v[22:23], v[12:13], v[110:111], v[22:23] neg_lo:[1,0,0] neg_hi:[1,0,0]
	v_pk_fma_f32 v[30:31], v[14:15], v[112:113], v[30:31] neg_lo:[1,0,0] neg_hi:[1,0,0]
	ds_read_b128 v[12:15], v33 offset:23088
	s_waitcnt lgkmcnt(10)
	v_pk_fma_f32 v[22:23], v[16:17], v[114:115], v[22:23] neg_lo:[1,0,0] neg_hi:[1,0,0]
	v_pk_fma_f32 v[30:31], v[18:19], v[116:117], v[30:31] neg_lo:[1,0,0] neg_hi:[1,0,0]
	ds_read_b128 v[16:19], v33 offset:23104
	v_pk_fma_f32 v[22:23], v[26:27], v[118:119], v[22:23] neg_lo:[1,0,0] neg_hi:[1,0,0]
	v_pk_fma_f32 v[30:31], v[28:29], v[120:121], v[30:31] neg_lo:[1,0,0] neg_hi:[1,0,0]
	ds_read_b128 v[26:29], v33 offset:23120
	v_cmp_eq_u32_e32 vcc, 22, v152
	v_pk_add_f32 v[82:83], v[22:23], v[30:31]
	v_add_f32_e32 v119, v82, v83
	v_cvt_pk_bf16_f32 v25, v119, v119
	ds_write_b16 v84, v25 offset:3024
	v_cndmask_b32_e64 v192, 0, 1.0, vcc
	s_waitcnt lgkmcnt(5)
	v_pk_fma_f32 v[22:23], v[0:1], v[98:99], v[192:193] neg_lo:[1,0,0] neg_hi:[1,0,0]
	v_pk_fma_f32 v[30:31], v[2:3], v[100:101], 0 neg_lo:[1,0,0] neg_hi:[1,0,0]
	ds_read_b128 v[0:3], v33 offset:23296
	v_pk_fma_f32 v[22:23], v[4:5], v[102:103], v[22:23] neg_lo:[1,0,0] neg_hi:[1,0,0]
	v_pk_fma_f32 v[30:31], v[6:7], v[104:105], v[30:31] neg_lo:[1,0,0] neg_hi:[1,0,0]
	ds_read_b128 v[4:7], v33 offset:23312
	s_waitcnt lgkmcnt(5)
	v_pk_fma_f32 v[22:23], v[8:9], v[106:107], v[22:23] neg_lo:[1,0,0] neg_hi:[1,0,0]
	v_pk_fma_f32 v[30:31], v[10:11], v[108:109], v[30:31] neg_lo:[1,0,0] neg_hi:[1,0,0]
	ds_read_b128 v[8:11], v33 offset:23328
	v_pk_fma_f32 v[22:23], v[12:13], v[110:111], v[22:23] neg_lo:[1,0,0] neg_hi:[1,0,0]
	v_pk_fma_f32 v[30:31], v[14:15], v[112:113], v[30:31] neg_lo:[1,0,0] neg_hi:[1,0,0]
	ds_read_b128 v[12:15], v33 offset:23344
	s_waitcnt lgkmcnt(5)
	v_pk_fma_f32 v[22:23], v[16:17], v[114:115], v[22:23] neg_lo:[1,0,0] neg_hi:[1,0,0]
	v_pk_fma_f32 v[30:31], v[18:19], v[116:117], v[30:31] neg_lo:[1,0,0] neg_hi:[1,0,0]
	ds_read_b128 v[16:19], v33 offset:23360
	v_pk_fma_f32 v[22:23], v[26:27], v[118:119], v[22:23] neg_lo:[1,0,0] neg_hi:[1,0,0]
	v_pk_fma_f32 v[30:31], v[28:29], v[120:121], v[30:31] neg_lo:[1,0,0] neg_hi:[1,0,0]
	ds_read_b128 v[26:29], v33 offset:23376
	v_cmp_eq_u32_e32 vcc, 23, v152
	v_pk_add_f32 v[82:83], v[22:23], v[30:31]
	v_add_f32_e32 v120, v82, v83
	v_cvt_pk_bf16_f32 v25, v120, v120
	ds_write_b16 v84, v25 offset:3168
	v_cndmask_b32_e64 v192, 0, 1.0, vcc
	s_waitcnt lgkmcnt(5)
	v_pk_fma_f32 v[22:23], v[0:1], v[98:99], v[192:193] neg_lo:[1,0,0] neg_hi:[1,0,0]
	v_pk_fma_f32 v[30:31], v[2:3], v[100:101], 0 neg_lo:[1,0,0] neg_hi:[1,0,0]
	ds_read_b128 v[0:3], v33 offset:23552
	v_pk_fma_f32 v[22:23], v[4:5], v[102:103], v[22:23] neg_lo:[1,0,0] neg_hi:[1,0,0]
	v_pk_fma_f32 v[30:31], v[6:7], v[104:105], v[30:31] neg_lo:[1,0,0] neg_hi:[1,0,0]
	ds_read_b128 v[4:7], v33 offset:23568
	s_waitcnt lgkmcnt(5)
	v_pk_fma_f32 v[22:23], v[8:9], v[106:107], v[22:23] neg_lo:[1,0,0] neg_hi:[1,0,0]
	v_pk_fma_f32 v[30:31], v[10:11], v[108:109], v[30:31] neg_lo:[1,0,0] neg_hi:[1,0,0]
	ds_read_b128 v[8:11], v33 offset:23584
	v_pk_fma_f32 v[22:23], v[12:13], v[110:111], v[22:23] neg_lo:[1,0,0] neg_hi:[1,0,0]
	v_pk_fma_f32 v[30:31], v[14:15], v[112:113], v[30:31] neg_lo:[1,0,0] neg_hi:[1,0,0]
	ds_read_b128 v[12:15], v33 offset:23600
	s_waitcnt lgkmcnt(5)
	v_pk_fma_f32 v[22:23], v[16:17], v[114:115], v[22:23] neg_lo:[1,0,0] neg_hi:[1,0,0]
	v_pk_fma_f32 v[30:31], v[18:19], v[116:117], v[30:31] neg_lo:[1,0,0] neg_hi:[1,0,0]
	ds_read_b128 v[16:19], v33 offset:23616
	v_pk_fma_f32 v[22:23], v[26:27], v[118:119], v[22:23] neg_lo:[1,0,0] neg_hi:[1,0,0]
	v_pk_fma_f32 v[30:31], v[28:29], v[120:121], v[30:31] neg_lo:[1,0,0] neg_hi:[1,0,0]
	ds_read_b128 v[26:29], v33 offset:23632
	v_cmp_eq_u32_e32 vcc, 24, v152
	v_pk_add_f32 v[82:83], v[22:23], v[30:31]
	v_add_f32_e32 v121, v82, v83
	v_cvt_pk_bf16_f32 v25, v121, v121
	ds_write_b16 v84, v25 offset:3312
	v_cndmask_b32_e64 v192, 0, 1.0, vcc
	ds_read_b128 v[34:37], v33 offset:23904
	s_waitcnt lgkmcnt(6)
	v_pk_fma_f32 v[22:23], v[0:1], v[98:99], v[192:193] neg_lo:[1,0,0] neg_hi:[1,0,0]
	v_pk_fma_f32 v[30:31], v[2:3], v[100:101], 0 neg_lo:[1,0,0] neg_hi:[1,0,0]
	ds_read_b128 v[0:3], v33 offset:23808
	v_pk_fma_f32 v[22:23], v[4:5], v[102:103], v[22:23] neg_lo:[1,0,0] neg_hi:[1,0,0]
	v_pk_fma_f32 v[30:31], v[6:7], v[104:105], v[30:31] neg_lo:[1,0,0] neg_hi:[1,0,0]
	ds_read_b128 v[4:7], v33 offset:23824
	s_waitcnt lgkmcnt(6)
	v_pk_fma_f32 v[22:23], v[8:9], v[106:107], v[22:23] neg_lo:[1,0,0] neg_hi:[1,0,0]
	v_pk_fma_f32 v[30:31], v[10:11], v[108:109], v[30:31] neg_lo:[1,0,0] neg_hi:[1,0,0]
	ds_read_b128 v[8:11], v33 offset:23840
	v_pk_fma_f32 v[22:23], v[12:13], v[110:111], v[22:23] neg_lo:[1,0,0] neg_hi:[1,0,0]
	v_pk_fma_f32 v[30:31], v[14:15], v[112:113], v[30:31] neg_lo:[1,0,0] neg_hi:[1,0,0]
	ds_read_b128 v[12:15], v33 offset:23856
	s_waitcnt lgkmcnt(6)
	v_pk_fma_f32 v[22:23], v[16:17], v[114:115], v[22:23] neg_lo:[1,0,0] neg_hi:[1,0,0]
	v_pk_fma_f32 v[30:31], v[18:19], v[116:117], v[30:31] neg_lo:[1,0,0] neg_hi:[1,0,0]
	ds_read_b128 v[16:19], v33 offset:23872
	v_pk_fma_f32 v[22:23], v[26:27], v[118:119], v[22:23] neg_lo:[1,0,0] neg_hi:[1,0,0]
	v_pk_fma_f32 v[30:31], v[28:29], v[120:121], v[30:31] neg_lo:[1,0,0] neg_hi:[1,0,0]
	ds_read_b128 v[26:29], v33 offset:23888
	v_cmp_eq_u32_e32 vcc, 25, v152
	v_pk_add_f32 v[82:83], v[22:23], v[30:31]
	v_add_f32_e32 v122, v82, v83
	v_cvt_pk_bf16_f32 v25, v122, v122
	ds_write_b16 v84, v25 offset:3456
	v_cndmask_b32_e64 v192, 0, 1.0, vcc
	s_waitcnt lgkmcnt(5)
	v_pk_fma_f32 v[22:23], v[0:1], v[98:99], v[192:193] neg_lo:[1,0,0] neg_hi:[1,0,0]
	v_pk_fma_f32 v[30:31], v[2:3], v[100:101], 0 neg_lo:[1,0,0] neg_hi:[1,0,0]
	ds_read_b128 v[0:3], v33 offset:24064
	v_pk_fma_f32 v[22:23], v[4:5], v[102:103], v[22:23] neg_lo:[1,0,0] neg_hi:[1,0,0]
	v_pk_fma_f32 v[30:31], v[6:7], v[104:105], v[30:31] neg_lo:[1,0,0] neg_hi:[1,0,0]
	ds_read_b128 v[4:7], v33 offset:24080
	s_waitcnt lgkmcnt(5)
	v_pk_fma_f32 v[22:23], v[8:9], v[106:107], v[22:23] neg_lo:[1,0,0] neg_hi:[1,0,0]
	v_pk_fma_f32 v[30:31], v[10:11], v[108:109], v[30:31] neg_lo:[1,0,0] neg_hi:[1,0,0]
	ds_read_b128 v[8:11], v33 offset:24096
	v_pk_fma_f32 v[22:23], v[12:13], v[110:111], v[22:23] neg_lo:[1,0,0] neg_hi:[1,0,0]
	v_pk_fma_f32 v[30:31], v[14:15], v[112:113], v[30:31] neg_lo:[1,0,0] neg_hi:[1,0,0]
	ds_read_b128 v[12:15], v33 offset:24112
	s_waitcnt lgkmcnt(5)
	v_pk_fma_f32 v[22:23], v[16:17], v[114:115], v[22:23] neg_lo:[1,0,0] neg_hi:[1,0,0]
	v_pk_fma_f32 v[30:31], v[18:19], v[116:117], v[30:31] neg_lo:[1,0,0] neg_hi:[1,0,0]
	ds_read_b128 v[16:19], v33 offset:24128
	v_pk_fma_f32 v[22:23], v[26:27], v[118:119], v[22:23] neg_lo:[1,0,0] neg_hi:[1,0,0]
	v_pk_fma_f32 v[30:31], v[28:29], v[120:121], v[30:31] neg_lo:[1,0,0] neg_hi:[1,0,0]
	ds_read_b128 v[26:29], v33 offset:24144
	s_waitcnt lgkmcnt(13)
	v_pk_fma_f32 v[22:23], v[34:35], v[122:123], v[22:23] neg_lo:[1,0,0] neg_hi:[1,0,0]
	v_pk_fma_f32 v[30:31], v[36:37], v[124:125], v[30:31] neg_lo:[1,0,0] neg_hi:[1,0,0]
	ds_read_b128 v[34:37], v33 offset:24160
	v_cmp_eq_u32_e32 vcc, 26, v152
	v_pk_add_f32 v[82:83], v[22:23], v[30:31]
	v_add_f32_e32 v123, v82, v83
	v_cvt_pk_bf16_f32 v25, v123, v123
	ds_write_b16 v84, v25 offset:3600
	v_cndmask_b32_e64 v192, 0, 1.0, vcc
	s_waitcnt lgkmcnt(6)
	v_pk_fma_f32 v[22:23], v[0:1], v[98:99], v[192:193] neg_lo:[1,0,0] neg_hi:[1,0,0]
	v_pk_fma_f32 v[30:31], v[2:3], v[100:101], 0 neg_lo:[1,0,0] neg_hi:[1,0,0]
	ds_read_b128 v[0:3], v33 offset:24320
	v_pk_fma_f32 v[22:23], v[4:5], v[102:103], v[22:23] neg_lo:[1,0,0] neg_hi:[1,0,0]
	v_pk_fma_f32 v[30:31], v[6:7], v[104:105], v[30:31] neg_lo:[1,0,0] neg_hi:[1,0,0]
	ds_read_b128 v[4:7], v33 offset:24336
	s_waitcnt lgkmcnt(6)
	v_pk_fma_f32 v[22:23], v[8:9], v[106:107], v[22:23] neg_lo:[1,0,0] neg_hi:[1,0,0]
	v_pk_fma_f32 v[30:31], v[10:11], v[108:109], v[30:31] neg_lo:[1,0,0] neg_hi:[1,0,0]
	ds_read_b128 v[8:11], v33 offset:24352
	v_pk_fma_f32 v[22:23], v[12:13], v[110:111], v[22:23] neg_lo:[1,0,0] neg_hi:[1,0,0]
	v_pk_fma_f32 v[30:31], v[14:15], v[112:113], v[30:31] neg_lo:[1,0,0] neg_hi:[1,0,0]
	ds_read_b128 v[12:15], v33 offset:24368
	s_waitcnt lgkmcnt(6)
	v_pk_fma_f32 v[22:23], v[16:17], v[114:115], v[22:23] neg_lo:[1,0,0] neg_hi:[1,0,0]
	v_pk_fma_f32 v[30:31], v[18:19], v[116:117], v[30:31] neg_lo:[1,0,0] neg_hi:[1,0,0]
	ds_read_b128 v[16:19], v33 offset:24384
	v_pk_fma_f32 v[22:23], v[26:27], v[118:119], v[22:23] neg_lo:[1,0,0] neg_hi:[1,0,0]
	v_pk_fma_f32 v[30:31], v[28:29], v[120:121], v[30:31] neg_lo:[1,0,0] neg_hi:[1,0,0]
	ds_read_b128 v[26:29], v33 offset:24400
	s_waitcnt lgkmcnt(7)
	v_pk_fma_f32 v[22:23], v[34:35], v[122:123], v[22:23] neg_lo:[1,0,0] neg_hi:[1,0,0]
	v_pk_fma_f32 v[30:31], v[36:37], v[124:125], v[30:31] neg_lo:[1,0,0] neg_hi:[1,0,0]
	ds_read_b128 v[34:37], v33 offset:24416
	v_cmp_eq_u32_e32 vcc, 27, v152
	v_pk_add_f32 v[82:83], v[22:23], v[30:31]
	v_add_f32_e32 v124, v82, v83
	v_cvt_pk_bf16_f32 v25, v124, v124
	ds_write_b16 v84, v25 offset:3744
	v_cndmask_b32_e64 v192, 0, 1.0, vcc
	s_waitcnt lgkmcnt(6)
	v_pk_fma_f32 v[22:23], v[0:1], v[98:99], v[192:193] neg_lo:[1,0,0] neg_hi:[1,0,0]
	v_pk_fma_f32 v[30:31], v[2:3], v[100:101], 0 neg_lo:[1,0,0] neg_hi:[1,0,0]
	ds_read_b128 v[0:3], v33 offset:24576
	v_pk_fma_f32 v[22:23], v[4:5], v[102:103], v[22:23] neg_lo:[1,0,0] neg_hi:[1,0,0]
	v_pk_fma_f32 v[30:31], v[6:7], v[104:105], v[30:31] neg_lo:[1,0,0] neg_hi:[1,0,0]
	ds_read_b128 v[4:7], v33 offset:24592
	s_waitcnt lgkmcnt(6)
	v_pk_fma_f32 v[22:23], v[8:9], v[106:107], v[22:23] neg_lo:[1,0,0] neg_hi:[1,0,0]
	v_pk_fma_f32 v[30:31], v[10:11], v[108:109], v[30:31] neg_lo:[1,0,0] neg_hi:[1,0,0]
	ds_read_b128 v[8:11], v33 offset:24608
	v_pk_fma_f32 v[22:23], v[12:13], v[110:111], v[22:23] neg_lo:[1,0,0] neg_hi:[1,0,0]
	v_pk_fma_f32 v[30:31], v[14:15], v[112:113], v[30:31] neg_lo:[1,0,0] neg_hi:[1,0,0]
	ds_read_b128 v[12:15], v33 offset:24624
	s_waitcnt lgkmcnt(6)
	v_pk_fma_f32 v[22:23], v[16:17], v[114:115], v[22:23] neg_lo:[1,0,0] neg_hi:[1,0,0]
	v_pk_fma_f32 v[30:31], v[18:19], v[116:117], v[30:31] neg_lo:[1,0,0] neg_hi:[1,0,0]
	ds_read_b128 v[16:19], v33 offset:24640
	v_pk_fma_f32 v[22:23], v[26:27], v[118:119], v[22:23] neg_lo:[1,0,0] neg_hi:[1,0,0]
	v_pk_fma_f32 v[30:31], v[28:29], v[120:121], v[30:31] neg_lo:[1,0,0] neg_hi:[1,0,0]
	ds_read_b128 v[26:29], v33 offset:24656
	s_waitcnt lgkmcnt(7)
	v_pk_fma_f32 v[22:23], v[34:35], v[122:123], v[22:23] neg_lo:[1,0,0] neg_hi:[1,0,0]
	v_pk_fma_f32 v[30:31], v[36:37], v[124:125], v[30:31] neg_lo:[1,0,0] neg_hi:[1,0,0]
	ds_read_b128 v[34:37], v33 offset:24672
	v_cmp_eq_u32_e32 vcc, 28, v152
	v_pk_add_f32 v[82:83], v[22:23], v[30:31]
	v_add_f32_e32 v125, v82, v83
	v_cvt_pk_bf16_f32 v25, v125, v125
	ds_write_b16 v84, v25 offset:3888
	v_cndmask_b32_e64 v192, 0, 1.0, vcc
	ds_read_b128 v[38:41], v33 offset:24944
	s_waitcnt lgkmcnt(7)
	v_pk_fma_f32 v[22:23], v[0:1], v[98:99], v[192:193] neg_lo:[1,0,0] neg_hi:[1,0,0]
	v_pk_fma_f32 v[30:31], v[2:3], v[100:101], 0 neg_lo:[1,0,0] neg_hi:[1,0,0]
	ds_read_b128 v[0:3], v33 offset:24832
	v_pk_fma_f32 v[22:23], v[4:5], v[102:103], v[22:23] neg_lo:[1,0,0] neg_hi:[1,0,0]
	v_pk_fma_f32 v[30:31], v[6:7], v[104:105], v[30:31] neg_lo:[1,0,0] neg_hi:[1,0,0]
	ds_read_b128 v[4:7], v33 offset:24848
	s_waitcnt lgkmcnt(7)
	v_pk_fma_f32 v[22:23], v[8:9], v[106:107], v[22:23] neg_lo:[1,0,0] neg_hi:[1,0,0]
	v_pk_fma_f32 v[30:31], v[10:11], v[108:109], v[30:31] neg_lo:[1,0,0] neg_hi:[1,0,0]
	ds_read_b128 v[8:11], v33 offset:24864
	v_pk_fma_f32 v[22:23], v[12:13], v[110:111], v[22:23] neg_lo:[1,0,0] neg_hi:[1,0,0]
	v_pk_fma_f32 v[30:31], v[14:15], v[112:113], v[30:31] neg_lo:[1,0,0] neg_hi:[1,0,0]
	ds_read_b128 v[12:15], v33 offset:24880
	s_waitcnt lgkmcnt(7)
	v_pk_fma_f32 v[22:23], v[16:17], v[114:115], v[22:23] neg_lo:[1,0,0] neg_hi:[1,0,0]
	v_pk_fma_f32 v[30:31], v[18:19], v[116:117], v[30:31] neg_lo:[1,0,0] neg_hi:[1,0,0]
	ds_read_b128 v[16:19], v33 offset:24896
	v_pk_fma_f32 v[22:23], v[26:27], v[118:119], v[22:23] neg_lo:[1,0,0] neg_hi:[1,0,0]
	v_pk_fma_f32 v[30:31], v[28:29], v[120:121], v[30:31] neg_lo:[1,0,0] neg_hi:[1,0,0]
	ds_read_b128 v[26:29], v33 offset:24912
	s_waitcnt lgkmcnt(8)
	v_pk_fma_f32 v[22:23], v[34:35], v[122:123], v[22:23] neg_lo:[1,0,0] neg_hi:[1,0,0]
	v_pk_fma_f32 v[30:31], v[36:37], v[124:125], v[30:31] neg_lo:[1,0,0] neg_hi:[1,0,0]
	ds_read_b128 v[34:37], v33 offset:24928
	v_cmp_eq_u32_e32 vcc, 29, v152
	v_pk_add_f32 v[82:83], v[22:23], v[30:31]
	v_add_f32_e32 v126, v82, v83
	v_cvt_pk_bf16_f32 v25, v126, v126
	ds_write_b16 v84, v25 offset:4032
	v_cndmask_b32_e64 v192, 0, 1.0, vcc
	s_waitcnt lgkmcnt(6)
	v_pk_fma_f32 v[22:23], v[0:1], v[98:99], v[192:193] neg_lo:[1,0,0] neg_hi:[1,0,0]
	v_pk_fma_f32 v[30:31], v[2:3], v[100:101], 0 neg_lo:[1,0,0] neg_hi:[1,0,0]
	ds_read_b128 v[0:3], v33 offset:25088
	v_pk_fma_f32 v[22:23], v[4:5], v[102:103], v[22:23] neg_lo:[1,0,0] neg_hi:[1,0,0]
	v_pk_fma_f32 v[30:31], v[6:7], v[104:105], v[30:31] neg_lo:[1,0,0] neg_hi:[1,0,0]
	ds_read_b128 v[4:7], v33 offset:25104
	s_waitcnt lgkmcnt(6)
	v_pk_fma_f32 v[22:23], v[8:9], v[106:107], v[22:23] neg_lo:[1,0,0] neg_hi:[1,0,0]
	v_pk_fma_f32 v[30:31], v[10:11], v[108:109], v[30:31] neg_lo:[1,0,0] neg_hi:[1,0,0]
	ds_read_b128 v[8:11], v33 offset:25120
	v_pk_fma_f32 v[22:23], v[12:13], v[110:111], v[22:23] neg_lo:[1,0,0] neg_hi:[1,0,0]
	v_pk_fma_f32 v[30:31], v[14:15], v[112:113], v[30:31] neg_lo:[1,0,0] neg_hi:[1,0,0]
	ds_read_b128 v[12:15], v33 offset:25136
	s_waitcnt lgkmcnt(6)
	v_pk_fma_f32 v[22:23], v[16:17], v[114:115], v[22:23] neg_lo:[1,0,0] neg_hi:[1,0,0]
	v_pk_fma_f32 v[30:31], v[18:19], v[116:117], v[30:31] neg_lo:[1,0,0] neg_hi:[1,0,0]
	ds_read_b128 v[16:19], v33 offset:25152
	v_pk_fma_f32 v[22:23], v[26:27], v[118:119], v[22:23] neg_lo:[1,0,0] neg_hi:[1,0,0]
	v_pk_fma_f32 v[30:31], v[28:29], v[120:121], v[30:31] neg_lo:[1,0,0] neg_hi:[1,0,0]
	ds_read_b128 v[26:29], v33 offset:25168
	s_waitcnt lgkmcnt(14)
	v_pk_fma_f32 v[22:23], v[34:35], v[122:123], v[22:23] neg_lo:[1,0,0] neg_hi:[1,0,0]
	v_pk_fma_f32 v[30:31], v[36:37], v[124:125], v[30:31] neg_lo:[1,0,0] neg_hi:[1,0,0]
	ds_read_b128 v[34:37], v33 offset:25184
	v_pk_fma_f32 v[22:23], v[38:39], v[126:127], v[22:23] neg_lo:[1,0,0] neg_hi:[1,0,0]
	v_pk_fma_f32 v[30:31], v[40:41], v[128:129], v[30:31] neg_lo:[1,0,0] neg_hi:[1,0,0]
	ds_read_b128 v[38:41], v33 offset:25200
	v_cmp_eq_u32_e32 vcc, 30, v152
	v_pk_add_f32 v[82:83], v[22:23], v[30:31]
	v_add_f32_e32 v127, v82, v83
	v_cvt_pk_bf16_f32 v25, v127, v127
	ds_write_b16 v84, v25 offset:4176
	v_cndmask_b32_e64 v192, 0, 1.0, vcc
	s_waitcnt lgkmcnt(7)
	v_pk_fma_f32 v[22:23], v[0:1], v[98:99], v[192:193] neg_lo:[1,0,0] neg_hi:[1,0,0]
	v_pk_fma_f32 v[30:31], v[2:3], v[100:101], 0 neg_lo:[1,0,0] neg_hi:[1,0,0]
	ds_read_b128 v[0:3], v33 offset:25344
	v_pk_fma_f32 v[22:23], v[4:5], v[102:103], v[22:23] neg_lo:[1,0,0] neg_hi:[1,0,0]
	v_pk_fma_f32 v[30:31], v[6:7], v[104:105], v[30:31] neg_lo:[1,0,0] neg_hi:[1,0,0]
	ds_read_b128 v[4:7], v33 offset:25360
	s_waitcnt lgkmcnt(7)
	v_pk_fma_f32 v[22:23], v[8:9], v[106:107], v[22:23] neg_lo:[1,0,0] neg_hi:[1,0,0]
	v_pk_fma_f32 v[30:31], v[10:11], v[108:109], v[30:31] neg_lo:[1,0,0] neg_hi:[1,0,0]
	ds_read_b128 v[8:11], v33 offset:25376
	v_pk_fma_f32 v[22:23], v[12:13], v[110:111], v[22:23] neg_lo:[1,0,0] neg_hi:[1,0,0]
	v_pk_fma_f32 v[30:31], v[14:15], v[112:113], v[30:31] neg_lo:[1,0,0] neg_hi:[1,0,0]
	ds_read_b128 v[12:15], v33 offset:25392
	s_waitcnt lgkmcnt(7)
	v_pk_fma_f32 v[22:23], v[16:17], v[114:115], v[22:23] neg_lo:[1,0,0] neg_hi:[1,0,0]
	v_pk_fma_f32 v[30:31], v[18:19], v[116:117], v[30:31] neg_lo:[1,0,0] neg_hi:[1,0,0]
	ds_read_b128 v[16:19], v33 offset:25408
	v_pk_fma_f32 v[22:23], v[26:27], v[118:119], v[22:23] neg_lo:[1,0,0] neg_hi:[1,0,0]
	v_pk_fma_f32 v[30:31], v[28:29], v[120:121], v[30:31] neg_lo:[1,0,0] neg_hi:[1,0,0]
	ds_read_b128 v[26:29], v33 offset:25424
	s_waitcnt lgkmcnt(7)
	v_pk_fma_f32 v[22:23], v[34:35], v[122:123], v[22:23] neg_lo:[1,0,0] neg_hi:[1,0,0]
	v_pk_fma_f32 v[30:31], v[36:37], v[124:125], v[30:31] neg_lo:[1,0,0] neg_hi:[1,0,0]
	ds_read_b128 v[34:37], v33 offset:25440
	v_pk_fma_f32 v[22:23], v[38:39], v[126:127], v[22:23] neg_lo:[1,0,0] neg_hi:[1,0,0]
	v_pk_fma_f32 v[30:31], v[40:41], v[128:129], v[30:31] neg_lo:[1,0,0] neg_hi:[1,0,0]
	ds_read_b128 v[38:41], v33 offset:25456
	v_cmp_eq_u32_e32 vcc, 31, v152
	v_pk_add_f32 v[82:83], v[22:23], v[30:31]
	v_add_f32_e32 v128, v82, v83
	v_cvt_pk_bf16_f32 v25, v128, v128
	ds_write_b16 v84, v25 offset:4320
	v_cndmask_b32_e64 v192, 0, 1.0, vcc
	s_waitcnt lgkmcnt(7)
	v_pk_fma_f32 v[22:23], v[0:1], v[98:99], v[192:193] neg_lo:[1,0,0] neg_hi:[1,0,0]
	v_pk_fma_f32 v[30:31], v[2:3], v[100:101], 0 neg_lo:[1,0,0] neg_hi:[1,0,0]
	ds_read_b128 v[0:3], v33 offset:25600
	v_pk_fma_f32 v[22:23], v[4:5], v[102:103], v[22:23] neg_lo:[1,0,0] neg_hi:[1,0,0]
	v_pk_fma_f32 v[30:31], v[6:7], v[104:105], v[30:31] neg_lo:[1,0,0] neg_hi:[1,0,0]
	ds_read_b128 v[4:7], v33 offset:25616
	s_waitcnt lgkmcnt(7)
	v_pk_fma_f32 v[22:23], v[8:9], v[106:107], v[22:23] neg_lo:[1,0,0] neg_hi:[1,0,0]
	v_pk_fma_f32 v[30:31], v[10:11], v[108:109], v[30:31] neg_lo:[1,0,0] neg_hi:[1,0,0]
	ds_read_b128 v[8:11], v33 offset:25632
	v_pk_fma_f32 v[22:23], v[12:13], v[110:111], v[22:23] neg_lo:[1,0,0] neg_hi:[1,0,0]
	v_pk_fma_f32 v[30:31], v[14:15], v[112:113], v[30:31] neg_lo:[1,0,0] neg_hi:[1,0,0]
	ds_read_b128 v[12:15], v33 offset:25648
	s_waitcnt lgkmcnt(7)
	v_pk_fma_f32 v[22:23], v[16:17], v[114:115], v[22:23] neg_lo:[1,0,0] neg_hi:[1,0,0]
	v_pk_fma_f32 v[30:31], v[18:19], v[116:117], v[30:31] neg_lo:[1,0,0] neg_hi:[1,0,0]
	ds_read_b128 v[16:19], v33 offset:25664
	v_pk_fma_f32 v[22:23], v[26:27], v[118:119], v[22:23] neg_lo:[1,0,0] neg_hi:[1,0,0]
	v_pk_fma_f32 v[30:31], v[28:29], v[120:121], v[30:31] neg_lo:[1,0,0] neg_hi:[1,0,0]
	ds_read_b128 v[26:29], v33 offset:25680
	s_waitcnt lgkmcnt(7)
	v_pk_fma_f32 v[22:23], v[34:35], v[122:123], v[22:23] neg_lo:[1,0,0] neg_hi:[1,0,0]
	v_pk_fma_f32 v[30:31], v[36:37], v[124:125], v[30:31] neg_lo:[1,0,0] neg_hi:[1,0,0]
	ds_read_b128 v[34:37], v33 offset:25696
	v_pk_fma_f32 v[22:23], v[38:39], v[126:127], v[22:23] neg_lo:[1,0,0] neg_hi:[1,0,0]
	v_pk_fma_f32 v[30:31], v[40:41], v[128:129], v[30:31] neg_lo:[1,0,0] neg_hi:[1,0,0]
	ds_read_b128 v[38:41], v33 offset:25712
	v_cmp_eq_u32_e32 vcc, 32, v152
	v_pk_add_f32 v[82:83], v[22:23], v[30:31]
	v_add_f32_e32 v129, v82, v83
	v_cvt_pk_bf16_f32 v25, v129, v129
	ds_write_b16 v84, v25 offset:4464
	v_cndmask_b32_e64 v192, 0, 1.0, vcc
	ds_read_b128 v[42:45], v33 offset:25984
	s_waitcnt lgkmcnt(8)
	v_pk_fma_f32 v[22:23], v[0:1], v[98:99], v[192:193] neg_lo:[1,0,0] neg_hi:[1,0,0]
	v_pk_fma_f32 v[30:31], v[2:3], v[100:101], 0 neg_lo:[1,0,0] neg_hi:[1,0,0]
	ds_read_b128 v[0:3], v33 offset:25856
	v_pk_fma_f32 v[22:23], v[4:5], v[102:103], v[22:23] neg_lo:[1,0,0] neg_hi:[1,0,0]
	v_pk_fma_f32 v[30:31], v[6:7], v[104:105], v[30:31] neg_lo:[1,0,0] neg_hi:[1,0,0]
	ds_read_b128 v[4:7], v33 offset:25872
	s_waitcnt lgkmcnt(8)
	v_pk_fma_f32 v[22:23], v[8:9], v[106:107], v[22:23] neg_lo:[1,0,0] neg_hi:[1,0,0]
	v_pk_fma_f32 v[30:31], v[10:11], v[108:109], v[30:31] neg_lo:[1,0,0] neg_hi:[1,0,0]
	ds_read_b128 v[8:11], v33 offset:25888
	v_pk_fma_f32 v[22:23], v[12:13], v[110:111], v[22:23] neg_lo:[1,0,0] neg_hi:[1,0,0]
	v_pk_fma_f32 v[30:31], v[14:15], v[112:113], v[30:31] neg_lo:[1,0,0] neg_hi:[1,0,0]
	ds_read_b128 v[12:15], v33 offset:25904
	s_waitcnt lgkmcnt(8)
	v_pk_fma_f32 v[22:23], v[16:17], v[114:115], v[22:23] neg_lo:[1,0,0] neg_hi:[1,0,0]
	v_pk_fma_f32 v[30:31], v[18:19], v[116:117], v[30:31] neg_lo:[1,0,0] neg_hi:[1,0,0]
	ds_read_b128 v[16:19], v33 offset:25920
	v_pk_fma_f32 v[22:23], v[26:27], v[118:119], v[22:23] neg_lo:[1,0,0] neg_hi:[1,0,0]
	v_pk_fma_f32 v[30:31], v[28:29], v[120:121], v[30:31] neg_lo:[1,0,0] neg_hi:[1,0,0]
	ds_read_b128 v[26:29], v33 offset:25936
	s_waitcnt lgkmcnt(8)
	v_pk_fma_f32 v[22:23], v[34:35], v[122:123], v[22:23] neg_lo:[1,0,0] neg_hi:[1,0,0]
	v_pk_fma_f32 v[30:31], v[36:37], v[124:125], v[30:31] neg_lo:[1,0,0] neg_hi:[1,0,0]
	ds_read_b128 v[34:37], v33 offset:25952
	v_pk_fma_f32 v[22:23], v[38:39], v[126:127], v[22:23] neg_lo:[1,0,0] neg_hi:[1,0,0]
	v_pk_fma_f32 v[30:31], v[40:41], v[128:129], v[30:31] neg_lo:[1,0,0] neg_hi:[1,0,0]
	ds_read_b128 v[38:41], v33 offset:25968
	v_cmp_eq_u32_e32 vcc, 33, v152
	v_pk_add_f32 v[82:83], v[22:23], v[30:31]
	v_add_f32_e32 v130, v82, v83
	v_cvt_pk_bf16_f32 v25, v130, v130
	ds_write_b16 v84, v25 offset:4608
	v_cndmask_b32_e64 v192, 0, 1.0, vcc
	s_waitcnt lgkmcnt(7)
	v_pk_fma_f32 v[22:23], v[0:1], v[98:99], v[192:193] neg_lo:[1,0,0] neg_hi:[1,0,0]
	v_pk_fma_f32 v[30:31], v[2:3], v[100:101], 0 neg_lo:[1,0,0] neg_hi:[1,0,0]
	ds_read_b128 v[0:3], v33 offset:26112
	v_pk_fma_f32 v[22:23], v[4:5], v[102:103], v[22:23] neg_lo:[1,0,0] neg_hi:[1,0,0]
	v_pk_fma_f32 v[30:31], v[6:7], v[104:105], v[30:31] neg_lo:[1,0,0] neg_hi:[1,0,0]
	ds_read_b128 v[4:7], v33 offset:26128
	s_waitcnt lgkmcnt(7)
	v_pk_fma_f32 v[22:23], v[8:9], v[106:107], v[22:23] neg_lo:[1,0,0] neg_hi:[1,0,0]
	v_pk_fma_f32 v[30:31], v[10:11], v[108:109], v[30:31] neg_lo:[1,0,0] neg_hi:[1,0,0]
	ds_read_b128 v[8:11], v33 offset:26144
	v_pk_fma_f32 v[22:23], v[12:13], v[110:111], v[22:23] neg_lo:[1,0,0] neg_hi:[1,0,0]
	v_pk_fma_f32 v[30:31], v[14:15], v[112:113], v[30:31] neg_lo:[1,0,0] neg_hi:[1,0,0]
	ds_read_b128 v[12:15], v33 offset:26160
	s_waitcnt lgkmcnt(7)
	v_pk_fma_f32 v[22:23], v[16:17], v[114:115], v[22:23] neg_lo:[1,0,0] neg_hi:[1,0,0]
	v_pk_fma_f32 v[30:31], v[18:19], v[116:117], v[30:31] neg_lo:[1,0,0] neg_hi:[1,0,0]
	ds_read_b128 v[16:19], v33 offset:26176
	v_pk_fma_f32 v[22:23], v[26:27], v[118:119], v[22:23] neg_lo:[1,0,0] neg_hi:[1,0,0]
	v_pk_fma_f32 v[30:31], v[28:29], v[120:121], v[30:31] neg_lo:[1,0,0] neg_hi:[1,0,0]
	ds_read_b128 v[26:29], v33 offset:26192
	s_waitcnt lgkmcnt(7)
	v_pk_fma_f32 v[22:23], v[34:35], v[122:123], v[22:23] neg_lo:[1,0,0] neg_hi:[1,0,0]
	v_pk_fma_f32 v[30:31], v[36:37], v[124:125], v[30:31] neg_lo:[1,0,0] neg_hi:[1,0,0]
	ds_read_b128 v[34:37], v33 offset:26208
	v_pk_fma_f32 v[22:23], v[38:39], v[126:127], v[22:23] neg_lo:[1,0,0] neg_hi:[1,0,0]
	v_pk_fma_f32 v[30:31], v[40:41], v[128:129], v[30:31] neg_lo:[1,0,0] neg_hi:[1,0,0]
	ds_read_b128 v[38:41], v33 offset:26224
	s_waitcnt lgkmcnt(15)
	v_pk_fma_f32 v[22:23], v[42:43], v[130:131], v[22:23] neg_lo:[1,0,0] neg_hi:[1,0,0]
	v_pk_fma_f32 v[30:31], v[44:45], v[132:133], v[30:31] neg_lo:[1,0,0] neg_hi:[1,0,0]
	ds_read_b128 v[42:45], v33 offset:26240
	v_cmp_eq_u32_e32 vcc, 34, v152
	v_pk_add_f32 v[82:83], v[22:23], v[30:31]
	v_add_f32_e32 v131, v82, v83
	v_cvt_pk_bf16_f32 v25, v131, v131
	ds_write_b16 v84, v25 offset:4752
	v_cndmask_b32_e64 v192, 0, 1.0, vcc
	s_waitcnt lgkmcnt(8)
	v_pk_fma_f32 v[22:23], v[0:1], v[98:99], v[192:193] neg_lo:[1,0,0] neg_hi:[1,0,0]
	v_pk_fma_f32 v[30:31], v[2:3], v[100:101], 0 neg_lo:[1,0,0] neg_hi:[1,0,0]
	ds_read_b128 v[0:3], v33 offset:26368
	v_pk_fma_f32 v[22:23], v[4:5], v[102:103], v[22:23] neg_lo:[1,0,0] neg_hi:[1,0,0]
	v_pk_fma_f32 v[30:31], v[6:7], v[104:105], v[30:31] neg_lo:[1,0,0] neg_hi:[1,0,0]
	ds_read_b128 v[4:7], v33 offset:26384
	s_waitcnt lgkmcnt(8)
	v_pk_fma_f32 v[22:23], v[8:9], v[106:107], v[22:23] neg_lo:[1,0,0] neg_hi:[1,0,0]
	v_pk_fma_f32 v[30:31], v[10:11], v[108:109], v[30:31] neg_lo:[1,0,0] neg_hi:[1,0,0]
	ds_read_b128 v[8:11], v33 offset:26400
	v_pk_fma_f32 v[22:23], v[12:13], v[110:111], v[22:23] neg_lo:[1,0,0] neg_hi:[1,0,0]
	v_pk_fma_f32 v[30:31], v[14:15], v[112:113], v[30:31] neg_lo:[1,0,0] neg_hi:[1,0,0]
	ds_read_b128 v[12:15], v33 offset:26416
	s_waitcnt lgkmcnt(8)
	v_pk_fma_f32 v[22:23], v[16:17], v[114:115], v[22:23] neg_lo:[1,0,0] neg_hi:[1,0,0]
	v_pk_fma_f32 v[30:31], v[18:19], v[116:117], v[30:31] neg_lo:[1,0,0] neg_hi:[1,0,0]
	ds_read_b128 v[16:19], v33 offset:26432
	v_pk_fma_f32 v[22:23], v[26:27], v[118:119], v[22:23] neg_lo:[1,0,0] neg_hi:[1,0,0]
	v_pk_fma_f32 v[30:31], v[28:29], v[120:121], v[30:31] neg_lo:[1,0,0] neg_hi:[1,0,0]
	ds_read_b128 v[26:29], v33 offset:26448
	s_waitcnt lgkmcnt(8)
	v_pk_fma_f32 v[22:23], v[34:35], v[122:123], v[22:23] neg_lo:[1,0,0] neg_hi:[1,0,0]
	v_pk_fma_f32 v[30:31], v[36:37], v[124:125], v[30:31] neg_lo:[1,0,0] neg_hi:[1,0,0]
	ds_read_b128 v[34:37], v33 offset:26464
	v_pk_fma_f32 v[22:23], v[38:39], v[126:127], v[22:23] neg_lo:[1,0,0] neg_hi:[1,0,0]
	v_pk_fma_f32 v[30:31], v[40:41], v[128:129], v[30:31] neg_lo:[1,0,0] neg_hi:[1,0,0]
	ds_read_b128 v[38:41], v33 offset:26480
	s_waitcnt lgkmcnt(9)
	v_pk_fma_f32 v[22:23], v[42:43], v[130:131], v[22:23] neg_lo:[1,0,0] neg_hi:[1,0,0]
	v_pk_fma_f32 v[30:31], v[44:45], v[132:133], v[30:31] neg_lo:[1,0,0] neg_hi:[1,0,0]
	ds_read_b128 v[42:45], v33 offset:26496
	v_cmp_eq_u32_e32 vcc, 35, v152
	v_pk_add_f32 v[82:83], v[22:23], v[30:31]
	v_add_f32_e32 v132, v82, v83
	v_cvt_pk_bf16_f32 v25, v132, v132
	ds_write_b16 v84, v25 offset:4896
	v_cndmask_b32_e64 v192, 0, 1.0, vcc
	s_waitcnt lgkmcnt(8)
	v_pk_fma_f32 v[22:23], v[0:1], v[98:99], v[192:193] neg_lo:[1,0,0] neg_hi:[1,0,0]
	v_pk_fma_f32 v[30:31], v[2:3], v[100:101], 0 neg_lo:[1,0,0] neg_hi:[1,0,0]
	ds_read_b128 v[0:3], v33 offset:26624
	v_pk_fma_f32 v[22:23], v[4:5], v[102:103], v[22:23] neg_lo:[1,0,0] neg_hi:[1,0,0]
	v_pk_fma_f32 v[30:31], v[6:7], v[104:105], v[30:31] neg_lo:[1,0,0] neg_hi:[1,0,0]
	ds_read_b128 v[4:7], v33 offset:26640
	s_waitcnt lgkmcnt(8)
	v_pk_fma_f32 v[22:23], v[8:9], v[106:107], v[22:23] neg_lo:[1,0,0] neg_hi:[1,0,0]
	v_pk_fma_f32 v[30:31], v[10:11], v[108:109], v[30:31] neg_lo:[1,0,0] neg_hi:[1,0,0]
	ds_read_b128 v[8:11], v33 offset:26656
	v_pk_fma_f32 v[22:23], v[12:13], v[110:111], v[22:23] neg_lo:[1,0,0] neg_hi:[1,0,0]
	v_pk_fma_f32 v[30:31], v[14:15], v[112:113], v[30:31] neg_lo:[1,0,0] neg_hi:[1,0,0]
	ds_read_b128 v[12:15], v33 offset:26672
	s_waitcnt lgkmcnt(8)
	v_pk_fma_f32 v[22:23], v[16:17], v[114:115], v[22:23] neg_lo:[1,0,0] neg_hi:[1,0,0]
	v_pk_fma_f32 v[30:31], v[18:19], v[116:117], v[30:31] neg_lo:[1,0,0] neg_hi:[1,0,0]
	ds_read_b128 v[16:19], v33 offset:26688
	v_pk_fma_f32 v[22:23], v[26:27], v[118:119], v[22:23] neg_lo:[1,0,0] neg_hi:[1,0,0]
	v_pk_fma_f32 v[30:31], v[28:29], v[120:121], v[30:31] neg_lo:[1,0,0] neg_hi:[1,0,0]
	ds_read_b128 v[26:29], v33 offset:26704
	s_waitcnt lgkmcnt(8)
	v_pk_fma_f32 v[22:23], v[34:35], v[122:123], v[22:23] neg_lo:[1,0,0] neg_hi:[1,0,0]
	v_pk_fma_f32 v[30:31], v[36:37], v[124:125], v[30:31] neg_lo:[1,0,0] neg_hi:[1,0,0]
	ds_read_b128 v[34:37], v33 offset:26720
	v_pk_fma_f32 v[22:23], v[38:39], v[126:127], v[22:23] neg_lo:[1,0,0] neg_hi:[1,0,0]
	v_pk_fma_f32 v[30:31], v[40:41], v[128:129], v[30:31] neg_lo:[1,0,0] neg_hi:[1,0,0]
	ds_read_b128 v[38:41], v33 offset:26736
	s_waitcnt lgkmcnt(9)
	v_pk_fma_f32 v[22:23], v[42:43], v[130:131], v[22:23] neg_lo:[1,0,0] neg_hi:[1,0,0]
	v_pk_fma_f32 v[30:31], v[44:45], v[132:133], v[30:31] neg_lo:[1,0,0] neg_hi:[1,0,0]
	ds_read_b128 v[42:45], v33 offset:26752
	v_cmp_eq_u32_e32 vcc, 36, v152
	v_pk_add_f32 v[82:83], v[22:23], v[30:31]
	v_add_f32_e32 v133, v82, v83
	v_cvt_pk_bf16_f32 v25, v133, v133
	ds_write_b16 v84, v25 offset:5040
	v_cndmask_b32_e64 v192, 0, 1.0, vcc
	ds_read_b128 v[46:49], v33 offset:27024
	s_waitcnt lgkmcnt(9)
	v_pk_fma_f32 v[22:23], v[0:1], v[98:99], v[192:193] neg_lo:[1,0,0] neg_hi:[1,0,0]
	v_pk_fma_f32 v[30:31], v[2:3], v[100:101], 0 neg_lo:[1,0,0] neg_hi:[1,0,0]
	ds_read_b128 v[0:3], v33 offset:26880
	v_pk_fma_f32 v[22:23], v[4:5], v[102:103], v[22:23] neg_lo:[1,0,0] neg_hi:[1,0,0]
	v_pk_fma_f32 v[30:31], v[6:7], v[104:105], v[30:31] neg_lo:[1,0,0] neg_hi:[1,0,0]
	ds_read_b128 v[4:7], v33 offset:26896
	s_waitcnt lgkmcnt(9)
	v_pk_fma_f32 v[22:23], v[8:9], v[106:107], v[22:23] neg_lo:[1,0,0] neg_hi:[1,0,0]
	v_pk_fma_f32 v[30:31], v[10:11], v[108:109], v[30:31] neg_lo:[1,0,0] neg_hi:[1,0,0]
	ds_read_b128 v[8:11], v33 offset:26912
	v_pk_fma_f32 v[22:23], v[12:13], v[110:111], v[22:23] neg_lo:[1,0,0] neg_hi:[1,0,0]
	v_pk_fma_f32 v[30:31], v[14:15], v[112:113], v[30:31] neg_lo:[1,0,0] neg_hi:[1,0,0]
	ds_read_b128 v[12:15], v33 offset:26928
	s_waitcnt lgkmcnt(9)
	v_pk_fma_f32 v[22:23], v[16:17], v[114:115], v[22:23] neg_lo:[1,0,0] neg_hi:[1,0,0]
	v_pk_fma_f32 v[30:31], v[18:19], v[116:117], v[30:31] neg_lo:[1,0,0] neg_hi:[1,0,0]
	ds_read_b128 v[16:19], v33 offset:26944
	v_pk_fma_f32 v[22:23], v[26:27], v[118:119], v[22:23] neg_lo:[1,0,0] neg_hi:[1,0,0]
	v_pk_fma_f32 v[30:31], v[28:29], v[120:121], v[30:31] neg_lo:[1,0,0] neg_hi:[1,0,0]
	ds_read_b128 v[26:29], v33 offset:26960
	s_waitcnt lgkmcnt(9)
	v_pk_fma_f32 v[22:23], v[34:35], v[122:123], v[22:23] neg_lo:[1,0,0] neg_hi:[1,0,0]
	v_pk_fma_f32 v[30:31], v[36:37], v[124:125], v[30:31] neg_lo:[1,0,0] neg_hi:[1,0,0]
	ds_read_b128 v[34:37], v33 offset:26976
	v_pk_fma_f32 v[22:23], v[38:39], v[126:127], v[22:23] neg_lo:[1,0,0] neg_hi:[1,0,0]
	v_pk_fma_f32 v[30:31], v[40:41], v[128:129], v[30:31] neg_lo:[1,0,0] neg_hi:[1,0,0]
	ds_read_b128 v[38:41], v33 offset:26992
	s_waitcnt lgkmcnt(10)
	v_pk_fma_f32 v[22:23], v[42:43], v[130:131], v[22:23] neg_lo:[1,0,0] neg_hi:[1,0,0]
	v_pk_fma_f32 v[30:31], v[44:45], v[132:133], v[30:31] neg_lo:[1,0,0] neg_hi:[1,0,0]
	ds_read_b128 v[42:45], v33 offset:27008
	v_cmp_eq_u32_e32 vcc, 37, v152
	v_pk_add_f32 v[82:83], v[22:23], v[30:31]
	v_add_f32_e32 v134, v82, v83
	v_cvt_pk_bf16_f32 v25, v134, v134
	ds_write_b16 v84, v25 offset:5184
	v_cndmask_b32_e64 v192, 0, 1.0, vcc
	s_waitcnt lgkmcnt(8)
	v_pk_fma_f32 v[22:23], v[0:1], v[98:99], v[192:193] neg_lo:[1,0,0] neg_hi:[1,0,0]
	v_pk_fma_f32 v[30:31], v[2:3], v[100:101], 0 neg_lo:[1,0,0] neg_hi:[1,0,0]
	ds_read_b128 v[0:3], v33 offset:27136
	v_pk_fma_f32 v[22:23], v[4:5], v[102:103], v[22:23] neg_lo:[1,0,0] neg_hi:[1,0,0]
	v_pk_fma_f32 v[30:31], v[6:7], v[104:105], v[30:31] neg_lo:[1,0,0] neg_hi:[1,0,0]
	ds_read_b128 v[4:7], v33 offset:27152
	s_waitcnt lgkmcnt(8)
	v_pk_fma_f32 v[22:23], v[8:9], v[106:107], v[22:23] neg_lo:[1,0,0] neg_hi:[1,0,0]
	v_pk_fma_f32 v[30:31], v[10:11], v[108:109], v[30:31] neg_lo:[1,0,0] neg_hi:[1,0,0]
	ds_read_b128 v[8:11], v33 offset:27168
	v_pk_fma_f32 v[22:23], v[12:13], v[110:111], v[22:23] neg_lo:[1,0,0] neg_hi:[1,0,0]
	v_pk_fma_f32 v[30:31], v[14:15], v[112:113], v[30:31] neg_lo:[1,0,0] neg_hi:[1,0,0]
	ds_read_b128 v[12:15], v33 offset:27184
	s_waitcnt lgkmcnt(8)
	v_pk_fma_f32 v[22:23], v[16:17], v[114:115], v[22:23] neg_lo:[1,0,0] neg_hi:[1,0,0]
	v_pk_fma_f32 v[30:31], v[18:19], v[116:117], v[30:31] neg_lo:[1,0,0] neg_hi:[1,0,0]
	ds_read_b128 v[16:19], v33 offset:27200
	v_pk_fma_f32 v[22:23], v[26:27], v[118:119], v[22:23] neg_lo:[1,0,0] neg_hi:[1,0,0]
	v_pk_fma_f32 v[30:31], v[28:29], v[120:121], v[30:31] neg_lo:[1,0,0] neg_hi:[1,0,0]
	ds_read_b128 v[26:29], v33 offset:27216
	s_waitcnt lgkmcnt(8)
	v_pk_fma_f32 v[22:23], v[34:35], v[122:123], v[22:23] neg_lo:[1,0,0] neg_hi:[1,0,0]
	v_pk_fma_f32 v[30:31], v[36:37], v[124:125], v[30:31] neg_lo:[1,0,0] neg_hi:[1,0,0]
	ds_read_b128 v[34:37], v33 offset:27232
	v_pk_fma_f32 v[22:23], v[38:39], v[126:127], v[22:23] neg_lo:[1,0,0] neg_hi:[1,0,0]
	v_pk_fma_f32 v[30:31], v[40:41], v[128:129], v[30:31] neg_lo:[1,0,0] neg_hi:[1,0,0]
	ds_read_b128 v[38:41], v33 offset:27248
	s_waitcnt lgkmcnt(15)
	v_pk_fma_f32 v[22:23], v[42:43], v[130:131], v[22:23] neg_lo:[1,0,0] neg_hi:[1,0,0]
	v_pk_fma_f32 v[30:31], v[44:45], v[132:133], v[30:31] neg_lo:[1,0,0] neg_hi:[1,0,0]
	ds_read_b128 v[42:45], v33 offset:27264
	v_pk_fma_f32 v[22:23], v[46:47], v[134:135], v[22:23] neg_lo:[1,0,0] neg_hi:[1,0,0]
	v_pk_fma_f32 v[30:31], v[48:49], v[136:137], v[30:31] neg_lo:[1,0,0] neg_hi:[1,0,0]
	ds_read_b128 v[46:49], v33 offset:27280
	v_cmp_eq_u32_e32 vcc, 38, v152
	v_pk_add_f32 v[82:83], v[22:23], v[30:31]
	v_add_f32_e32 v135, v82, v83
	v_cvt_pk_bf16_f32 v25, v135, v135
	ds_write_b16 v84, v25 offset:5328
	v_cndmask_b32_e64 v192, 0, 1.0, vcc
	s_waitcnt lgkmcnt(9)
	v_pk_fma_f32 v[22:23], v[0:1], v[98:99], v[192:193] neg_lo:[1,0,0] neg_hi:[1,0,0]
	v_pk_fma_f32 v[30:31], v[2:3], v[100:101], 0 neg_lo:[1,0,0] neg_hi:[1,0,0]
	ds_read_b128 v[0:3], v33 offset:27392
	v_pk_fma_f32 v[22:23], v[4:5], v[102:103], v[22:23] neg_lo:[1,0,0] neg_hi:[1,0,0]
	v_pk_fma_f32 v[30:31], v[6:7], v[104:105], v[30:31] neg_lo:[1,0,0] neg_hi:[1,0,0]
	ds_read_b128 v[4:7], v33 offset:27408
	s_waitcnt lgkmcnt(9)
	v_pk_fma_f32 v[22:23], v[8:9], v[106:107], v[22:23] neg_lo:[1,0,0] neg_hi:[1,0,0]
	v_pk_fma_f32 v[30:31], v[10:11], v[108:109], v[30:31] neg_lo:[1,0,0] neg_hi:[1,0,0]
	ds_read_b128 v[8:11], v33 offset:27424
	v_pk_fma_f32 v[22:23], v[12:13], v[110:111], v[22:23] neg_lo:[1,0,0] neg_hi:[1,0,0]
	v_pk_fma_f32 v[30:31], v[14:15], v[112:113], v[30:31] neg_lo:[1,0,0] neg_hi:[1,0,0]
	ds_read_b128 v[12:15], v33 offset:27440
	s_waitcnt lgkmcnt(9)
	v_pk_fma_f32 v[22:23], v[16:17], v[114:115], v[22:23] neg_lo:[1,0,0] neg_hi:[1,0,0]
	v_pk_fma_f32 v[30:31], v[18:19], v[116:117], v[30:31] neg_lo:[1,0,0] neg_hi:[1,0,0]
	ds_read_b128 v[16:19], v33 offset:27456
	v_pk_fma_f32 v[22:23], v[26:27], v[118:119], v[22:23] neg_lo:[1,0,0] neg_hi:[1,0,0]
	v_pk_fma_f32 v[30:31], v[28:29], v[120:121], v[30:31] neg_lo:[1,0,0] neg_hi:[1,0,0]
	ds_read_b128 v[26:29], v33 offset:27472
	s_waitcnt lgkmcnt(9)
	v_pk_fma_f32 v[22:23], v[34:35], v[122:123], v[22:23] neg_lo:[1,0,0] neg_hi:[1,0,0]
	v_pk_fma_f32 v[30:31], v[36:37], v[124:125], v[30:31] neg_lo:[1,0,0] neg_hi:[1,0,0]
	ds_read_b128 v[34:37], v33 offset:27488
	v_pk_fma_f32 v[22:23], v[38:39], v[126:127], v[22:23] neg_lo:[1,0,0] neg_hi:[1,0,0]
	v_pk_fma_f32 v[30:31], v[40:41], v[128:129], v[30:31] neg_lo:[1,0,0] neg_hi:[1,0,0]
	ds_read_b128 v[38:41], v33 offset:27504
	s_waitcnt lgkmcnt(9)
	v_pk_fma_f32 v[22:23], v[42:43], v[130:131], v[22:23] neg_lo:[1,0,0] neg_hi:[1,0,0]
	v_pk_fma_f32 v[30:31], v[44:45], v[132:133], v[30:31] neg_lo:[1,0,0] neg_hi:[1,0,0]
	ds_read_b128 v[42:45], v33 offset:27520
	v_pk_fma_f32 v[22:23], v[46:47], v[134:135], v[22:23] neg_lo:[1,0,0] neg_hi:[1,0,0]
	v_pk_fma_f32 v[30:31], v[48:49], v[136:137], v[30:31] neg_lo:[1,0,0] neg_hi:[1,0,0]
	ds_read_b128 v[46:49], v33 offset:27536
	v_cmp_eq_u32_e32 vcc, 39, v152
	v_pk_add_f32 v[82:83], v[22:23], v[30:31]
	v_add_f32_e32 v136, v82, v83
	v_cvt_pk_bf16_f32 v25, v136, v136
	ds_write_b16 v84, v25 offset:5472
	v_cndmask_b32_e64 v192, 0, 1.0, vcc
	s_waitcnt lgkmcnt(9)
	v_pk_fma_f32 v[22:23], v[0:1], v[98:99], v[192:193] neg_lo:[1,0,0] neg_hi:[1,0,0]
	v_pk_fma_f32 v[30:31], v[2:3], v[100:101], 0 neg_lo:[1,0,0] neg_hi:[1,0,0]
	ds_read_b128 v[0:3], v33 offset:27648
	v_pk_fma_f32 v[22:23], v[4:5], v[102:103], v[22:23] neg_lo:[1,0,0] neg_hi:[1,0,0]
	v_pk_fma_f32 v[30:31], v[6:7], v[104:105], v[30:31] neg_lo:[1,0,0] neg_hi:[1,0,0]
	ds_read_b128 v[4:7], v33 offset:27664
	s_waitcnt lgkmcnt(9)
	v_pk_fma_f32 v[22:23], v[8:9], v[106:107], v[22:23] neg_lo:[1,0,0] neg_hi:[1,0,0]
	v_pk_fma_f32 v[30:31], v[10:11], v[108:109], v[30:31] neg_lo:[1,0,0] neg_hi:[1,0,0]
	ds_read_b128 v[8:11], v33 offset:27680
	v_pk_fma_f32 v[22:23], v[12:13], v[110:111], v[22:23] neg_lo:[1,0,0] neg_hi:[1,0,0]
	v_pk_fma_f32 v[30:31], v[14:15], v[112:113], v[30:31] neg_lo:[1,0,0] neg_hi:[1,0,0]
	ds_read_b128 v[12:15], v33 offset:27696
	s_waitcnt lgkmcnt(9)
	v_pk_fma_f32 v[22:23], v[16:17], v[114:115], v[22:23] neg_lo:[1,0,0] neg_hi:[1,0,0]
	v_pk_fma_f32 v[30:31], v[18:19], v[116:117], v[30:31] neg_lo:[1,0,0] neg_hi:[1,0,0]
	ds_read_b128 v[16:19], v33 offset:27712
	v_pk_fma_f32 v[22:23], v[26:27], v[118:119], v[22:23] neg_lo:[1,0,0] neg_hi:[1,0,0]
	v_pk_fma_f32 v[30:31], v[28:29], v[120:121], v[30:31] neg_lo:[1,0,0] neg_hi:[1,0,0]
	ds_read_b128 v[26:29], v33 offset:27728
	s_waitcnt lgkmcnt(9)
	v_pk_fma_f32 v[22:23], v[34:35], v[122:123], v[22:23] neg_lo:[1,0,0] neg_hi:[1,0,0]
	v_pk_fma_f32 v[30:31], v[36:37], v[124:125], v[30:31] neg_lo:[1,0,0] neg_hi:[1,0,0]
	ds_read_b128 v[34:37], v33 offset:27744
	v_pk_fma_f32 v[22:23], v[38:39], v[126:127], v[22:23] neg_lo:[1,0,0] neg_hi:[1,0,0]
	v_pk_fma_f32 v[30:31], v[40:41], v[128:129], v[30:31] neg_lo:[1,0,0] neg_hi:[1,0,0]
	ds_read_b128 v[38:41], v33 offset:27760
	s_waitcnt lgkmcnt(9)
	v_pk_fma_f32 v[22:23], v[42:43], v[130:131], v[22:23] neg_lo:[1,0,0] neg_hi:[1,0,0]
	v_pk_fma_f32 v[30:31], v[44:45], v[132:133], v[30:31] neg_lo:[1,0,0] neg_hi:[1,0,0]
	ds_read_b128 v[42:45], v33 offset:27776
	v_pk_fma_f32 v[22:23], v[46:47], v[134:135], v[22:23] neg_lo:[1,0,0] neg_hi:[1,0,0]
	v_pk_fma_f32 v[30:31], v[48:49], v[136:137], v[30:31] neg_lo:[1,0,0] neg_hi:[1,0,0]
	ds_read_b128 v[46:49], v33 offset:27792
	v_cmp_eq_u32_e32 vcc, 40, v152
	v_pk_add_f32 v[82:83], v[22:23], v[30:31]
	v_add_f32_e32 v137, v82, v83
	v_cvt_pk_bf16_f32 v25, v137, v137
	ds_write_b16 v84, v25 offset:5616
	v_cndmask_b32_e64 v192, 0, 1.0, vcc
	ds_read_b128 v[50:53], v33 offset:28064
	s_waitcnt lgkmcnt(10)
	v_pk_fma_f32 v[22:23], v[0:1], v[98:99], v[192:193] neg_lo:[1,0,0] neg_hi:[1,0,0]
	v_pk_fma_f32 v[30:31], v[2:3], v[100:101], 0 neg_lo:[1,0,0] neg_hi:[1,0,0]
	ds_read_b128 v[0:3], v33 offset:27904
	v_pk_fma_f32 v[22:23], v[4:5], v[102:103], v[22:23] neg_lo:[1,0,0] neg_hi:[1,0,0]
	v_pk_fma_f32 v[30:31], v[6:7], v[104:105], v[30:31] neg_lo:[1,0,0] neg_hi:[1,0,0]
	ds_read_b128 v[4:7], v33 offset:27920
	s_waitcnt lgkmcnt(10)
	v_pk_fma_f32 v[22:23], v[8:9], v[106:107], v[22:23] neg_lo:[1,0,0] neg_hi:[1,0,0]
	v_pk_fma_f32 v[30:31], v[10:11], v[108:109], v[30:31] neg_lo:[1,0,0] neg_hi:[1,0,0]
	ds_read_b128 v[8:11], v33 offset:27936
	v_pk_fma_f32 v[22:23], v[12:13], v[110:111], v[22:23] neg_lo:[1,0,0] neg_hi:[1,0,0]
	v_pk_fma_f32 v[30:31], v[14:15], v[112:113], v[30:31] neg_lo:[1,0,0] neg_hi:[1,0,0]
	ds_read_b128 v[12:15], v33 offset:27952
	s_waitcnt lgkmcnt(10)
	v_pk_fma_f32 v[22:23], v[16:17], v[114:115], v[22:23] neg_lo:[1,0,0] neg_hi:[1,0,0]
	v_pk_fma_f32 v[30:31], v[18:19], v[116:117], v[30:31] neg_lo:[1,0,0] neg_hi:[1,0,0]
	ds_read_b128 v[16:19], v33 offset:27968
	v_pk_fma_f32 v[22:23], v[26:27], v[118:119], v[22:23] neg_lo:[1,0,0] neg_hi:[1,0,0]
	v_pk_fma_f32 v[30:31], v[28:29], v[120:121], v[30:31] neg_lo:[1,0,0] neg_hi:[1,0,0]
	ds_read_b128 v[26:29], v33 offset:27984
	s_waitcnt lgkmcnt(10)
	v_pk_fma_f32 v[22:23], v[34:35], v[122:123], v[22:23] neg_lo:[1,0,0] neg_hi:[1,0,0]
	v_pk_fma_f32 v[30:31], v[36:37], v[124:125], v[30:31] neg_lo:[1,0,0] neg_hi:[1,0,0]
	ds_read_b128 v[34:37], v33 offset:28000
	v_pk_fma_f32 v[22:23], v[38:39], v[126:127], v[22:23] neg_lo:[1,0,0] neg_hi:[1,0,0]
	v_pk_fma_f32 v[30:31], v[40:41], v[128:129], v[30:31] neg_lo:[1,0,0] neg_hi:[1,0,0]
	ds_read_b128 v[38:41], v33 offset:28016
	s_waitcnt lgkmcnt(10)
	v_pk_fma_f32 v[22:23], v[42:43], v[130:131], v[22:23] neg_lo:[1,0,0] neg_hi:[1,0,0]
	v_pk_fma_f32 v[30:31], v[44:45], v[132:133], v[30:31] neg_lo:[1,0,0] neg_hi:[1,0,0]
	ds_read_b128 v[42:45], v33 offset:28032
	v_pk_fma_f32 v[22:23], v[46:47], v[134:135], v[22:23] neg_lo:[1,0,0] neg_hi:[1,0,0]
	v_pk_fma_f32 v[30:31], v[48:49], v[136:137], v[30:31] neg_lo:[1,0,0] neg_hi:[1,0,0]
	ds_read_b128 v[46:49], v33 offset:28048
	v_cmp_eq_u32_e32 vcc, 41, v152
	v_pk_add_f32 v[82:83], v[22:23], v[30:31]
	v_add_f32_e32 v138, v82, v83
	v_cvt_pk_bf16_f32 v25, v138, v138
	ds_write_b16 v84, v25 offset:5760
	v_cndmask_b32_e64 v192, 0, 1.0, vcc
	s_waitcnt lgkmcnt(9)
	v_pk_fma_f32 v[22:23], v[0:1], v[98:99], v[192:193] neg_lo:[1,0,0] neg_hi:[1,0,0]
	v_pk_fma_f32 v[30:31], v[2:3], v[100:101], 0 neg_lo:[1,0,0] neg_hi:[1,0,0]
	ds_read_b128 v[0:3], v33 offset:28160
	v_pk_fma_f32 v[22:23], v[4:5], v[102:103], v[22:23] neg_lo:[1,0,0] neg_hi:[1,0,0]
	v_pk_fma_f32 v[30:31], v[6:7], v[104:105], v[30:31] neg_lo:[1,0,0] neg_hi:[1,0,0]
	ds_read_b128 v[4:7], v33 offset:28176
	s_waitcnt lgkmcnt(9)
	v_pk_fma_f32 v[22:23], v[8:9], v[106:107], v[22:23] neg_lo:[1,0,0] neg_hi:[1,0,0]
	v_pk_fma_f32 v[30:31], v[10:11], v[108:109], v[30:31] neg_lo:[1,0,0] neg_hi:[1,0,0]
	ds_read_b128 v[8:11], v33 offset:28192
	v_pk_fma_f32 v[22:23], v[12:13], v[110:111], v[22:23] neg_lo:[1,0,0] neg_hi:[1,0,0]
	v_pk_fma_f32 v[30:31], v[14:15], v[112:113], v[30:31] neg_lo:[1,0,0] neg_hi:[1,0,0]
	ds_read_b128 v[12:15], v33 offset:28208
	s_waitcnt lgkmcnt(9)
	v_pk_fma_f32 v[22:23], v[16:17], v[114:115], v[22:23] neg_lo:[1,0,0] neg_hi:[1,0,0]
	v_pk_fma_f32 v[30:31], v[18:19], v[116:117], v[30:31] neg_lo:[1,0,0] neg_hi:[1,0,0]
	ds_read_b128 v[16:19], v33 offset:28224
	v_pk_fma_f32 v[22:23], v[26:27], v[118:119], v[22:23] neg_lo:[1,0,0] neg_hi:[1,0,0]
	v_pk_fma_f32 v[30:31], v[28:29], v[120:121], v[30:31] neg_lo:[1,0,0] neg_hi:[1,0,0]
	ds_read_b128 v[26:29], v33 offset:28240
	s_waitcnt lgkmcnt(9)
	v_pk_fma_f32 v[22:23], v[34:35], v[122:123], v[22:23] neg_lo:[1,0,0] neg_hi:[1,0,0]
	v_pk_fma_f32 v[30:31], v[36:37], v[124:125], v[30:31] neg_lo:[1,0,0] neg_hi:[1,0,0]
	ds_read_b128 v[34:37], v33 offset:28256
	v_pk_fma_f32 v[22:23], v[38:39], v[126:127], v[22:23] neg_lo:[1,0,0] neg_hi:[1,0,0]
	v_pk_fma_f32 v[30:31], v[40:41], v[128:129], v[30:31] neg_lo:[1,0,0] neg_hi:[1,0,0]
	ds_read_b128 v[38:41], v33 offset:28272
	s_waitcnt lgkmcnt(9)
	v_pk_fma_f32 v[22:23], v[42:43], v[130:131], v[22:23] neg_lo:[1,0,0] neg_hi:[1,0,0]
	v_pk_fma_f32 v[30:31], v[44:45], v[132:133], v[30:31] neg_lo:[1,0,0] neg_hi:[1,0,0]
	ds_read_b128 v[42:45], v33 offset:28288
	v_pk_fma_f32 v[22:23], v[46:47], v[134:135], v[22:23] neg_lo:[1,0,0] neg_hi:[1,0,0]
	v_pk_fma_f32 v[30:31], v[48:49], v[136:137], v[30:31] neg_lo:[1,0,0] neg_hi:[1,0,0]
	ds_read_b128 v[46:49], v33 offset:28304
	s_waitcnt lgkmcnt(15)
	v_pk_fma_f32 v[22:23], v[50:51], v[138:139], v[22:23] neg_lo:[1,0,0] neg_hi:[1,0,0]
	v_pk_fma_f32 v[30:31], v[52:53], v[140:141], v[30:31] neg_lo:[1,0,0] neg_hi:[1,0,0]
	ds_read_b128 v[50:53], v33 offset:28320
	v_cmp_eq_u32_e32 vcc, 42, v152
	v_pk_add_f32 v[82:83], v[22:23], v[30:31]
	v_add_f32_e32 v139, v82, v83
	v_cvt_pk_bf16_f32 v25, v139, v139
	ds_write_b16 v84, v25 offset:5904
	v_cndmask_b32_e64 v192, 0, 1.0, vcc
	s_waitcnt lgkmcnt(10)
	v_pk_fma_f32 v[22:23], v[0:1], v[98:99], v[192:193] neg_lo:[1,0,0] neg_hi:[1,0,0]
	v_pk_fma_f32 v[30:31], v[2:3], v[100:101], 0 neg_lo:[1,0,0] neg_hi:[1,0,0]
	ds_read_b128 v[0:3], v33 offset:28416
	v_pk_fma_f32 v[22:23], v[4:5], v[102:103], v[22:23] neg_lo:[1,0,0] neg_hi:[1,0,0]
	v_pk_fma_f32 v[30:31], v[6:7], v[104:105], v[30:31] neg_lo:[1,0,0] neg_hi:[1,0,0]
	ds_read_b128 v[4:7], v33 offset:28432
	s_waitcnt lgkmcnt(10)
	v_pk_fma_f32 v[22:23], v[8:9], v[106:107], v[22:23] neg_lo:[1,0,0] neg_hi:[1,0,0]
	v_pk_fma_f32 v[30:31], v[10:11], v[108:109], v[30:31] neg_lo:[1,0,0] neg_hi:[1,0,0]
	ds_read_b128 v[8:11], v33 offset:28448
	v_pk_fma_f32 v[22:23], v[12:13], v[110:111], v[22:23] neg_lo:[1,0,0] neg_hi:[1,0,0]
	v_pk_fma_f32 v[30:31], v[14:15], v[112:113], v[30:31] neg_lo:[1,0,0] neg_hi:[1,0,0]
	ds_read_b128 v[12:15], v33 offset:28464
	s_waitcnt lgkmcnt(10)
	v_pk_fma_f32 v[22:23], v[16:17], v[114:115], v[22:23] neg_lo:[1,0,0] neg_hi:[1,0,0]
	v_pk_fma_f32 v[30:31], v[18:19], v[116:117], v[30:31] neg_lo:[1,0,0] neg_hi:[1,0,0]
	ds_read_b128 v[16:19], v33 offset:28480
	v_pk_fma_f32 v[22:23], v[26:27], v[118:119], v[22:23] neg_lo:[1,0,0] neg_hi:[1,0,0]
	v_pk_fma_f32 v[30:31], v[28:29], v[120:121], v[30:31] neg_lo:[1,0,0] neg_hi:[1,0,0]
	ds_read_b128 v[26:29], v33 offset:28496
	s_waitcnt lgkmcnt(10)
	v_pk_fma_f32 v[22:23], v[34:35], v[122:123], v[22:23] neg_lo:[1,0,0] neg_hi:[1,0,0]
	v_pk_fma_f32 v[30:31], v[36:37], v[124:125], v[30:31] neg_lo:[1,0,0] neg_hi:[1,0,0]
	ds_read_b128 v[34:37], v33 offset:28512
	v_pk_fma_f32 v[22:23], v[38:39], v[126:127], v[22:23] neg_lo:[1,0,0] neg_hi:[1,0,0]
	v_pk_fma_f32 v[30:31], v[40:41], v[128:129], v[30:31] neg_lo:[1,0,0] neg_hi:[1,0,0]
	ds_read_b128 v[38:41], v33 offset:28528
	s_waitcnt lgkmcnt(10)
	v_pk_fma_f32 v[22:23], v[42:43], v[130:131], v[22:23] neg_lo:[1,0,0] neg_hi:[1,0,0]
	v_pk_fma_f32 v[30:31], v[44:45], v[132:133], v[30:31] neg_lo:[1,0,0] neg_hi:[1,0,0]
	ds_read_b128 v[42:45], v33 offset:28544
	v_pk_fma_f32 v[22:23], v[46:47], v[134:135], v[22:23] neg_lo:[1,0,0] neg_hi:[1,0,0]
	v_pk_fma_f32 v[30:31], v[48:49], v[136:137], v[30:31] neg_lo:[1,0,0] neg_hi:[1,0,0]
	ds_read_b128 v[46:49], v33 offset:28560
	s_waitcnt lgkmcnt(11)
	v_pk_fma_f32 v[22:23], v[50:51], v[138:139], v[22:23] neg_lo:[1,0,0] neg_hi:[1,0,0]
	v_pk_fma_f32 v[30:31], v[52:53], v[140:141], v[30:31] neg_lo:[1,0,0] neg_hi:[1,0,0]
	ds_read_b128 v[50:53], v33 offset:28576
	v_cmp_eq_u32_e32 vcc, 43, v152
	v_pk_add_f32 v[82:83], v[22:23], v[30:31]
	v_add_f32_e32 v140, v82, v83
	v_cvt_pk_bf16_f32 v25, v140, v140
	ds_write_b16 v84, v25 offset:6048
	v_cndmask_b32_e64 v192, 0, 1.0, vcc
	s_waitcnt lgkmcnt(10)
	v_pk_fma_f32 v[22:23], v[0:1], v[98:99], v[192:193] neg_lo:[1,0,0] neg_hi:[1,0,0]
	v_pk_fma_f32 v[30:31], v[2:3], v[100:101], 0 neg_lo:[1,0,0] neg_hi:[1,0,0]
	ds_read_b128 v[0:3], v33 offset:28672
	v_pk_fma_f32 v[22:23], v[4:5], v[102:103], v[22:23] neg_lo:[1,0,0] neg_hi:[1,0,0]
	v_pk_fma_f32 v[30:31], v[6:7], v[104:105], v[30:31] neg_lo:[1,0,0] neg_hi:[1,0,0]
	ds_read_b128 v[4:7], v33 offset:28688
	s_waitcnt lgkmcnt(10)
	v_pk_fma_f32 v[22:23], v[8:9], v[106:107], v[22:23] neg_lo:[1,0,0] neg_hi:[1,0,0]
	v_pk_fma_f32 v[30:31], v[10:11], v[108:109], v[30:31] neg_lo:[1,0,0] neg_hi:[1,0,0]
	ds_read_b128 v[8:11], v33 offset:28704
	v_pk_fma_f32 v[22:23], v[12:13], v[110:111], v[22:23] neg_lo:[1,0,0] neg_hi:[1,0,0]
	v_pk_fma_f32 v[30:31], v[14:15], v[112:113], v[30:31] neg_lo:[1,0,0] neg_hi:[1,0,0]
	ds_read_b128 v[12:15], v33 offset:28720
	s_waitcnt lgkmcnt(10)
	v_pk_fma_f32 v[22:23], v[16:17], v[114:115], v[22:23] neg_lo:[1,0,0] neg_hi:[1,0,0]
	v_pk_fma_f32 v[30:31], v[18:19], v[116:117], v[30:31] neg_lo:[1,0,0] neg_hi:[1,0,0]
	ds_read_b128 v[16:19], v33 offset:28736
	v_pk_fma_f32 v[22:23], v[26:27], v[118:119], v[22:23] neg_lo:[1,0,0] neg_hi:[1,0,0]
	v_pk_fma_f32 v[30:31], v[28:29], v[120:121], v[30:31] neg_lo:[1,0,0] neg_hi:[1,0,0]
	ds_read_b128 v[26:29], v33 offset:28752
	s_waitcnt lgkmcnt(10)
	v_pk_fma_f32 v[22:23], v[34:35], v[122:123], v[22:23] neg_lo:[1,0,0] neg_hi:[1,0,0]
	v_pk_fma_f32 v[30:31], v[36:37], v[124:125], v[30:31] neg_lo:[1,0,0] neg_hi:[1,0,0]
	ds_read_b128 v[34:37], v33 offset:28768
	v_pk_fma_f32 v[22:23], v[38:39], v[126:127], v[22:23] neg_lo:[1,0,0] neg_hi:[1,0,0]
	v_pk_fma_f32 v[30:31], v[40:41], v[128:129], v[30:31] neg_lo:[1,0,0] neg_hi:[1,0,0]
	ds_read_b128 v[38:41], v33 offset:28784
	s_waitcnt lgkmcnt(10)
	v_pk_fma_f32 v[22:23], v[42:43], v[130:131], v[22:23] neg_lo:[1,0,0] neg_hi:[1,0,0]
	v_pk_fma_f32 v[30:31], v[44:45], v[132:133], v[30:31] neg_lo:[1,0,0] neg_hi:[1,0,0]
	ds_read_b128 v[42:45], v33 offset:28800
	v_pk_fma_f32 v[22:23], v[46:47], v[134:135], v[22:23] neg_lo:[1,0,0] neg_hi:[1,0,0]
	v_pk_fma_f32 v[30:31], v[48:49], v[136:137], v[30:31] neg_lo:[1,0,0] neg_hi:[1,0,0]
	ds_read_b128 v[46:49], v33 offset:28816
	s_waitcnt lgkmcnt(11)
	v_pk_fma_f32 v[22:23], v[50:51], v[138:139], v[22:23] neg_lo:[1,0,0] neg_hi:[1,0,0]
	v_pk_fma_f32 v[30:31], v[52:53], v[140:141], v[30:31] neg_lo:[1,0,0] neg_hi:[1,0,0]
	ds_read_b128 v[50:53], v33 offset:28832
	v_cmp_eq_u32_e32 vcc, 44, v152
	v_pk_add_f32 v[82:83], v[22:23], v[30:31]
	v_add_f32_e32 v141, v82, v83
	v_cvt_pk_bf16_f32 v25, v141, v141
	ds_write_b16 v84, v25 offset:6192
	v_cndmask_b32_e64 v192, 0, 1.0, vcc
	ds_read_b128 v[54:57], v33 offset:29104
	s_waitcnt lgkmcnt(11)
	v_pk_fma_f32 v[22:23], v[0:1], v[98:99], v[192:193] neg_lo:[1,0,0] neg_hi:[1,0,0]
	v_pk_fma_f32 v[30:31], v[2:3], v[100:101], 0 neg_lo:[1,0,0] neg_hi:[1,0,0]
	ds_read_b128 v[0:3], v33 offset:28928
	v_pk_fma_f32 v[22:23], v[4:5], v[102:103], v[22:23] neg_lo:[1,0,0] neg_hi:[1,0,0]
	v_pk_fma_f32 v[30:31], v[6:7], v[104:105], v[30:31] neg_lo:[1,0,0] neg_hi:[1,0,0]
	ds_read_b128 v[4:7], v33 offset:28944
	s_waitcnt lgkmcnt(11)
	v_pk_fma_f32 v[22:23], v[8:9], v[106:107], v[22:23] neg_lo:[1,0,0] neg_hi:[1,0,0]
	v_pk_fma_f32 v[30:31], v[10:11], v[108:109], v[30:31] neg_lo:[1,0,0] neg_hi:[1,0,0]
	ds_read_b128 v[8:11], v33 offset:28960
	v_pk_fma_f32 v[22:23], v[12:13], v[110:111], v[22:23] neg_lo:[1,0,0] neg_hi:[1,0,0]
	v_pk_fma_f32 v[30:31], v[14:15], v[112:113], v[30:31] neg_lo:[1,0,0] neg_hi:[1,0,0]
	ds_read_b128 v[12:15], v33 offset:28976
	s_waitcnt lgkmcnt(11)
	v_pk_fma_f32 v[22:23], v[16:17], v[114:115], v[22:23] neg_lo:[1,0,0] neg_hi:[1,0,0]
	v_pk_fma_f32 v[30:31], v[18:19], v[116:117], v[30:31] neg_lo:[1,0,0] neg_hi:[1,0,0]
	ds_read_b128 v[16:19], v33 offset:28992
	v_pk_fma_f32 v[22:23], v[26:27], v[118:119], v[22:23] neg_lo:[1,0,0] neg_hi:[1,0,0]
	v_pk_fma_f32 v[30:31], v[28:29], v[120:121], v[30:31] neg_lo:[1,0,0] neg_hi:[1,0,0]
	ds_read_b128 v[26:29], v33 offset:29008
	s_waitcnt lgkmcnt(11)
	v_pk_fma_f32 v[22:23], v[34:35], v[122:123], v[22:23] neg_lo:[1,0,0] neg_hi:[1,0,0]
	v_pk_fma_f32 v[30:31], v[36:37], v[124:125], v[30:31] neg_lo:[1,0,0] neg_hi:[1,0,0]
	ds_read_b128 v[34:37], v33 offset:29024
	v_pk_fma_f32 v[22:23], v[38:39], v[126:127], v[22:23] neg_lo:[1,0,0] neg_hi:[1,0,0]
	v_pk_fma_f32 v[30:31], v[40:41], v[128:129], v[30:31] neg_lo:[1,0,0] neg_hi:[1,0,0]
	ds_read_b128 v[38:41], v33 offset:29040
	s_waitcnt lgkmcnt(11)
	v_pk_fma_f32 v[22:23], v[42:43], v[130:131], v[22:23] neg_lo:[1,0,0] neg_hi:[1,0,0]
	v_pk_fma_f32 v[30:31], v[44:45], v[132:133], v[30:31] neg_lo:[1,0,0] neg_hi:[1,0,0]
	ds_read_b128 v[42:45], v33 offset:29056
	v_pk_fma_f32 v[22:23], v[46:47], v[134:135], v[22:23] neg_lo:[1,0,0] neg_hi:[1,0,0]
	v_pk_fma_f32 v[30:31], v[48:49], v[136:137], v[30:31] neg_lo:[1,0,0] neg_hi:[1,0,0]
	ds_read_b128 v[46:49], v33 offset:29072
	s_waitcnt lgkmcnt(12)
	v_pk_fma_f32 v[22:23], v[50:51], v[138:139], v[22:23] neg_lo:[1,0,0] neg_hi:[1,0,0]
	v_pk_fma_f32 v[30:31], v[52:53], v[140:141], v[30:31] neg_lo:[1,0,0] neg_hi:[1,0,0]
	ds_read_b128 v[50:53], v33 offset:29088
	v_cmp_eq_u32_e32 vcc, 45, v152
	v_pk_add_f32 v[82:83], v[22:23], v[30:31]
	v_add_f32_e32 v142, v82, v83
	v_cvt_pk_bf16_f32 v25, v142, v142
	ds_write_b16 v84, v25 offset:6336
	v_cndmask_b32_e64 v192, 0, 1.0, vcc
	s_waitcnt lgkmcnt(10)
	v_pk_fma_f32 v[22:23], v[0:1], v[98:99], v[192:193] neg_lo:[1,0,0] neg_hi:[1,0,0]
	v_pk_fma_f32 v[30:31], v[2:3], v[100:101], 0 neg_lo:[1,0,0] neg_hi:[1,0,0]
	ds_read_b128 v[0:3], v33 offset:29184
	v_pk_fma_f32 v[22:23], v[4:5], v[102:103], v[22:23] neg_lo:[1,0,0] neg_hi:[1,0,0]
	v_pk_fma_f32 v[30:31], v[6:7], v[104:105], v[30:31] neg_lo:[1,0,0] neg_hi:[1,0,0]
	ds_read_b128 v[4:7], v33 offset:29200
	s_waitcnt lgkmcnt(10)
	v_pk_fma_f32 v[22:23], v[8:9], v[106:107], v[22:23] neg_lo:[1,0,0] neg_hi:[1,0,0]
	v_pk_fma_f32 v[30:31], v[10:11], v[108:109], v[30:31] neg_lo:[1,0,0] neg_hi:[1,0,0]
	ds_read_b128 v[8:11], v33 offset:29216
	v_pk_fma_f32 v[22:23], v[12:13], v[110:111], v[22:23] neg_lo:[1,0,0] neg_hi:[1,0,0]
	v_pk_fma_f32 v[30:31], v[14:15], v[112:113], v[30:31] neg_lo:[1,0,0] neg_hi:[1,0,0]
	ds_read_b128 v[12:15], v33 offset:29232
	s_waitcnt lgkmcnt(10)
	v_pk_fma_f32 v[22:23], v[16:17], v[114:115], v[22:23] neg_lo:[1,0,0] neg_hi:[1,0,0]
	v_pk_fma_f32 v[30:31], v[18:19], v[116:117], v[30:31] neg_lo:[1,0,0] neg_hi:[1,0,0]
	ds_read_b128 v[16:19], v33 offset:29248
	v_pk_fma_f32 v[22:23], v[26:27], v[118:119], v[22:23] neg_lo:[1,0,0] neg_hi:[1,0,0]
	v_pk_fma_f32 v[30:31], v[28:29], v[120:121], v[30:31] neg_lo:[1,0,0] neg_hi:[1,0,0]
	ds_read_b128 v[26:29], v33 offset:29264
	s_waitcnt lgkmcnt(10)
	v_pk_fma_f32 v[22:23], v[34:35], v[122:123], v[22:23] neg_lo:[1,0,0] neg_hi:[1,0,0]
	v_pk_fma_f32 v[30:31], v[36:37], v[124:125], v[30:31] neg_lo:[1,0,0] neg_hi:[1,0,0]
	ds_read_b128 v[34:37], v33 offset:29280
	v_pk_fma_f32 v[22:23], v[38:39], v[126:127], v[22:23] neg_lo:[1,0,0] neg_hi:[1,0,0]
	v_pk_fma_f32 v[30:31], v[40:41], v[128:129], v[30:31] neg_lo:[1,0,0] neg_hi:[1,0,0]
	ds_read_b128 v[38:41], v33 offset:29296
	s_waitcnt lgkmcnt(10)
	v_pk_fma_f32 v[22:23], v[42:43], v[130:131], v[22:23] neg_lo:[1,0,0] neg_hi:[1,0,0]
	v_pk_fma_f32 v[30:31], v[44:45], v[132:133], v[30:31] neg_lo:[1,0,0] neg_hi:[1,0,0]
	ds_read_b128 v[42:45], v33 offset:29312
	v_pk_fma_f32 v[22:23], v[46:47], v[134:135], v[22:23] neg_lo:[1,0,0] neg_hi:[1,0,0]
	v_pk_fma_f32 v[30:31], v[48:49], v[136:137], v[30:31] neg_lo:[1,0,0] neg_hi:[1,0,0]
	ds_read_b128 v[46:49], v33 offset:29328
	s_waitcnt lgkmcnt(15)
	v_pk_fma_f32 v[22:23], v[50:51], v[138:139], v[22:23] neg_lo:[1,0,0] neg_hi:[1,0,0]
	v_pk_fma_f32 v[30:31], v[52:53], v[140:141], v[30:31] neg_lo:[1,0,0] neg_hi:[1,0,0]
	ds_read_b128 v[50:53], v33 offset:29344
	v_pk_fma_f32 v[22:23], v[54:55], v[142:143], v[22:23] neg_lo:[1,0,0] neg_hi:[1,0,0]
	v_pk_fma_f32 v[30:31], v[56:57], v[162:163], v[30:31] neg_lo:[1,0,0] neg_hi:[1,0,0]
	ds_read_b128 v[54:57], v33 offset:29360
	v_cmp_eq_u32_e32 vcc, 46, v152
	v_pk_add_f32 v[82:83], v[22:23], v[30:31]
	v_add_f32_e32 v143, v82, v83
	v_cvt_pk_bf16_f32 v25, v143, v143
	ds_write_b16 v84, v25 offset:6480
	v_cndmask_b32_e64 v192, 0, 1.0, vcc
	s_waitcnt lgkmcnt(11)
	v_pk_fma_f32 v[22:23], v[0:1], v[98:99], v[192:193] neg_lo:[1,0,0] neg_hi:[1,0,0]
	v_pk_fma_f32 v[30:31], v[2:3], v[100:101], 0 neg_lo:[1,0,0] neg_hi:[1,0,0]
	ds_read_b128 v[0:3], v33 offset:29440
	v_pk_fma_f32 v[22:23], v[4:5], v[102:103], v[22:23] neg_lo:[1,0,0] neg_hi:[1,0,0]
	v_pk_fma_f32 v[30:31], v[6:7], v[104:105], v[30:31] neg_lo:[1,0,0] neg_hi:[1,0,0]
	ds_read_b128 v[4:7], v33 offset:29456
	s_waitcnt lgkmcnt(11)
	v_pk_fma_f32 v[22:23], v[8:9], v[106:107], v[22:23] neg_lo:[1,0,0] neg_hi:[1,0,0]
	v_pk_fma_f32 v[30:31], v[10:11], v[108:109], v[30:31] neg_lo:[1,0,0] neg_hi:[1,0,0]
	ds_read_b128 v[8:11], v33 offset:29472
	v_pk_fma_f32 v[22:23], v[12:13], v[110:111], v[22:23] neg_lo:[1,0,0] neg_hi:[1,0,0]
	v_pk_fma_f32 v[30:31], v[14:15], v[112:113], v[30:31] neg_lo:[1,0,0] neg_hi:[1,0,0]
	ds_read_b128 v[12:15], v33 offset:29488
	s_waitcnt lgkmcnt(11)
	v_pk_fma_f32 v[22:23], v[16:17], v[114:115], v[22:23] neg_lo:[1,0,0] neg_hi:[1,0,0]
	v_pk_fma_f32 v[30:31], v[18:19], v[116:117], v[30:31] neg_lo:[1,0,0] neg_hi:[1,0,0]
	ds_read_b128 v[16:19], v33 offset:29504
	v_pk_fma_f32 v[22:23], v[26:27], v[118:119], v[22:23] neg_lo:[1,0,0] neg_hi:[1,0,0]
	v_pk_fma_f32 v[30:31], v[28:29], v[120:121], v[30:31] neg_lo:[1,0,0] neg_hi:[1,0,0]
	ds_read_b128 v[26:29], v33 offset:29520
	s_waitcnt lgkmcnt(11)
	v_pk_fma_f32 v[22:23], v[34:35], v[122:123], v[22:23] neg_lo:[1,0,0] neg_hi:[1,0,0]
	v_pk_fma_f32 v[30:31], v[36:37], v[124:125], v[30:31] neg_lo:[1,0,0] neg_hi:[1,0,0]
	ds_read_b128 v[34:37], v33 offset:29536
	v_pk_fma_f32 v[22:23], v[38:39], v[126:127], v[22:23] neg_lo:[1,0,0] neg_hi:[1,0,0]
	v_pk_fma_f32 v[30:31], v[40:41], v[128:129], v[30:31] neg_lo:[1,0,0] neg_hi:[1,0,0]
	ds_read_b128 v[38:41], v33 offset:29552
	s_waitcnt lgkmcnt(11)
	v_pk_fma_f32 v[22:23], v[42:43], v[130:131], v[22:23] neg_lo:[1,0,0] neg_hi:[1,0,0]
	v_pk_fma_f32 v[30:31], v[44:45], v[132:133], v[30:31] neg_lo:[1,0,0] neg_hi:[1,0,0]
	ds_read_b128 v[42:45], v33 offset:29568
	v_pk_fma_f32 v[22:23], v[46:47], v[134:135], v[22:23] neg_lo:[1,0,0] neg_hi:[1,0,0]
	v_pk_fma_f32 v[30:31], v[48:49], v[136:137], v[30:31] neg_lo:[1,0,0] neg_hi:[1,0,0]
	ds_read_b128 v[46:49], v33 offset:29584
	s_waitcnt lgkmcnt(11)
	v_pk_fma_f32 v[22:23], v[50:51], v[138:139], v[22:23] neg_lo:[1,0,0] neg_hi:[1,0,0]
	v_pk_fma_f32 v[30:31], v[52:53], v[140:141], v[30:31] neg_lo:[1,0,0] neg_hi:[1,0,0]
	ds_read_b128 v[50:53], v33 offset:29600
	v_pk_fma_f32 v[22:23], v[54:55], v[142:143], v[22:23] neg_lo:[1,0,0] neg_hi:[1,0,0]
	v_pk_fma_f32 v[30:31], v[56:57], v[162:163], v[30:31] neg_lo:[1,0,0] neg_hi:[1,0,0]
	ds_read_b128 v[54:57], v33 offset:29616
	v_cmp_eq_u32_e32 vcc, 47, v152
	v_pk_add_f32 v[82:83], v[22:23], v[30:31]
	v_add_f32_e32 v162, v82, v83
	v_cvt_pk_bf16_f32 v25, v162, v162
	ds_write_b16 v84, v25 offset:6624
	v_cndmask_b32_e64 v192, 0, 1.0, vcc
	s_waitcnt lgkmcnt(11)
	v_pk_fma_f32 v[22:23], v[0:1], v[98:99], v[192:193] neg_lo:[1,0,0] neg_hi:[1,0,0]
	v_pk_fma_f32 v[30:31], v[2:3], v[100:101], 0 neg_lo:[1,0,0] neg_hi:[1,0,0]
	ds_read_b128 v[0:3], v33 offset:29696
	v_pk_fma_f32 v[22:23], v[4:5], v[102:103], v[22:23] neg_lo:[1,0,0] neg_hi:[1,0,0]
	v_pk_fma_f32 v[30:31], v[6:7], v[104:105], v[30:31] neg_lo:[1,0,0] neg_hi:[1,0,0]
	ds_read_b128 v[4:7], v33 offset:29712
	s_waitcnt lgkmcnt(11)
	v_pk_fma_f32 v[22:23], v[8:9], v[106:107], v[22:23] neg_lo:[1,0,0] neg_hi:[1,0,0]
	v_pk_fma_f32 v[30:31], v[10:11], v[108:109], v[30:31] neg_lo:[1,0,0] neg_hi:[1,0,0]
	ds_read_b128 v[8:11], v33 offset:29728
	v_pk_fma_f32 v[22:23], v[12:13], v[110:111], v[22:23] neg_lo:[1,0,0] neg_hi:[1,0,0]
	v_pk_fma_f32 v[30:31], v[14:15], v[112:113], v[30:31] neg_lo:[1,0,0] neg_hi:[1,0,0]
	ds_read_b128 v[12:15], v33 offset:29744
	s_waitcnt lgkmcnt(11)
	v_pk_fma_f32 v[22:23], v[16:17], v[114:115], v[22:23] neg_lo:[1,0,0] neg_hi:[1,0,0]
	v_pk_fma_f32 v[30:31], v[18:19], v[116:117], v[30:31] neg_lo:[1,0,0] neg_hi:[1,0,0]
	ds_read_b128 v[16:19], v33 offset:29760
	v_pk_fma_f32 v[22:23], v[26:27], v[118:119], v[22:23] neg_lo:[1,0,0] neg_hi:[1,0,0]
	v_pk_fma_f32 v[30:31], v[28:29], v[120:121], v[30:31] neg_lo:[1,0,0] neg_hi:[1,0,0]
	ds_read_b128 v[26:29], v33 offset:29776
	s_waitcnt lgkmcnt(11)
	v_pk_fma_f32 v[22:23], v[34:35], v[122:123], v[22:23] neg_lo:[1,0,0] neg_hi:[1,0,0]
	v_pk_fma_f32 v[30:31], v[36:37], v[124:125], v[30:31] neg_lo:[1,0,0] neg_hi:[1,0,0]
	ds_read_b128 v[34:37], v33 offset:29792
	v_pk_fma_f32 v[22:23], v[38:39], v[126:127], v[22:23] neg_lo:[1,0,0] neg_hi:[1,0,0]
	v_pk_fma_f32 v[30:31], v[40:41], v[128:129], v[30:31] neg_lo:[1,0,0] neg_hi:[1,0,0]
	ds_read_b128 v[38:41], v33 offset:29808
	s_waitcnt lgkmcnt(11)
	v_pk_fma_f32 v[22:23], v[42:43], v[130:131], v[22:23] neg_lo:[1,0,0] neg_hi:[1,0,0]
	v_pk_fma_f32 v[30:31], v[44:45], v[132:133], v[30:31] neg_lo:[1,0,0] neg_hi:[1,0,0]
	ds_read_b128 v[42:45], v33 offset:29824
	v_pk_fma_f32 v[22:23], v[46:47], v[134:135], v[22:23] neg_lo:[1,0,0] neg_hi:[1,0,0]
	v_pk_fma_f32 v[30:31], v[48:49], v[136:137], v[30:31] neg_lo:[1,0,0] neg_hi:[1,0,0]
	ds_read_b128 v[46:49], v33 offset:29840
	s_waitcnt lgkmcnt(11)
	v_pk_fma_f32 v[22:23], v[50:51], v[138:139], v[22:23] neg_lo:[1,0,0] neg_hi:[1,0,0]
	v_pk_fma_f32 v[30:31], v[52:53], v[140:141], v[30:31] neg_lo:[1,0,0] neg_hi:[1,0,0]
	ds_read_b128 v[50:53], v33 offset:29856
	v_pk_fma_f32 v[22:23], v[54:55], v[142:143], v[22:23] neg_lo:[1,0,0] neg_hi:[1,0,0]
	v_pk_fma_f32 v[30:31], v[56:57], v[162:163], v[30:31] neg_lo:[1,0,0] neg_hi:[1,0,0]
	ds_read_b128 v[54:57], v33 offset:29872
	v_cmp_eq_u32_e32 vcc, 48, v152
	v_pk_add_f32 v[82:83], v[22:23], v[30:31]
	v_add_f32_e32 v163, v82, v83
	v_cvt_pk_bf16_f32 v25, v163, v163
	ds_write_b16 v84, v25 offset:6768
	v_cndmask_b32_e64 v192, 0, 1.0, vcc
	ds_read_b128 v[58:61], v33 offset:30144
	s_waitcnt lgkmcnt(12)
	v_pk_fma_f32 v[22:23], v[0:1], v[98:99], v[192:193] neg_lo:[1,0,0] neg_hi:[1,0,0]
	v_pk_fma_f32 v[30:31], v[2:3], v[100:101], 0 neg_lo:[1,0,0] neg_hi:[1,0,0]
	ds_read_b128 v[0:3], v33 offset:29952
	v_pk_fma_f32 v[22:23], v[4:5], v[102:103], v[22:23] neg_lo:[1,0,0] neg_hi:[1,0,0]
	v_pk_fma_f32 v[30:31], v[6:7], v[104:105], v[30:31] neg_lo:[1,0,0] neg_hi:[1,0,0]
	ds_read_b128 v[4:7], v33 offset:29968
	s_waitcnt lgkmcnt(12)
	v_pk_fma_f32 v[22:23], v[8:9], v[106:107], v[22:23] neg_lo:[1,0,0] neg_hi:[1,0,0]
	v_pk_fma_f32 v[30:31], v[10:11], v[108:109], v[30:31] neg_lo:[1,0,0] neg_hi:[1,0,0]
	ds_read_b128 v[8:11], v33 offset:29984
	v_pk_fma_f32 v[22:23], v[12:13], v[110:111], v[22:23] neg_lo:[1,0,0] neg_hi:[1,0,0]
	v_pk_fma_f32 v[30:31], v[14:15], v[112:113], v[30:31] neg_lo:[1,0,0] neg_hi:[1,0,0]
	ds_read_b128 v[12:15], v33 offset:30000
	s_waitcnt lgkmcnt(12)
	v_pk_fma_f32 v[22:23], v[16:17], v[114:115], v[22:23] neg_lo:[1,0,0] neg_hi:[1,0,0]
	v_pk_fma_f32 v[30:31], v[18:19], v[116:117], v[30:31] neg_lo:[1,0,0] neg_hi:[1,0,0]
	ds_read_b128 v[16:19], v33 offset:30016
	v_pk_fma_f32 v[22:23], v[26:27], v[118:119], v[22:23] neg_lo:[1,0,0] neg_hi:[1,0,0]
	v_pk_fma_f32 v[30:31], v[28:29], v[120:121], v[30:31] neg_lo:[1,0,0] neg_hi:[1,0,0]
	ds_read_b128 v[26:29], v33 offset:30032
	s_waitcnt lgkmcnt(12)
	v_pk_fma_f32 v[22:23], v[34:35], v[122:123], v[22:23] neg_lo:[1,0,0] neg_hi:[1,0,0]
	v_pk_fma_f32 v[30:31], v[36:37], v[124:125], v[30:31] neg_lo:[1,0,0] neg_hi:[1,0,0]
	ds_read_b128 v[34:37], v33 offset:30048
	v_pk_fma_f32 v[22:23], v[38:39], v[126:127], v[22:23] neg_lo:[1,0,0] neg_hi:[1,0,0]
	v_pk_fma_f32 v[30:31], v[40:41], v[128:129], v[30:31] neg_lo:[1,0,0] neg_hi:[1,0,0]
	ds_read_b128 v[38:41], v33 offset:30064
	s_waitcnt lgkmcnt(12)
	v_pk_fma_f32 v[22:23], v[42:43], v[130:131], v[22:23] neg_lo:[1,0,0] neg_hi:[1,0,0]
	v_pk_fma_f32 v[30:31], v[44:45], v[132:133], v[30:31] neg_lo:[1,0,0] neg_hi:[1,0,0]
	ds_read_b128 v[42:45], v33 offset:30080
	v_pk_fma_f32 v[22:23], v[46:47], v[134:135], v[22:23] neg_lo:[1,0,0] neg_hi:[1,0,0]
	v_pk_fma_f32 v[30:31], v[48:49], v[136:137], v[30:31] neg_lo:[1,0,0] neg_hi:[1,0,0]
	ds_read_b128 v[46:49], v33 offset:30096
	s_waitcnt lgkmcnt(12)
	v_pk_fma_f32 v[22:23], v[50:51], v[138:139], v[22:23] neg_lo:[1,0,0] neg_hi:[1,0,0]
	v_pk_fma_f32 v[30:31], v[52:53], v[140:141], v[30:31] neg_lo:[1,0,0] neg_hi:[1,0,0]
	ds_read_b128 v[50:53], v33 offset:30112
	v_pk_fma_f32 v[22:23], v[54:55], v[142:143], v[22:23] neg_lo:[1,0,0] neg_hi:[1,0,0]
	v_pk_fma_f32 v[30:31], v[56:57], v[162:163], v[30:31] neg_lo:[1,0,0] neg_hi:[1,0,0]
	ds_read_b128 v[54:57], v33 offset:30128
	v_cmp_eq_u32_e32 vcc, 49, v152
	v_pk_add_f32 v[82:83], v[22:23], v[30:31]
	v_add_f32_e32 v164, v82, v83
	v_cvt_pk_bf16_f32 v25, v164, v164
	ds_write_b16 v84, v25 offset:6912
	v_cndmask_b32_e64 v192, 0, 1.0, vcc
	s_waitcnt lgkmcnt(11)
	v_pk_fma_f32 v[22:23], v[0:1], v[98:99], v[192:193] neg_lo:[1,0,0] neg_hi:[1,0,0]
	v_pk_fma_f32 v[30:31], v[2:3], v[100:101], 0 neg_lo:[1,0,0] neg_hi:[1,0,0]
	ds_read_b128 v[0:3], v33 offset:30208
	v_pk_fma_f32 v[22:23], v[4:5], v[102:103], v[22:23] neg_lo:[1,0,0] neg_hi:[1,0,0]
	v_pk_fma_f32 v[30:31], v[6:7], v[104:105], v[30:31] neg_lo:[1,0,0] neg_hi:[1,0,0]
	ds_read_b128 v[4:7], v33 offset:30224
	s_waitcnt lgkmcnt(11)
	v_pk_fma_f32 v[22:23], v[8:9], v[106:107], v[22:23] neg_lo:[1,0,0] neg_hi:[1,0,0]
	v_pk_fma_f32 v[30:31], v[10:11], v[108:109], v[30:31] neg_lo:[1,0,0] neg_hi:[1,0,0]
	ds_read_b128 v[8:11], v33 offset:30240
	v_pk_fma_f32 v[22:23], v[12:13], v[110:111], v[22:23] neg_lo:[1,0,0] neg_hi:[1,0,0]
	v_pk_fma_f32 v[30:31], v[14:15], v[112:113], v[30:31] neg_lo:[1,0,0] neg_hi:[1,0,0]
	ds_read_b128 v[12:15], v33 offset:30256
	s_waitcnt lgkmcnt(11)
	v_pk_fma_f32 v[22:23], v[16:17], v[114:115], v[22:23] neg_lo:[1,0,0] neg_hi:[1,0,0]
	v_pk_fma_f32 v[30:31], v[18:19], v[116:117], v[30:31] neg_lo:[1,0,0] neg_hi:[1,0,0]
	ds_read_b128 v[16:19], v33 offset:30272
	v_pk_fma_f32 v[22:23], v[26:27], v[118:119], v[22:23] neg_lo:[1,0,0] neg_hi:[1,0,0]
	v_pk_fma_f32 v[30:31], v[28:29], v[120:121], v[30:31] neg_lo:[1,0,0] neg_hi:[1,0,0]
	ds_read_b128 v[26:29], v33 offset:30288
	s_waitcnt lgkmcnt(11)
	v_pk_fma_f32 v[22:23], v[34:35], v[122:123], v[22:23] neg_lo:[1,0,0] neg_hi:[1,0,0]
	v_pk_fma_f32 v[30:31], v[36:37], v[124:125], v[30:31] neg_lo:[1,0,0] neg_hi:[1,0,0]
	ds_read_b128 v[34:37], v33 offset:30304
	v_pk_fma_f32 v[22:23], v[38:39], v[126:127], v[22:23] neg_lo:[1,0,0] neg_hi:[1,0,0]
	v_pk_fma_f32 v[30:31], v[40:41], v[128:129], v[30:31] neg_lo:[1,0,0] neg_hi:[1,0,0]
	ds_read_b128 v[38:41], v33 offset:30320
	s_waitcnt lgkmcnt(11)
	v_pk_fma_f32 v[22:23], v[42:43], v[130:131], v[22:23] neg_lo:[1,0,0] neg_hi:[1,0,0]
	v_pk_fma_f32 v[30:31], v[44:45], v[132:133], v[30:31] neg_lo:[1,0,0] neg_hi:[1,0,0]
	ds_read_b128 v[42:45], v33 offset:30336
	v_pk_fma_f32 v[22:23], v[46:47], v[134:135], v[22:23] neg_lo:[1,0,0] neg_hi:[1,0,0]
	v_pk_fma_f32 v[30:31], v[48:49], v[136:137], v[30:31] neg_lo:[1,0,0] neg_hi:[1,0,0]
	ds_read_b128 v[46:49], v33 offset:30352
	s_waitcnt lgkmcnt(11)
	v_pk_fma_f32 v[22:23], v[50:51], v[138:139], v[22:23] neg_lo:[1,0,0] neg_hi:[1,0,0]
	v_pk_fma_f32 v[30:31], v[52:53], v[140:141], v[30:31] neg_lo:[1,0,0] neg_hi:[1,0,0]
	ds_read_b128 v[50:53], v33 offset:30368
	v_pk_fma_f32 v[22:23], v[54:55], v[142:143], v[22:23] neg_lo:[1,0,0] neg_hi:[1,0,0]
	v_pk_fma_f32 v[30:31], v[56:57], v[162:163], v[30:31] neg_lo:[1,0,0] neg_hi:[1,0,0]
	ds_read_b128 v[54:57], v33 offset:30384
	s_waitcnt lgkmcnt(15)
	v_pk_fma_f32 v[22:23], v[58:59], v[164:165], v[22:23] neg_lo:[1,0,0] neg_hi:[1,0,0]
	v_pk_fma_f32 v[30:31], v[60:61], v[166:167], v[30:31] neg_lo:[1,0,0] neg_hi:[1,0,0]
	ds_read_b128 v[58:61], v33 offset:30400
	v_cmp_eq_u32_e32 vcc, 50, v152
	v_pk_add_f32 v[82:83], v[22:23], v[30:31]
	v_add_f32_e32 v165, v82, v83
	v_cvt_pk_bf16_f32 v25, v165, v165
	ds_write_b16 v84, v25 offset:7056
	v_cndmask_b32_e64 v192, 0, 1.0, vcc
	s_waitcnt lgkmcnt(12)
	v_pk_fma_f32 v[22:23], v[0:1], v[98:99], v[192:193] neg_lo:[1,0,0] neg_hi:[1,0,0]
	v_pk_fma_f32 v[30:31], v[2:3], v[100:101], 0 neg_lo:[1,0,0] neg_hi:[1,0,0]
	ds_read_b128 v[0:3], v33 offset:30464
	v_pk_fma_f32 v[22:23], v[4:5], v[102:103], v[22:23] neg_lo:[1,0,0] neg_hi:[1,0,0]
	v_pk_fma_f32 v[30:31], v[6:7], v[104:105], v[30:31] neg_lo:[1,0,0] neg_hi:[1,0,0]
	ds_read_b128 v[4:7], v33 offset:30480
	s_waitcnt lgkmcnt(12)
	v_pk_fma_f32 v[22:23], v[8:9], v[106:107], v[22:23] neg_lo:[1,0,0] neg_hi:[1,0,0]
	v_pk_fma_f32 v[30:31], v[10:11], v[108:109], v[30:31] neg_lo:[1,0,0] neg_hi:[1,0,0]
	ds_read_b128 v[8:11], v33 offset:30496
	v_pk_fma_f32 v[22:23], v[12:13], v[110:111], v[22:23] neg_lo:[1,0,0] neg_hi:[1,0,0]
	v_pk_fma_f32 v[30:31], v[14:15], v[112:113], v[30:31] neg_lo:[1,0,0] neg_hi:[1,0,0]
	ds_read_b128 v[12:15], v33 offset:30512
	s_waitcnt lgkmcnt(12)
	v_pk_fma_f32 v[22:23], v[16:17], v[114:115], v[22:23] neg_lo:[1,0,0] neg_hi:[1,0,0]
	v_pk_fma_f32 v[30:31], v[18:19], v[116:117], v[30:31] neg_lo:[1,0,0] neg_hi:[1,0,0]
	ds_read_b128 v[16:19], v33 offset:30528
	v_pk_fma_f32 v[22:23], v[26:27], v[118:119], v[22:23] neg_lo:[1,0,0] neg_hi:[1,0,0]
	v_pk_fma_f32 v[30:31], v[28:29], v[120:121], v[30:31] neg_lo:[1,0,0] neg_hi:[1,0,0]
	ds_read_b128 v[26:29], v33 offset:30544
	s_waitcnt lgkmcnt(12)
	v_pk_fma_f32 v[22:23], v[34:35], v[122:123], v[22:23] neg_lo:[1,0,0] neg_hi:[1,0,0]
	v_pk_fma_f32 v[30:31], v[36:37], v[124:125], v[30:31] neg_lo:[1,0,0] neg_hi:[1,0,0]
	ds_read_b128 v[34:37], v33 offset:30560
	v_pk_fma_f32 v[22:23], v[38:39], v[126:127], v[22:23] neg_lo:[1,0,0] neg_hi:[1,0,0]
	v_pk_fma_f32 v[30:31], v[40:41], v[128:129], v[30:31] neg_lo:[1,0,0] neg_hi:[1,0,0]
	ds_read_b128 v[38:41], v33 offset:30576
	s_waitcnt lgkmcnt(12)
	v_pk_fma_f32 v[22:23], v[42:43], v[130:131], v[22:23] neg_lo:[1,0,0] neg_hi:[1,0,0]
	v_pk_fma_f32 v[30:31], v[44:45], v[132:133], v[30:31] neg_lo:[1,0,0] neg_hi:[1,0,0]
	ds_read_b128 v[42:45], v33 offset:30592
	v_pk_fma_f32 v[22:23], v[46:47], v[134:135], v[22:23] neg_lo:[1,0,0] neg_hi:[1,0,0]
	v_pk_fma_f32 v[30:31], v[48:49], v[136:137], v[30:31] neg_lo:[1,0,0] neg_hi:[1,0,0]
	ds_read_b128 v[46:49], v33 offset:30608
	s_waitcnt lgkmcnt(12)
	v_pk_fma_f32 v[22:23], v[50:51], v[138:139], v[22:23] neg_lo:[1,0,0] neg_hi:[1,0,0]
	v_pk_fma_f32 v[30:31], v[52:53], v[140:141], v[30:31] neg_lo:[1,0,0] neg_hi:[1,0,0]
	ds_read_b128 v[50:53], v33 offset:30624
	v_pk_fma_f32 v[22:23], v[54:55], v[142:143], v[22:23] neg_lo:[1,0,0] neg_hi:[1,0,0]
	v_pk_fma_f32 v[30:31], v[56:57], v[162:163], v[30:31] neg_lo:[1,0,0] neg_hi:[1,0,0]
	ds_read_b128 v[54:57], v33 offset:30640
	s_waitcnt lgkmcnt(13)
	v_pk_fma_f32 v[22:23], v[58:59], v[164:165], v[22:23] neg_lo:[1,0,0] neg_hi:[1,0,0]
	v_pk_fma_f32 v[30:31], v[60:61], v[166:167], v[30:31] neg_lo:[1,0,0] neg_hi:[1,0,0]
	ds_read_b128 v[58:61], v33 offset:30656
	v_cmp_eq_u32_e32 vcc, 51, v152
	v_pk_add_f32 v[82:83], v[22:23], v[30:31]
	v_add_f32_e32 v166, v82, v83
	v_cvt_pk_bf16_f32 v25, v166, v166
	ds_write_b16 v84, v25 offset:7200
	v_cndmask_b32_e64 v192, 0, 1.0, vcc
	s_waitcnt lgkmcnt(12)
	v_pk_fma_f32 v[22:23], v[0:1], v[98:99], v[192:193] neg_lo:[1,0,0] neg_hi:[1,0,0]
	v_pk_fma_f32 v[30:31], v[2:3], v[100:101], 0 neg_lo:[1,0,0] neg_hi:[1,0,0]
	ds_read_b128 v[0:3], v33 offset:30720
	v_pk_fma_f32 v[22:23], v[4:5], v[102:103], v[22:23] neg_lo:[1,0,0] neg_hi:[1,0,0]
	v_pk_fma_f32 v[30:31], v[6:7], v[104:105], v[30:31] neg_lo:[1,0,0] neg_hi:[1,0,0]
	ds_read_b128 v[4:7], v33 offset:30736
	s_waitcnt lgkmcnt(12)
	v_pk_fma_f32 v[22:23], v[8:9], v[106:107], v[22:23] neg_lo:[1,0,0] neg_hi:[1,0,0]
	v_pk_fma_f32 v[30:31], v[10:11], v[108:109], v[30:31] neg_lo:[1,0,0] neg_hi:[1,0,0]
	ds_read_b128 v[8:11], v33 offset:30752
	v_pk_fma_f32 v[22:23], v[12:13], v[110:111], v[22:23] neg_lo:[1,0,0] neg_hi:[1,0,0]
	v_pk_fma_f32 v[30:31], v[14:15], v[112:113], v[30:31] neg_lo:[1,0,0] neg_hi:[1,0,0]
	ds_read_b128 v[12:15], v33 offset:30768
	s_waitcnt lgkmcnt(12)
	v_pk_fma_f32 v[22:23], v[16:17], v[114:115], v[22:23] neg_lo:[1,0,0] neg_hi:[1,0,0]
	v_pk_fma_f32 v[30:31], v[18:19], v[116:117], v[30:31] neg_lo:[1,0,0] neg_hi:[1,0,0]
	ds_read_b128 v[16:19], v33 offset:30784
	v_pk_fma_f32 v[22:23], v[26:27], v[118:119], v[22:23] neg_lo:[1,0,0] neg_hi:[1,0,0]
	v_pk_fma_f32 v[30:31], v[28:29], v[120:121], v[30:31] neg_lo:[1,0,0] neg_hi:[1,0,0]
	ds_read_b128 v[26:29], v33 offset:30800
	s_waitcnt lgkmcnt(12)
	v_pk_fma_f32 v[22:23], v[34:35], v[122:123], v[22:23] neg_lo:[1,0,0] neg_hi:[1,0,0]
	v_pk_fma_f32 v[30:31], v[36:37], v[124:125], v[30:31] neg_lo:[1,0,0] neg_hi:[1,0,0]
	ds_read_b128 v[34:37], v33 offset:30816
	v_pk_fma_f32 v[22:23], v[38:39], v[126:127], v[22:23] neg_lo:[1,0,0] neg_hi:[1,0,0]
	v_pk_fma_f32 v[30:31], v[40:41], v[128:129], v[30:31] neg_lo:[1,0,0] neg_hi:[1,0,0]
	ds_read_b128 v[38:41], v33 offset:30832
	s_waitcnt lgkmcnt(12)
	v_pk_fma_f32 v[22:23], v[42:43], v[130:131], v[22:23] neg_lo:[1,0,0] neg_hi:[1,0,0]
	v_pk_fma_f32 v[30:31], v[44:45], v[132:133], v[30:31] neg_lo:[1,0,0] neg_hi:[1,0,0]
	ds_read_b128 v[42:45], v33 offset:30848
	v_pk_fma_f32 v[22:23], v[46:47], v[134:135], v[22:23] neg_lo:[1,0,0] neg_hi:[1,0,0]
	v_pk_fma_f32 v[30:31], v[48:49], v[136:137], v[30:31] neg_lo:[1,0,0] neg_hi:[1,0,0]
	ds_read_b128 v[46:49], v33 offset:30864
	s_waitcnt lgkmcnt(12)
	v_pk_fma_f32 v[22:23], v[50:51], v[138:139], v[22:23] neg_lo:[1,0,0] neg_hi:[1,0,0]
	v_pk_fma_f32 v[30:31], v[52:53], v[140:141], v[30:31] neg_lo:[1,0,0] neg_hi:[1,0,0]
	ds_read_b128 v[50:53], v33 offset:30880
	v_pk_fma_f32 v[22:23], v[54:55], v[142:143], v[22:23] neg_lo:[1,0,0] neg_hi:[1,0,0]
	v_pk_fma_f32 v[30:31], v[56:57], v[162:163], v[30:31] neg_lo:[1,0,0] neg_hi:[1,0,0]
	ds_read_b128 v[54:57], v33 offset:30896
	s_waitcnt lgkmcnt(13)
	v_pk_fma_f32 v[22:23], v[58:59], v[164:165], v[22:23] neg_lo:[1,0,0] neg_hi:[1,0,0]
	v_pk_fma_f32 v[30:31], v[60:61], v[166:167], v[30:31] neg_lo:[1,0,0] neg_hi:[1,0,0]
	ds_read_b128 v[58:61], v33 offset:30912
	v_cmp_eq_u32_e32 vcc, 52, v152
	v_pk_add_f32 v[82:83], v[22:23], v[30:31]
	v_add_f32_e32 v167, v82, v83
	v_cvt_pk_bf16_f32 v25, v167, v167
	ds_write_b16 v84, v25 offset:7344
	v_cndmask_b32_e64 v192, 0, 1.0, vcc
	ds_read_b128 v[62:65], v33 offset:31184
	s_waitcnt lgkmcnt(13)
	v_pk_fma_f32 v[22:23], v[0:1], v[98:99], v[192:193] neg_lo:[1,0,0] neg_hi:[1,0,0]
	v_pk_fma_f32 v[30:31], v[2:3], v[100:101], 0 neg_lo:[1,0,0] neg_hi:[1,0,0]
	ds_read_b128 v[0:3], v33 offset:30976
	v_pk_fma_f32 v[22:23], v[4:5], v[102:103], v[22:23] neg_lo:[1,0,0] neg_hi:[1,0,0]
	v_pk_fma_f32 v[30:31], v[6:7], v[104:105], v[30:31] neg_lo:[1,0,0] neg_hi:[1,0,0]
	ds_read_b128 v[4:7], v33 offset:30992
	s_waitcnt lgkmcnt(13)
	v_pk_fma_f32 v[22:23], v[8:9], v[106:107], v[22:23] neg_lo:[1,0,0] neg_hi:[1,0,0]
	v_pk_fma_f32 v[30:31], v[10:11], v[108:109], v[30:31] neg_lo:[1,0,0] neg_hi:[1,0,0]
	ds_read_b128 v[8:11], v33 offset:31008
	v_pk_fma_f32 v[22:23], v[12:13], v[110:111], v[22:23] neg_lo:[1,0,0] neg_hi:[1,0,0]
	v_pk_fma_f32 v[30:31], v[14:15], v[112:113], v[30:31] neg_lo:[1,0,0] neg_hi:[1,0,0]
	ds_read_b128 v[12:15], v33 offset:31024
	s_waitcnt lgkmcnt(13)
	v_pk_fma_f32 v[22:23], v[16:17], v[114:115], v[22:23] neg_lo:[1,0,0] neg_hi:[1,0,0]
	v_pk_fma_f32 v[30:31], v[18:19], v[116:117], v[30:31] neg_lo:[1,0,0] neg_hi:[1,0,0]
	ds_read_b128 v[16:19], v33 offset:31040
	v_pk_fma_f32 v[22:23], v[26:27], v[118:119], v[22:23] neg_lo:[1,0,0] neg_hi:[1,0,0]
	v_pk_fma_f32 v[30:31], v[28:29], v[120:121], v[30:31] neg_lo:[1,0,0] neg_hi:[1,0,0]
	ds_read_b128 v[26:29], v33 offset:31056
	s_waitcnt lgkmcnt(13)
	v_pk_fma_f32 v[22:23], v[34:35], v[122:123], v[22:23] neg_lo:[1,0,0] neg_hi:[1,0,0]
	v_pk_fma_f32 v[30:31], v[36:37], v[124:125], v[30:31] neg_lo:[1,0,0] neg_hi:[1,0,0]
	ds_read_b128 v[34:37], v33 offset:31072
	v_pk_fma_f32 v[22:23], v[38:39], v[126:127], v[22:23] neg_lo:[1,0,0] neg_hi:[1,0,0]
	v_pk_fma_f32 v[30:31], v[40:41], v[128:129], v[30:31] neg_lo:[1,0,0] neg_hi:[1,0,0]
	ds_read_b128 v[38:41], v33 offset:31088
	s_waitcnt lgkmcnt(13)
	v_pk_fma_f32 v[22:23], v[42:43], v[130:131], v[22:23] neg_lo:[1,0,0] neg_hi:[1,0,0]
	v_pk_fma_f32 v[30:31], v[44:45], v[132:133], v[30:31] neg_lo:[1,0,0] neg_hi:[1,0,0]
	ds_read_b128 v[42:45], v33 offset:31104
	v_pk_fma_f32 v[22:23], v[46:47], v[134:135], v[22:23] neg_lo:[1,0,0] neg_hi:[1,0,0]
	v_pk_fma_f32 v[30:31], v[48:49], v[136:137], v[30:31] neg_lo:[1,0,0] neg_hi:[1,0,0]
	ds_read_b128 v[46:49], v33 offset:31120
	s_waitcnt lgkmcnt(13)
	v_pk_fma_f32 v[22:23], v[50:51], v[138:139], v[22:23] neg_lo:[1,0,0] neg_hi:[1,0,0]
	v_pk_fma_f32 v[30:31], v[52:53], v[140:141], v[30:31] neg_lo:[1,0,0] neg_hi:[1,0,0]
	ds_read_b128 v[50:53], v33 offset:31136
	v_pk_fma_f32 v[22:23], v[54:55], v[142:143], v[22:23] neg_lo:[1,0,0] neg_hi:[1,0,0]
	v_pk_fma_f32 v[30:31], v[56:57], v[162:163], v[30:31] neg_lo:[1,0,0] neg_hi:[1,0,0]
	ds_read_b128 v[54:57], v33 offset:31152
	s_waitcnt lgkmcnt(14)
	v_pk_fma_f32 v[22:23], v[58:59], v[164:165], v[22:23] neg_lo:[1,0,0] neg_hi:[1,0,0]
	v_pk_fma_f32 v[30:31], v[60:61], v[166:167], v[30:31] neg_lo:[1,0,0] neg_hi:[1,0,0]
	ds_read_b128 v[58:61], v33 offset:31168
	v_cmp_eq_u32_e32 vcc, 53, v152
	v_pk_add_f32 v[82:83], v[22:23], v[30:31]
	v_add_f32_e32 v168, v82, v83
	v_cvt_pk_bf16_f32 v25, v168, v168
	ds_write_b16 v84, v25 offset:7488
	v_cndmask_b32_e64 v192, 0, 1.0, vcc
	s_waitcnt lgkmcnt(12)
	v_pk_fma_f32 v[22:23], v[0:1], v[98:99], v[192:193] neg_lo:[1,0,0] neg_hi:[1,0,0]
	v_pk_fma_f32 v[30:31], v[2:3], v[100:101], 0 neg_lo:[1,0,0] neg_hi:[1,0,0]
	ds_read_b128 v[0:3], v33 offset:31232
	v_pk_fma_f32 v[22:23], v[4:5], v[102:103], v[22:23] neg_lo:[1,0,0] neg_hi:[1,0,0]
	v_pk_fma_f32 v[30:31], v[6:7], v[104:105], v[30:31] neg_lo:[1,0,0] neg_hi:[1,0,0]
	ds_read_b128 v[4:7], v33 offset:31248
	s_waitcnt lgkmcnt(12)
	v_pk_fma_f32 v[22:23], v[8:9], v[106:107], v[22:23] neg_lo:[1,0,0] neg_hi:[1,0,0]
	v_pk_fma_f32 v[30:31], v[10:11], v[108:109], v[30:31] neg_lo:[1,0,0] neg_hi:[1,0,0]
	ds_read_b128 v[8:11], v33 offset:31264
	v_pk_fma_f32 v[22:23], v[12:13], v[110:111], v[22:23] neg_lo:[1,0,0] neg_hi:[1,0,0]
	v_pk_fma_f32 v[30:31], v[14:15], v[112:113], v[30:31] neg_lo:[1,0,0] neg_hi:[1,0,0]
	ds_read_b128 v[12:15], v33 offset:31280
	s_waitcnt lgkmcnt(12)
	v_pk_fma_f32 v[22:23], v[16:17], v[114:115], v[22:23] neg_lo:[1,0,0] neg_hi:[1,0,0]
	v_pk_fma_f32 v[30:31], v[18:19], v[116:117], v[30:31] neg_lo:[1,0,0] neg_hi:[1,0,0]
	ds_read_b128 v[16:19], v33 offset:31296
	v_pk_fma_f32 v[22:23], v[26:27], v[118:119], v[22:23] neg_lo:[1,0,0] neg_hi:[1,0,0]
	v_pk_fma_f32 v[30:31], v[28:29], v[120:121], v[30:31] neg_lo:[1,0,0] neg_hi:[1,0,0]
	ds_read_b128 v[26:29], v33 offset:31312
	s_waitcnt lgkmcnt(12)
	v_pk_fma_f32 v[22:23], v[34:35], v[122:123], v[22:23] neg_lo:[1,0,0] neg_hi:[1,0,0]
	v_pk_fma_f32 v[30:31], v[36:37], v[124:125], v[30:31] neg_lo:[1,0,0] neg_hi:[1,0,0]
	ds_read_b128 v[34:37], v33 offset:31328
	v_pk_fma_f32 v[22:23], v[38:39], v[126:127], v[22:23] neg_lo:[1,0,0] neg_hi:[1,0,0]
	v_pk_fma_f32 v[30:31], v[40:41], v[128:129], v[30:31] neg_lo:[1,0,0] neg_hi:[1,0,0]
	ds_read_b128 v[38:41], v33 offset:31344
	s_waitcnt lgkmcnt(12)
	v_pk_fma_f32 v[22:23], v[42:43], v[130:131], v[22:23] neg_lo:[1,0,0] neg_hi:[1,0,0]
	v_pk_fma_f32 v[30:31], v[44:45], v[132:133], v[30:31] neg_lo:[1,0,0] neg_hi:[1,0,0]
	ds_read_b128 v[42:45], v33 offset:31360
	v_pk_fma_f32 v[22:23], v[46:47], v[134:135], v[22:23] neg_lo:[1,0,0] neg_hi:[1,0,0]
	v_pk_fma_f32 v[30:31], v[48:49], v[136:137], v[30:31] neg_lo:[1,0,0] neg_hi:[1,0,0]
	ds_read_b128 v[46:49], v33 offset:31376
	s_waitcnt lgkmcnt(12)
	v_pk_fma_f32 v[22:23], v[50:51], v[138:139], v[22:23] neg_lo:[1,0,0] neg_hi:[1,0,0]
	v_pk_fma_f32 v[30:31], v[52:53], v[140:141], v[30:31] neg_lo:[1,0,0] neg_hi:[1,0,0]
	ds_read_b128 v[50:53], v33 offset:31392
	v_pk_fma_f32 v[22:23], v[54:55], v[142:143], v[22:23] neg_lo:[1,0,0] neg_hi:[1,0,0]
	v_pk_fma_f32 v[30:31], v[56:57], v[162:163], v[30:31] neg_lo:[1,0,0] neg_hi:[1,0,0]
	ds_read_b128 v[54:57], v33 offset:31408
	s_waitcnt lgkmcnt(15)
	v_pk_fma_f32 v[22:23], v[58:59], v[164:165], v[22:23] neg_lo:[1,0,0] neg_hi:[1,0,0]
	v_pk_fma_f32 v[30:31], v[60:61], v[166:167], v[30:31] neg_lo:[1,0,0] neg_hi:[1,0,0]
	ds_read_b128 v[58:61], v33 offset:31424
	v_pk_fma_f32 v[22:23], v[62:63], v[168:169], v[22:23] neg_lo:[1,0,0] neg_hi:[1,0,0]
	v_pk_fma_f32 v[30:31], v[64:65], v[170:171], v[30:31] neg_lo:[1,0,0] neg_hi:[1,0,0]
	ds_read_b128 v[62:65], v33 offset:31440
	v_cmp_eq_u32_e32 vcc, 54, v152
	v_pk_add_f32 v[82:83], v[22:23], v[30:31]
	v_add_f32_e32 v169, v82, v83
	v_cvt_pk_bf16_f32 v25, v169, v169
	ds_write_b16 v84, v25 offset:7632
	v_cndmask_b32_e64 v192, 0, 1.0, vcc
	s_waitcnt lgkmcnt(13)
	v_pk_fma_f32 v[22:23], v[0:1], v[98:99], v[192:193] neg_lo:[1,0,0] neg_hi:[1,0,0]
	v_pk_fma_f32 v[30:31], v[2:3], v[100:101], 0 neg_lo:[1,0,0] neg_hi:[1,0,0]
	ds_read_b128 v[0:3], v33 offset:31488
	v_pk_fma_f32 v[22:23], v[4:5], v[102:103], v[22:23] neg_lo:[1,0,0] neg_hi:[1,0,0]
	v_pk_fma_f32 v[30:31], v[6:7], v[104:105], v[30:31] neg_lo:[1,0,0] neg_hi:[1,0,0]
	ds_read_b128 v[4:7], v33 offset:31504
	s_waitcnt lgkmcnt(13)
	v_pk_fma_f32 v[22:23], v[8:9], v[106:107], v[22:23] neg_lo:[1,0,0] neg_hi:[1,0,0]
	v_pk_fma_f32 v[30:31], v[10:11], v[108:109], v[30:31] neg_lo:[1,0,0] neg_hi:[1,0,0]
	ds_read_b128 v[8:11], v33 offset:31520
	v_pk_fma_f32 v[22:23], v[12:13], v[110:111], v[22:23] neg_lo:[1,0,0] neg_hi:[1,0,0]
	v_pk_fma_f32 v[30:31], v[14:15], v[112:113], v[30:31] neg_lo:[1,0,0] neg_hi:[1,0,0]
	ds_read_b128 v[12:15], v33 offset:31536
	s_waitcnt lgkmcnt(13)
	v_pk_fma_f32 v[22:23], v[16:17], v[114:115], v[22:23] neg_lo:[1,0,0] neg_hi:[1,0,0]
	v_pk_fma_f32 v[30:31], v[18:19], v[116:117], v[30:31] neg_lo:[1,0,0] neg_hi:[1,0,0]
	ds_read_b128 v[16:19], v33 offset:31552
	v_pk_fma_f32 v[22:23], v[26:27], v[118:119], v[22:23] neg_lo:[1,0,0] neg_hi:[1,0,0]
	v_pk_fma_f32 v[30:31], v[28:29], v[120:121], v[30:31] neg_lo:[1,0,0] neg_hi:[1,0,0]
	ds_read_b128 v[26:29], v33 offset:31568
	s_waitcnt lgkmcnt(13)
	v_pk_fma_f32 v[22:23], v[34:35], v[122:123], v[22:23] neg_lo:[1,0,0] neg_hi:[1,0,0]
	v_pk_fma_f32 v[30:31], v[36:37], v[124:125], v[30:31] neg_lo:[1,0,0] neg_hi:[1,0,0]
	ds_read_b128 v[34:37], v33 offset:31584
	v_pk_fma_f32 v[22:23], v[38:39], v[126:127], v[22:23] neg_lo:[1,0,0] neg_hi:[1,0,0]
	v_pk_fma_f32 v[30:31], v[40:41], v[128:129], v[30:31] neg_lo:[1,0,0] neg_hi:[1,0,0]
	ds_read_b128 v[38:41], v33 offset:31600
	s_waitcnt lgkmcnt(13)
	v_pk_fma_f32 v[22:23], v[42:43], v[130:131], v[22:23] neg_lo:[1,0,0] neg_hi:[1,0,0]
	v_pk_fma_f32 v[30:31], v[44:45], v[132:133], v[30:31] neg_lo:[1,0,0] neg_hi:[1,0,0]
	ds_read_b128 v[42:45], v33 offset:31616
	v_pk_fma_f32 v[22:23], v[46:47], v[134:135], v[22:23] neg_lo:[1,0,0] neg_hi:[1,0,0]
	v_pk_fma_f32 v[30:31], v[48:49], v[136:137], v[30:31] neg_lo:[1,0,0] neg_hi:[1,0,0]
	ds_read_b128 v[46:49], v33 offset:31632
	s_waitcnt lgkmcnt(13)
	v_pk_fma_f32 v[22:23], v[50:51], v[138:139], v[22:23] neg_lo:[1,0,0] neg_hi:[1,0,0]
	v_pk_fma_f32 v[30:31], v[52:53], v[140:141], v[30:31] neg_lo:[1,0,0] neg_hi:[1,0,0]
	ds_read_b128 v[50:53], v33 offset:31648
	v_pk_fma_f32 v[22:23], v[54:55], v[142:143], v[22:23] neg_lo:[1,0,0] neg_hi:[1,0,0]
	v_pk_fma_f32 v[30:31], v[56:57], v[162:163], v[30:31] neg_lo:[1,0,0] neg_hi:[1,0,0]
	ds_read_b128 v[54:57], v33 offset:31664
	s_waitcnt lgkmcnt(13)
	v_pk_fma_f32 v[22:23], v[58:59], v[164:165], v[22:23] neg_lo:[1,0,0] neg_hi:[1,0,0]
	v_pk_fma_f32 v[30:31], v[60:61], v[166:167], v[30:31] neg_lo:[1,0,0] neg_hi:[1,0,0]
	ds_read_b128 v[58:61], v33 offset:31680
	v_pk_fma_f32 v[22:23], v[62:63], v[168:169], v[22:23] neg_lo:[1,0,0] neg_hi:[1,0,0]
	v_pk_fma_f32 v[30:31], v[64:65], v[170:171], v[30:31] neg_lo:[1,0,0] neg_hi:[1,0,0]
	ds_read_b128 v[62:65], v33 offset:31696
	v_cmp_eq_u32_e32 vcc, 55, v152
	v_pk_add_f32 v[82:83], v[22:23], v[30:31]
	v_add_f32_e32 v170, v82, v83
	v_cvt_pk_bf16_f32 v25, v170, v170
	ds_write_b16 v84, v25 offset:7776
	v_cndmask_b32_e64 v192, 0, 1.0, vcc
	s_waitcnt lgkmcnt(13)
	v_pk_fma_f32 v[22:23], v[0:1], v[98:99], v[192:193] neg_lo:[1,0,0] neg_hi:[1,0,0]
	v_pk_fma_f32 v[30:31], v[2:3], v[100:101], 0 neg_lo:[1,0,0] neg_hi:[1,0,0]
	ds_read_b128 v[0:3], v33 offset:31744
	v_pk_fma_f32 v[22:23], v[4:5], v[102:103], v[22:23] neg_lo:[1,0,0] neg_hi:[1,0,0]
	v_pk_fma_f32 v[30:31], v[6:7], v[104:105], v[30:31] neg_lo:[1,0,0] neg_hi:[1,0,0]
	ds_read_b128 v[4:7], v33 offset:31760
	s_waitcnt lgkmcnt(13)
	v_pk_fma_f32 v[22:23], v[8:9], v[106:107], v[22:23] neg_lo:[1,0,0] neg_hi:[1,0,0]
	v_pk_fma_f32 v[30:31], v[10:11], v[108:109], v[30:31] neg_lo:[1,0,0] neg_hi:[1,0,0]
	ds_read_b128 v[8:11], v33 offset:31776
	v_pk_fma_f32 v[22:23], v[12:13], v[110:111], v[22:23] neg_lo:[1,0,0] neg_hi:[1,0,0]
	v_pk_fma_f32 v[30:31], v[14:15], v[112:113], v[30:31] neg_lo:[1,0,0] neg_hi:[1,0,0]
	ds_read_b128 v[12:15], v33 offset:31792
	s_waitcnt lgkmcnt(13)
	v_pk_fma_f32 v[22:23], v[16:17], v[114:115], v[22:23] neg_lo:[1,0,0] neg_hi:[1,0,0]
	v_pk_fma_f32 v[30:31], v[18:19], v[116:117], v[30:31] neg_lo:[1,0,0] neg_hi:[1,0,0]
	ds_read_b128 v[16:19], v33 offset:31808
	v_pk_fma_f32 v[22:23], v[26:27], v[118:119], v[22:23] neg_lo:[1,0,0] neg_hi:[1,0,0]
	v_pk_fma_f32 v[30:31], v[28:29], v[120:121], v[30:31] neg_lo:[1,0,0] neg_hi:[1,0,0]
	ds_read_b128 v[26:29], v33 offset:31824
	s_waitcnt lgkmcnt(13)
	v_pk_fma_f32 v[22:23], v[34:35], v[122:123], v[22:23] neg_lo:[1,0,0] neg_hi:[1,0,0]
	v_pk_fma_f32 v[30:31], v[36:37], v[124:125], v[30:31] neg_lo:[1,0,0] neg_hi:[1,0,0]
	ds_read_b128 v[34:37], v33 offset:31840
	v_pk_fma_f32 v[22:23], v[38:39], v[126:127], v[22:23] neg_lo:[1,0,0] neg_hi:[1,0,0]
	v_pk_fma_f32 v[30:31], v[40:41], v[128:129], v[30:31] neg_lo:[1,0,0] neg_hi:[1,0,0]
	ds_read_b128 v[38:41], v33 offset:31856
	s_waitcnt lgkmcnt(13)
	v_pk_fma_f32 v[22:23], v[42:43], v[130:131], v[22:23] neg_lo:[1,0,0] neg_hi:[1,0,0]
	v_pk_fma_f32 v[30:31], v[44:45], v[132:133], v[30:31] neg_lo:[1,0,0] neg_hi:[1,0,0]
	ds_read_b128 v[42:45], v33 offset:31872
	v_pk_fma_f32 v[22:23], v[46:47], v[134:135], v[22:23] neg_lo:[1,0,0] neg_hi:[1,0,0]
	v_pk_fma_f32 v[30:31], v[48:49], v[136:137], v[30:31] neg_lo:[1,0,0] neg_hi:[1,0,0]
	ds_read_b128 v[46:49], v33 offset:31888
	s_waitcnt lgkmcnt(13)
	v_pk_fma_f32 v[22:23], v[50:51], v[138:139], v[22:23] neg_lo:[1,0,0] neg_hi:[1,0,0]
	v_pk_fma_f32 v[30:31], v[52:53], v[140:141], v[30:31] neg_lo:[1,0,0] neg_hi:[1,0,0]
	ds_read_b128 v[50:53], v33 offset:31904
	v_pk_fma_f32 v[22:23], v[54:55], v[142:143], v[22:23] neg_lo:[1,0,0] neg_hi:[1,0,0]
	v_pk_fma_f32 v[30:31], v[56:57], v[162:163], v[30:31] neg_lo:[1,0,0] neg_hi:[1,0,0]
	ds_read_b128 v[54:57], v33 offset:31920
	s_waitcnt lgkmcnt(13)
	v_pk_fma_f32 v[22:23], v[58:59], v[164:165], v[22:23] neg_lo:[1,0,0] neg_hi:[1,0,0]
	v_pk_fma_f32 v[30:31], v[60:61], v[166:167], v[30:31] neg_lo:[1,0,0] neg_hi:[1,0,0]
	ds_read_b128 v[58:61], v33 offset:31936
	v_pk_fma_f32 v[22:23], v[62:63], v[168:169], v[22:23] neg_lo:[1,0,0] neg_hi:[1,0,0]
	v_pk_fma_f32 v[30:31], v[64:65], v[170:171], v[30:31] neg_lo:[1,0,0] neg_hi:[1,0,0]
	ds_read_b128 v[62:65], v33 offset:31952
	v_cmp_eq_u32_e32 vcc, 56, v152
	v_pk_add_f32 v[82:83], v[22:23], v[30:31]
	v_add_f32_e32 v171, v82, v83
	v_cvt_pk_bf16_f32 v25, v171, v171
	ds_write_b16 v84, v25 offset:7920
	v_cndmask_b32_e64 v192, 0, 1.0, vcc
	ds_read_b128 v[66:69], v33 offset:32224
	s_waitcnt lgkmcnt(14)
	v_pk_fma_f32 v[22:23], v[0:1], v[98:99], v[192:193] neg_lo:[1,0,0] neg_hi:[1,0,0]
	v_pk_fma_f32 v[30:31], v[2:3], v[100:101], 0 neg_lo:[1,0,0] neg_hi:[1,0,0]
	ds_read_b128 v[0:3], v33 offset:32000
	v_pk_fma_f32 v[22:23], v[4:5], v[102:103], v[22:23] neg_lo:[1,0,0] neg_hi:[1,0,0]
	v_pk_fma_f32 v[30:31], v[6:7], v[104:105], v[30:31] neg_lo:[1,0,0] neg_hi:[1,0,0]
	ds_read_b128 v[4:7], v33 offset:32016
	s_waitcnt lgkmcnt(14)
	v_pk_fma_f32 v[22:23], v[8:9], v[106:107], v[22:23] neg_lo:[1,0,0] neg_hi:[1,0,0]
	v_pk_fma_f32 v[30:31], v[10:11], v[108:109], v[30:31] neg_lo:[1,0,0] neg_hi:[1,0,0]
	ds_read_b128 v[8:11], v33 offset:32032
	v_pk_fma_f32 v[22:23], v[12:13], v[110:111], v[22:23] neg_lo:[1,0,0] neg_hi:[1,0,0]
	v_pk_fma_f32 v[30:31], v[14:15], v[112:113], v[30:31] neg_lo:[1,0,0] neg_hi:[1,0,0]
	ds_read_b128 v[12:15], v33 offset:32048
	s_waitcnt lgkmcnt(14)
	v_pk_fma_f32 v[22:23], v[16:17], v[114:115], v[22:23] neg_lo:[1,0,0] neg_hi:[1,0,0]
	v_pk_fma_f32 v[30:31], v[18:19], v[116:117], v[30:31] neg_lo:[1,0,0] neg_hi:[1,0,0]
	ds_read_b128 v[16:19], v33 offset:32064
	v_pk_fma_f32 v[22:23], v[26:27], v[118:119], v[22:23] neg_lo:[1,0,0] neg_hi:[1,0,0]
	v_pk_fma_f32 v[30:31], v[28:29], v[120:121], v[30:31] neg_lo:[1,0,0] neg_hi:[1,0,0]
	ds_read_b128 v[26:29], v33 offset:32080
	s_waitcnt lgkmcnt(14)
	v_pk_fma_f32 v[22:23], v[34:35], v[122:123], v[22:23] neg_lo:[1,0,0] neg_hi:[1,0,0]
	v_pk_fma_f32 v[30:31], v[36:37], v[124:125], v[30:31] neg_lo:[1,0,0] neg_hi:[1,0,0]
	ds_read_b128 v[34:37], v33 offset:32096
	v_pk_fma_f32 v[22:23], v[38:39], v[126:127], v[22:23] neg_lo:[1,0,0] neg_hi:[1,0,0]
	v_pk_fma_f32 v[30:31], v[40:41], v[128:129], v[30:31] neg_lo:[1,0,0] neg_hi:[1,0,0]
	ds_read_b128 v[38:41], v33 offset:32112
	s_waitcnt lgkmcnt(14)
	v_pk_fma_f32 v[22:23], v[42:43], v[130:131], v[22:23] neg_lo:[1,0,0] neg_hi:[1,0,0]
	v_pk_fma_f32 v[30:31], v[44:45], v[132:133], v[30:31] neg_lo:[1,0,0] neg_hi:[1,0,0]
	ds_read_b128 v[42:45], v33 offset:32128
	v_pk_fma_f32 v[22:23], v[46:47], v[134:135], v[22:23] neg_lo:[1,0,0] neg_hi:[1,0,0]
	v_pk_fma_f32 v[30:31], v[48:49], v[136:137], v[30:31] neg_lo:[1,0,0] neg_hi:[1,0,0]
	ds_read_b128 v[46:49], v33 offset:32144
	s_waitcnt lgkmcnt(14)
	v_pk_fma_f32 v[22:23], v[50:51], v[138:139], v[22:23] neg_lo:[1,0,0] neg_hi:[1,0,0]
	v_pk_fma_f32 v[30:31], v[52:53], v[140:141], v[30:31] neg_lo:[1,0,0] neg_hi:[1,0,0]
	ds_read_b128 v[50:53], v33 offset:32160
	v_pk_fma_f32 v[22:23], v[54:55], v[142:143], v[22:23] neg_lo:[1,0,0] neg_hi:[1,0,0]
	v_pk_fma_f32 v[30:31], v[56:57], v[162:163], v[30:31] neg_lo:[1,0,0] neg_hi:[1,0,0]
	ds_read_b128 v[54:57], v33 offset:32176
	s_waitcnt lgkmcnt(14)
	v_pk_fma_f32 v[22:23], v[58:59], v[164:165], v[22:23] neg_lo:[1,0,0] neg_hi:[1,0,0]
	v_pk_fma_f32 v[30:31], v[60:61], v[166:167], v[30:31] neg_lo:[1,0,0] neg_hi:[1,0,0]
	ds_read_b128 v[58:61], v33 offset:32192
	v_pk_fma_f32 v[22:23], v[62:63], v[168:169], v[22:23] neg_lo:[1,0,0] neg_hi:[1,0,0]
	v_pk_fma_f32 v[30:31], v[64:65], v[170:171], v[30:31] neg_lo:[1,0,0] neg_hi:[1,0,0]
	ds_read_b128 v[62:65], v33 offset:32208
	v_cmp_eq_u32_e32 vcc, 57, v152
	v_pk_add_f32 v[82:83], v[22:23], v[30:31]
	v_add_f32_e32 v172, v82, v83
	v_cvt_pk_bf16_f32 v25, v172, v172
	ds_write_b16 v84, v25 offset:8064
	v_cndmask_b32_e64 v192, 0, 1.0, vcc
	s_waitcnt lgkmcnt(13)
	v_pk_fma_f32 v[22:23], v[0:1], v[98:99], v[192:193] neg_lo:[1,0,0] neg_hi:[1,0,0]
	v_pk_fma_f32 v[30:31], v[2:3], v[100:101], 0 neg_lo:[1,0,0] neg_hi:[1,0,0]
	ds_read_b128 v[0:3], v33 offset:32256
	v_pk_fma_f32 v[22:23], v[4:5], v[102:103], v[22:23] neg_lo:[1,0,0] neg_hi:[1,0,0]
	v_pk_fma_f32 v[30:31], v[6:7], v[104:105], v[30:31] neg_lo:[1,0,0] neg_hi:[1,0,0]
	ds_read_b128 v[4:7], v33 offset:32272
	s_waitcnt lgkmcnt(13)
	v_pk_fma_f32 v[22:23], v[8:9], v[106:107], v[22:23] neg_lo:[1,0,0] neg_hi:[1,0,0]
	v_pk_fma_f32 v[30:31], v[10:11], v[108:109], v[30:31] neg_lo:[1,0,0] neg_hi:[1,0,0]
	ds_read_b128 v[8:11], v33 offset:32288
	v_pk_fma_f32 v[22:23], v[12:13], v[110:111], v[22:23] neg_lo:[1,0,0] neg_hi:[1,0,0]
	v_pk_fma_f32 v[30:31], v[14:15], v[112:113], v[30:31] neg_lo:[1,0,0] neg_hi:[1,0,0]
	ds_read_b128 v[12:15], v33 offset:32304
	s_waitcnt lgkmcnt(13)
	v_pk_fma_f32 v[22:23], v[16:17], v[114:115], v[22:23] neg_lo:[1,0,0] neg_hi:[1,0,0]
	v_pk_fma_f32 v[30:31], v[18:19], v[116:117], v[30:31] neg_lo:[1,0,0] neg_hi:[1,0,0]
	ds_read_b128 v[16:19], v33 offset:32320
	v_pk_fma_f32 v[22:23], v[26:27], v[118:119], v[22:23] neg_lo:[1,0,0] neg_hi:[1,0,0]
	v_pk_fma_f32 v[30:31], v[28:29], v[120:121], v[30:31] neg_lo:[1,0,0] neg_hi:[1,0,0]
	ds_read_b128 v[26:29], v33 offset:32336
	s_waitcnt lgkmcnt(13)
	v_pk_fma_f32 v[22:23], v[34:35], v[122:123], v[22:23] neg_lo:[1,0,0] neg_hi:[1,0,0]
	v_pk_fma_f32 v[30:31], v[36:37], v[124:125], v[30:31] neg_lo:[1,0,0] neg_hi:[1,0,0]
	ds_read_b128 v[34:37], v33 offset:32352
	v_pk_fma_f32 v[22:23], v[38:39], v[126:127], v[22:23] neg_lo:[1,0,0] neg_hi:[1,0,0]
	v_pk_fma_f32 v[30:31], v[40:41], v[128:129], v[30:31] neg_lo:[1,0,0] neg_hi:[1,0,0]
	ds_read_b128 v[38:41], v33 offset:32368
	s_waitcnt lgkmcnt(13)
	v_pk_fma_f32 v[22:23], v[42:43], v[130:131], v[22:23] neg_lo:[1,0,0] neg_hi:[1,0,0]
	v_pk_fma_f32 v[30:31], v[44:45], v[132:133], v[30:31] neg_lo:[1,0,0] neg_hi:[1,0,0]
	ds_read_b128 v[42:45], v33 offset:32384
	v_pk_fma_f32 v[22:23], v[46:47], v[134:135], v[22:23] neg_lo:[1,0,0] neg_hi:[1,0,0]
	v_pk_fma_f32 v[30:31], v[48:49], v[136:137], v[30:31] neg_lo:[1,0,0] neg_hi:[1,0,0]
	ds_read_b128 v[46:49], v33 offset:32400
	s_waitcnt lgkmcnt(13)
	v_pk_fma_f32 v[22:23], v[50:51], v[138:139], v[22:23] neg_lo:[1,0,0] neg_hi:[1,0,0]
	v_pk_fma_f32 v[30:31], v[52:53], v[140:141], v[30:31] neg_lo:[1,0,0] neg_hi:[1,0,0]
	ds_read_b128 v[50:53], v33 offset:32416
	v_pk_fma_f32 v[22:23], v[54:55], v[142:143], v[22:23] neg_lo:[1,0,0] neg_hi:[1,0,0]
	v_pk_fma_f32 v[30:31], v[56:57], v[162:163], v[30:31] neg_lo:[1,0,0] neg_hi:[1,0,0]
	ds_read_b128 v[54:57], v33 offset:32432
	s_waitcnt lgkmcnt(13)
	v_pk_fma_f32 v[22:23], v[58:59], v[164:165], v[22:23] neg_lo:[1,0,0] neg_hi:[1,0,0]
	v_pk_fma_f32 v[30:31], v[60:61], v[166:167], v[30:31] neg_lo:[1,0,0] neg_hi:[1,0,0]
	ds_read_b128 v[58:61], v33 offset:32448
	v_pk_fma_f32 v[22:23], v[62:63], v[168:169], v[22:23] neg_lo:[1,0,0] neg_hi:[1,0,0]
	v_pk_fma_f32 v[30:31], v[64:65], v[170:171], v[30:31] neg_lo:[1,0,0] neg_hi:[1,0,0]
	ds_read_b128 v[62:65], v33 offset:32464
	s_waitcnt lgkmcnt(15)
	v_pk_fma_f32 v[22:23], v[66:67], v[172:173], v[22:23] neg_lo:[1,0,0] neg_hi:[1,0,0]
	v_pk_fma_f32 v[30:31], v[68:69], v[174:175], v[30:31] neg_lo:[1,0,0] neg_hi:[1,0,0]
	ds_read_b128 v[66:69], v33 offset:32480
	v_cmp_eq_u32_e32 vcc, 58, v152
	v_pk_add_f32 v[82:83], v[22:23], v[30:31]
	v_add_f32_e32 v173, v82, v83
	v_cvt_pk_bf16_f32 v25, v173, v173
	ds_write_b16 v84, v25 offset:8208
	v_cndmask_b32_e64 v192, 0, 1.0, vcc
	s_waitcnt lgkmcnt(14)
	v_pk_fma_f32 v[22:23], v[0:1], v[98:99], v[192:193] neg_lo:[1,0,0] neg_hi:[1,0,0]
	v_pk_fma_f32 v[30:31], v[2:3], v[100:101], 0 neg_lo:[1,0,0] neg_hi:[1,0,0]
	ds_read_b128 v[0:3], v33 offset:32512
	v_pk_fma_f32 v[22:23], v[4:5], v[102:103], v[22:23] neg_lo:[1,0,0] neg_hi:[1,0,0]
	v_pk_fma_f32 v[30:31], v[6:7], v[104:105], v[30:31] neg_lo:[1,0,0] neg_hi:[1,0,0]
	ds_read_b128 v[4:7], v33 offset:32528
	s_waitcnt lgkmcnt(14)
	v_pk_fma_f32 v[22:23], v[8:9], v[106:107], v[22:23] neg_lo:[1,0,0] neg_hi:[1,0,0]
	v_pk_fma_f32 v[30:31], v[10:11], v[108:109], v[30:31] neg_lo:[1,0,0] neg_hi:[1,0,0]
	ds_read_b128 v[8:11], v33 offset:32544
	v_pk_fma_f32 v[22:23], v[12:13], v[110:111], v[22:23] neg_lo:[1,0,0] neg_hi:[1,0,0]
	v_pk_fma_f32 v[30:31], v[14:15], v[112:113], v[30:31] neg_lo:[1,0,0] neg_hi:[1,0,0]
	ds_read_b128 v[12:15], v33 offset:32560
	s_waitcnt lgkmcnt(14)
	v_pk_fma_f32 v[22:23], v[16:17], v[114:115], v[22:23] neg_lo:[1,0,0] neg_hi:[1,0,0]
	v_pk_fma_f32 v[30:31], v[18:19], v[116:117], v[30:31] neg_lo:[1,0,0] neg_hi:[1,0,0]
	ds_read_b128 v[16:19], v33 offset:32576
	v_pk_fma_f32 v[22:23], v[26:27], v[118:119], v[22:23] neg_lo:[1,0,0] neg_hi:[1,0,0]
	v_pk_fma_f32 v[30:31], v[28:29], v[120:121], v[30:31] neg_lo:[1,0,0] neg_hi:[1,0,0]
	ds_read_b128 v[26:29], v33 offset:32592
	s_waitcnt lgkmcnt(14)
	v_pk_fma_f32 v[22:23], v[34:35], v[122:123], v[22:23] neg_lo:[1,0,0] neg_hi:[1,0,0]
	v_pk_fma_f32 v[30:31], v[36:37], v[124:125], v[30:31] neg_lo:[1,0,0] neg_hi:[1,0,0]
	ds_read_b128 v[34:37], v33 offset:32608
	v_pk_fma_f32 v[22:23], v[38:39], v[126:127], v[22:23] neg_lo:[1,0,0] neg_hi:[1,0,0]
	v_pk_fma_f32 v[30:31], v[40:41], v[128:129], v[30:31] neg_lo:[1,0,0] neg_hi:[1,0,0]
	ds_read_b128 v[38:41], v33 offset:32624
	s_waitcnt lgkmcnt(14)
	v_pk_fma_f32 v[22:23], v[42:43], v[130:131], v[22:23] neg_lo:[1,0,0] neg_hi:[1,0,0]
	v_pk_fma_f32 v[30:31], v[44:45], v[132:133], v[30:31] neg_lo:[1,0,0] neg_hi:[1,0,0]
	ds_read_b128 v[42:45], v33 offset:32640
	v_pk_fma_f32 v[22:23], v[46:47], v[134:135], v[22:23] neg_lo:[1,0,0] neg_hi:[1,0,0]
	v_pk_fma_f32 v[30:31], v[48:49], v[136:137], v[30:31] neg_lo:[1,0,0] neg_hi:[1,0,0]
	ds_read_b128 v[46:49], v33 offset:32656
	s_waitcnt lgkmcnt(14)
	v_pk_fma_f32 v[22:23], v[50:51], v[138:139], v[22:23] neg_lo:[1,0,0] neg_hi:[1,0,0]
	v_pk_fma_f32 v[30:31], v[52:53], v[140:141], v[30:31] neg_lo:[1,0,0] neg_hi:[1,0,0]
	ds_read_b128 v[50:53], v33 offset:32672
	v_pk_fma_f32 v[22:23], v[54:55], v[142:143], v[22:23] neg_lo:[1,0,0] neg_hi:[1,0,0]
	v_pk_fma_f32 v[30:31], v[56:57], v[162:163], v[30:31] neg_lo:[1,0,0] neg_hi:[1,0,0]
	ds_read_b128 v[54:57], v33 offset:32688
	s_waitcnt lgkmcnt(14)
	v_pk_fma_f32 v[22:23], v[58:59], v[164:165], v[22:23] neg_lo:[1,0,0] neg_hi:[1,0,0]
	v_pk_fma_f32 v[30:31], v[60:61], v[166:167], v[30:31] neg_lo:[1,0,0] neg_hi:[1,0,0]
	ds_read_b128 v[58:61], v33 offset:32704
	v_pk_fma_f32 v[22:23], v[62:63], v[168:169], v[22:23] neg_lo:[1,0,0] neg_hi:[1,0,0]
	v_pk_fma_f32 v[30:31], v[64:65], v[170:171], v[30:31] neg_lo:[1,0,0] neg_hi:[1,0,0]
	ds_read_b128 v[62:65], v33 offset:32720
	s_waitcnt lgkmcnt(15)
	v_pk_fma_f32 v[22:23], v[66:67], v[172:173], v[22:23] neg_lo:[1,0,0] neg_hi:[1,0,0]
	v_pk_fma_f32 v[30:31], v[68:69], v[174:175], v[30:31] neg_lo:[1,0,0] neg_hi:[1,0,0]
	ds_read_b128 v[66:69], v33 offset:32736
	v_cmp_eq_u32_e32 vcc, 59, v152
	v_pk_add_f32 v[82:83], v[22:23], v[30:31]
	v_add_f32_e32 v174, v82, v83
	v_cvt_pk_bf16_f32 v25, v174, v174
	ds_write_b16 v84, v25 offset:8352
	v_cndmask_b32_e64 v192, 0, 1.0, vcc
	s_waitcnt lgkmcnt(14)
	v_pk_fma_f32 v[22:23], v[0:1], v[98:99], v[192:193] neg_lo:[1,0,0] neg_hi:[1,0,0]
	v_pk_fma_f32 v[30:31], v[2:3], v[100:101], 0 neg_lo:[1,0,0] neg_hi:[1,0,0]
	ds_read_b128 v[0:3], v33 offset:32768
	v_pk_fma_f32 v[22:23], v[4:5], v[102:103], v[22:23] neg_lo:[1,0,0] neg_hi:[1,0,0]
	v_pk_fma_f32 v[30:31], v[6:7], v[104:105], v[30:31] neg_lo:[1,0,0] neg_hi:[1,0,0]
	ds_read_b128 v[4:7], v33 offset:32784
	s_waitcnt lgkmcnt(14)
	v_pk_fma_f32 v[22:23], v[8:9], v[106:107], v[22:23] neg_lo:[1,0,0] neg_hi:[1,0,0]
	v_pk_fma_f32 v[30:31], v[10:11], v[108:109], v[30:31] neg_lo:[1,0,0] neg_hi:[1,0,0]
	ds_read_b128 v[8:11], v33 offset:32800
	v_pk_fma_f32 v[22:23], v[12:13], v[110:111], v[22:23] neg_lo:[1,0,0] neg_hi:[1,0,0]
	v_pk_fma_f32 v[30:31], v[14:15], v[112:113], v[30:31] neg_lo:[1,0,0] neg_hi:[1,0,0]
	ds_read_b128 v[12:15], v33 offset:32816
	s_waitcnt lgkmcnt(14)
	v_pk_fma_f32 v[22:23], v[16:17], v[114:115], v[22:23] neg_lo:[1,0,0] neg_hi:[1,0,0]
	v_pk_fma_f32 v[30:31], v[18:19], v[116:117], v[30:31] neg_lo:[1,0,0] neg_hi:[1,0,0]
	ds_read_b128 v[16:19], v33 offset:32832
	v_pk_fma_f32 v[22:23], v[26:27], v[118:119], v[22:23] neg_lo:[1,0,0] neg_hi:[1,0,0]
	v_pk_fma_f32 v[30:31], v[28:29], v[120:121], v[30:31] neg_lo:[1,0,0] neg_hi:[1,0,0]
	ds_read_b128 v[26:29], v33 offset:32848
	s_waitcnt lgkmcnt(14)
	v_pk_fma_f32 v[22:23], v[34:35], v[122:123], v[22:23] neg_lo:[1,0,0] neg_hi:[1,0,0]
	v_pk_fma_f32 v[30:31], v[36:37], v[124:125], v[30:31] neg_lo:[1,0,0] neg_hi:[1,0,0]
	ds_read_b128 v[34:37], v33 offset:32864
	v_pk_fma_f32 v[22:23], v[38:39], v[126:127], v[22:23] neg_lo:[1,0,0] neg_hi:[1,0,0]
	v_pk_fma_f32 v[30:31], v[40:41], v[128:129], v[30:31] neg_lo:[1,0,0] neg_hi:[1,0,0]
	ds_read_b128 v[38:41], v33 offset:32880
	s_waitcnt lgkmcnt(14)
	v_pk_fma_f32 v[22:23], v[42:43], v[130:131], v[22:23] neg_lo:[1,0,0] neg_hi:[1,0,0]
	v_pk_fma_f32 v[30:31], v[44:45], v[132:133], v[30:31] neg_lo:[1,0,0] neg_hi:[1,0,0]
	ds_read_b128 v[42:45], v33 offset:32896
	v_pk_fma_f32 v[22:23], v[46:47], v[134:135], v[22:23] neg_lo:[1,0,0] neg_hi:[1,0,0]
	v_pk_fma_f32 v[30:31], v[48:49], v[136:137], v[30:31] neg_lo:[1,0,0] neg_hi:[1,0,0]
	ds_read_b128 v[46:49], v33 offset:32912
	s_waitcnt lgkmcnt(14)
	v_pk_fma_f32 v[22:23], v[50:51], v[138:139], v[22:23] neg_lo:[1,0,0] neg_hi:[1,0,0]
	v_pk_fma_f32 v[30:31], v[52:53], v[140:141], v[30:31] neg_lo:[1,0,0] neg_hi:[1,0,0]
	ds_read_b128 v[50:53], v33 offset:32928
	v_pk_fma_f32 v[22:23], v[54:55], v[142:143], v[22:23] neg_lo:[1,0,0] neg_hi:[1,0,0]
	v_pk_fma_f32 v[30:31], v[56:57], v[162:163], v[30:31] neg_lo:[1,0,0] neg_hi:[1,0,0]
	ds_read_b128 v[54:57], v33 offset:32944
	s_waitcnt lgkmcnt(14)
	v_pk_fma_f32 v[22:23], v[58:59], v[164:165], v[22:23] neg_lo:[1,0,0] neg_hi:[1,0,0]
	v_pk_fma_f32 v[30:31], v[60:61], v[166:167], v[30:31] neg_lo:[1,0,0] neg_hi:[1,0,0]
	ds_read_b128 v[58:61], v33 offset:32960
	v_pk_fma_f32 v[22:23], v[62:63], v[168:169], v[22:23] neg_lo:[1,0,0] neg_hi:[1,0,0]
	v_pk_fma_f32 v[30:31], v[64:65], v[170:171], v[30:31] neg_lo:[1,0,0] neg_hi:[1,0,0]
	ds_read_b128 v[62:65], v33 offset:32976
	s_waitcnt lgkmcnt(15)
	v_pk_fma_f32 v[22:23], v[66:67], v[172:173], v[22:23] neg_lo:[1,0,0] neg_hi:[1,0,0]
	v_pk_fma_f32 v[30:31], v[68:69], v[174:175], v[30:31] neg_lo:[1,0,0] neg_hi:[1,0,0]
	ds_read_b128 v[66:69], v33 offset:32992
	v_cmp_eq_u32_e32 vcc, 60, v152
	v_pk_add_f32 v[82:83], v[22:23], v[30:31]
	v_add_f32_e32 v175, v82, v83
	v_cvt_pk_bf16_f32 v25, v175, v175
	ds_write_b16 v84, v25 offset:8496
	v_cndmask_b32_e64 v192, 0, 1.0, vcc
	ds_read_b128 v[70:73], v33 offset:33264
	s_waitcnt lgkmcnt(15)
	v_pk_fma_f32 v[22:23], v[0:1], v[98:99], v[192:193] neg_lo:[1,0,0] neg_hi:[1,0,0]
	v_pk_fma_f32 v[30:31], v[2:3], v[100:101], 0 neg_lo:[1,0,0] neg_hi:[1,0,0]
	ds_read_b128 v[0:3], v33 offset:33024
	v_pk_fma_f32 v[22:23], v[4:5], v[102:103], v[22:23] neg_lo:[1,0,0] neg_hi:[1,0,0]
	v_pk_fma_f32 v[30:31], v[6:7], v[104:105], v[30:31] neg_lo:[1,0,0] neg_hi:[1,0,0]
	ds_read_b128 v[4:7], v33 offset:33040
	s_waitcnt lgkmcnt(15)
	v_pk_fma_f32 v[22:23], v[8:9], v[106:107], v[22:23] neg_lo:[1,0,0] neg_hi:[1,0,0]
	v_pk_fma_f32 v[30:31], v[10:11], v[108:109], v[30:31] neg_lo:[1,0,0] neg_hi:[1,0,0]
	ds_read_b128 v[8:11], v33 offset:33056
	v_pk_fma_f32 v[22:23], v[12:13], v[110:111], v[22:23] neg_lo:[1,0,0] neg_hi:[1,0,0]
	v_pk_fma_f32 v[30:31], v[14:15], v[112:113], v[30:31] neg_lo:[1,0,0] neg_hi:[1,0,0]
	ds_read_b128 v[12:15], v33 offset:33072
	s_waitcnt lgkmcnt(15)
	v_pk_fma_f32 v[22:23], v[16:17], v[114:115], v[22:23] neg_lo:[1,0,0] neg_hi:[1,0,0]
	v_pk_fma_f32 v[30:31], v[18:19], v[116:117], v[30:31] neg_lo:[1,0,0] neg_hi:[1,0,0]
	ds_read_b128 v[16:19], v33 offset:33088
	v_pk_fma_f32 v[22:23], v[26:27], v[118:119], v[22:23] neg_lo:[1,0,0] neg_hi:[1,0,0]
	v_pk_fma_f32 v[30:31], v[28:29], v[120:121], v[30:31] neg_lo:[1,0,0] neg_hi:[1,0,0]
	ds_read_b128 v[26:29], v33 offset:33104
	s_waitcnt lgkmcnt(15)
	v_pk_fma_f32 v[22:23], v[34:35], v[122:123], v[22:23] neg_lo:[1,0,0] neg_hi:[1,0,0]
	v_pk_fma_f32 v[30:31], v[36:37], v[124:125], v[30:31] neg_lo:[1,0,0] neg_hi:[1,0,0]
	ds_read_b128 v[34:37], v33 offset:33120
	v_pk_fma_f32 v[22:23], v[38:39], v[126:127], v[22:23] neg_lo:[1,0,0] neg_hi:[1,0,0]
	v_pk_fma_f32 v[30:31], v[40:41], v[128:129], v[30:31] neg_lo:[1,0,0] neg_hi:[1,0,0]
	ds_read_b128 v[38:41], v33 offset:33136
	s_waitcnt lgkmcnt(15)
	v_pk_fma_f32 v[22:23], v[42:43], v[130:131], v[22:23] neg_lo:[1,0,0] neg_hi:[1,0,0]
	v_pk_fma_f32 v[30:31], v[44:45], v[132:133], v[30:31] neg_lo:[1,0,0] neg_hi:[1,0,0]
	ds_read_b128 v[42:45], v33 offset:33152
	v_pk_fma_f32 v[22:23], v[46:47], v[134:135], v[22:23] neg_lo:[1,0,0] neg_hi:[1,0,0]
	v_pk_fma_f32 v[30:31], v[48:49], v[136:137], v[30:31] neg_lo:[1,0,0] neg_hi:[1,0,0]
	ds_read_b128 v[46:49], v33 offset:33168
	s_waitcnt lgkmcnt(15)
	v_pk_fma_f32 v[22:23], v[50:51], v[138:139], v[22:23] neg_lo:[1,0,0] neg_hi:[1,0,0]
	v_pk_fma_f32 v[30:31], v[52:53], v[140:141], v[30:31] neg_lo:[1,0,0] neg_hi:[1,0,0]
	ds_read_b128 v[50:53], v33 offset:33184
	v_pk_fma_f32 v[22:23], v[54:55], v[142:143], v[22:23] neg_lo:[1,0,0] neg_hi:[1,0,0]
	v_pk_fma_f32 v[30:31], v[56:57], v[162:163], v[30:31] neg_lo:[1,0,0] neg_hi:[1,0,0]
	ds_read_b128 v[54:57], v33 offset:33200
	s_waitcnt lgkmcnt(15)
	v_pk_fma_f32 v[22:23], v[58:59], v[164:165], v[22:23] neg_lo:[1,0,0] neg_hi:[1,0,0]
	v_pk_fma_f32 v[30:31], v[60:61], v[166:167], v[30:31] neg_lo:[1,0,0] neg_hi:[1,0,0]
	ds_read_b128 v[58:61], v33 offset:33216
	v_pk_fma_f32 v[22:23], v[62:63], v[168:169], v[22:23] neg_lo:[1,0,0] neg_hi:[1,0,0]
	v_pk_fma_f32 v[30:31], v[64:65], v[170:171], v[30:31] neg_lo:[1,0,0] neg_hi:[1,0,0]
	ds_read_b128 v[62:65], v33 offset:33232
	s_waitcnt lgkmcnt(15)
	v_pk_fma_f32 v[22:23], v[66:67], v[172:173], v[22:23] neg_lo:[1,0,0] neg_hi:[1,0,0]
	v_pk_fma_f32 v[30:31], v[68:69], v[174:175], v[30:31] neg_lo:[1,0,0] neg_hi:[1,0,0]
	ds_read_b128 v[66:69], v33 offset:33248
	v_cmp_eq_u32_e32 vcc, 61, v152
	v_pk_add_f32 v[82:83], v[22:23], v[30:31]
	v_add_f32_e32 v176, v82, v83
	v_cvt_pk_bf16_f32 v25, v176, v176
	ds_write_b16 v84, v25 offset:8640
	v_cndmask_b32_e64 v192, 0, 1.0, vcc
	s_waitcnt lgkmcnt(14)
	v_pk_fma_f32 v[22:23], v[0:1], v[98:99], v[192:193] neg_lo:[1,0,0] neg_hi:[1,0,0]
	v_pk_fma_f32 v[30:31], v[2:3], v[100:101], 0 neg_lo:[1,0,0] neg_hi:[1,0,0]
	ds_read_b128 v[0:3], v33 offset:33280
	v_pk_fma_f32 v[22:23], v[4:5], v[102:103], v[22:23] neg_lo:[1,0,0] neg_hi:[1,0,0]
	v_pk_fma_f32 v[30:31], v[6:7], v[104:105], v[30:31] neg_lo:[1,0,0] neg_hi:[1,0,0]
	ds_read_b128 v[4:7], v33 offset:33296
	s_waitcnt lgkmcnt(14)
	v_pk_fma_f32 v[22:23], v[8:9], v[106:107], v[22:23] neg_lo:[1,0,0] neg_hi:[1,0,0]
	v_pk_fma_f32 v[30:31], v[10:11], v[108:109], v[30:31] neg_lo:[1,0,0] neg_hi:[1,0,0]
	ds_read_b128 v[8:11], v33 offset:33312
	v_pk_fma_f32 v[22:23], v[12:13], v[110:111], v[22:23] neg_lo:[1,0,0] neg_hi:[1,0,0]
	v_pk_fma_f32 v[30:31], v[14:15], v[112:113], v[30:31] neg_lo:[1,0,0] neg_hi:[1,0,0]
	ds_read_b128 v[12:15], v33 offset:33328
	s_waitcnt lgkmcnt(14)
	v_pk_fma_f32 v[22:23], v[16:17], v[114:115], v[22:23] neg_lo:[1,0,0] neg_hi:[1,0,0]
	v_pk_fma_f32 v[30:31], v[18:19], v[116:117], v[30:31] neg_lo:[1,0,0] neg_hi:[1,0,0]
	ds_read_b128 v[16:19], v33 offset:33344
	v_pk_fma_f32 v[22:23], v[26:27], v[118:119], v[22:23] neg_lo:[1,0,0] neg_hi:[1,0,0]
	v_pk_fma_f32 v[30:31], v[28:29], v[120:121], v[30:31] neg_lo:[1,0,0] neg_hi:[1,0,0]
	ds_read_b128 v[26:29], v33 offset:33360
	s_waitcnt lgkmcnt(14)
	v_pk_fma_f32 v[22:23], v[34:35], v[122:123], v[22:23] neg_lo:[1,0,0] neg_hi:[1,0,0]
	v_pk_fma_f32 v[30:31], v[36:37], v[124:125], v[30:31] neg_lo:[1,0,0] neg_hi:[1,0,0]
	ds_read_b128 v[34:37], v33 offset:33376
	v_pk_fma_f32 v[22:23], v[38:39], v[126:127], v[22:23] neg_lo:[1,0,0] neg_hi:[1,0,0]
	v_pk_fma_f32 v[30:31], v[40:41], v[128:129], v[30:31] neg_lo:[1,0,0] neg_hi:[1,0,0]
	ds_read_b128 v[38:41], v33 offset:33392
	s_waitcnt lgkmcnt(14)
	v_pk_fma_f32 v[22:23], v[42:43], v[130:131], v[22:23] neg_lo:[1,0,0] neg_hi:[1,0,0]
	v_pk_fma_f32 v[30:31], v[44:45], v[132:133], v[30:31] neg_lo:[1,0,0] neg_hi:[1,0,0]
	ds_read_b128 v[42:45], v33 offset:33408
	v_pk_fma_f32 v[22:23], v[46:47], v[134:135], v[22:23] neg_lo:[1,0,0] neg_hi:[1,0,0]
	v_pk_fma_f32 v[30:31], v[48:49], v[136:137], v[30:31] neg_lo:[1,0,0] neg_hi:[1,0,0]
	ds_read_b128 v[46:49], v33 offset:33424
	s_waitcnt lgkmcnt(14)
	v_pk_fma_f32 v[22:23], v[50:51], v[138:139], v[22:23] neg_lo:[1,0,0] neg_hi:[1,0,0]
	v_pk_fma_f32 v[30:31], v[52:53], v[140:141], v[30:31] neg_lo:[1,0,0] neg_hi:[1,0,0]
	ds_read_b128 v[50:53], v33 offset:33440
	v_pk_fma_f32 v[22:23], v[54:55], v[142:143], v[22:23] neg_lo:[1,0,0] neg_hi:[1,0,0]
	v_pk_fma_f32 v[30:31], v[56:57], v[162:163], v[30:31] neg_lo:[1,0,0] neg_hi:[1,0,0]
	ds_read_b128 v[54:57], v33 offset:33456
	s_waitcnt lgkmcnt(14)
	v_pk_fma_f32 v[22:23], v[58:59], v[164:165], v[22:23] neg_lo:[1,0,0] neg_hi:[1,0,0]
	v_pk_fma_f32 v[30:31], v[60:61], v[166:167], v[30:31] neg_lo:[1,0,0] neg_hi:[1,0,0]
	ds_read_b128 v[58:61], v33 offset:33472
	v_pk_fma_f32 v[22:23], v[62:63], v[168:169], v[22:23] neg_lo:[1,0,0] neg_hi:[1,0,0]
	v_pk_fma_f32 v[30:31], v[64:65], v[170:171], v[30:31] neg_lo:[1,0,0] neg_hi:[1,0,0]
	ds_read_b128 v[62:65], v33 offset:33488
	s_waitcnt lgkmcnt(15)
	v_pk_fma_f32 v[22:23], v[66:67], v[172:173], v[22:23] neg_lo:[1,0,0] neg_hi:[1,0,0]
	v_pk_fma_f32 v[30:31], v[68:69], v[174:175], v[30:31] neg_lo:[1,0,0] neg_hi:[1,0,0]
	ds_read_b128 v[66:69], v33 offset:33504
	v_pk_fma_f32 v[22:23], v[70:71], v[176:177], v[22:23] neg_lo:[1,0,0] neg_hi:[1,0,0]
	v_pk_fma_f32 v[30:31], v[72:73], v[178:179], v[30:31] neg_lo:[1,0,0] neg_hi:[1,0,0]
	ds_read_b128 v[70:73], v33 offset:33520
	v_cmp_eq_u32_e32 vcc, 62, v152
	v_pk_add_f32 v[82:83], v[22:23], v[30:31]
	v_add_f32_e32 v177, v82, v83
	v_cvt_pk_bf16_f32 v25, v177, v177
	ds_write_b16 v84, v25 offset:8784
	v_cndmask_b32_e64 v192, 0, 1.0, vcc
	s_waitcnt lgkmcnt(15)
	v_pk_fma_f32 v[22:23], v[0:1], v[98:99], v[192:193] neg_lo:[1,0,0] neg_hi:[1,0,0]
	v_pk_fma_f32 v[30:31], v[2:3], v[100:101], 0 neg_lo:[1,0,0] neg_hi:[1,0,0]
	ds_read_b128 v[0:3], v33 offset:33536
	v_pk_fma_f32 v[22:23], v[4:5], v[102:103], v[22:23] neg_lo:[1,0,0] neg_hi:[1,0,0]
	v_pk_fma_f32 v[30:31], v[6:7], v[104:105], v[30:31] neg_lo:[1,0,0] neg_hi:[1,0,0]
	ds_read_b128 v[4:7], v33 offset:33552
	s_waitcnt lgkmcnt(15)
	v_pk_fma_f32 v[22:23], v[8:9], v[106:107], v[22:23] neg_lo:[1,0,0] neg_hi:[1,0,0]
	v_pk_fma_f32 v[30:31], v[10:11], v[108:109], v[30:31] neg_lo:[1,0,0] neg_hi:[1,0,0]
	ds_read_b128 v[8:11], v33 offset:33568
	v_pk_fma_f32 v[22:23], v[12:13], v[110:111], v[22:23] neg_lo:[1,0,0] neg_hi:[1,0,0]
	v_pk_fma_f32 v[30:31], v[14:15], v[112:113], v[30:31] neg_lo:[1,0,0] neg_hi:[1,0,0]
	ds_read_b128 v[12:15], v33 offset:33584
	s_waitcnt lgkmcnt(15)
	v_pk_fma_f32 v[22:23], v[16:17], v[114:115], v[22:23] neg_lo:[1,0,0] neg_hi:[1,0,0]
	v_pk_fma_f32 v[30:31], v[18:19], v[116:117], v[30:31] neg_lo:[1,0,0] neg_hi:[1,0,0]
	ds_read_b128 v[16:19], v33 offset:33600
	v_pk_fma_f32 v[22:23], v[26:27], v[118:119], v[22:23] neg_lo:[1,0,0] neg_hi:[1,0,0]
	v_pk_fma_f32 v[30:31], v[28:29], v[120:121], v[30:31] neg_lo:[1,0,0] neg_hi:[1,0,0]
	ds_read_b128 v[26:29], v33 offset:33616
	s_waitcnt lgkmcnt(15)
	v_pk_fma_f32 v[22:23], v[34:35], v[122:123], v[22:23] neg_lo:[1,0,0] neg_hi:[1,0,0]
	v_pk_fma_f32 v[30:31], v[36:37], v[124:125], v[30:31] neg_lo:[1,0,0] neg_hi:[1,0,0]
	ds_read_b128 v[34:37], v33 offset:33632
	v_pk_fma_f32 v[22:23], v[38:39], v[126:127], v[22:23] neg_lo:[1,0,0] neg_hi:[1,0,0]
	v_pk_fma_f32 v[30:31], v[40:41], v[128:129], v[30:31] neg_lo:[1,0,0] neg_hi:[1,0,0]
	ds_read_b128 v[38:41], v33 offset:33648
	s_waitcnt lgkmcnt(15)
	v_pk_fma_f32 v[22:23], v[42:43], v[130:131], v[22:23] neg_lo:[1,0,0] neg_hi:[1,0,0]
	v_pk_fma_f32 v[30:31], v[44:45], v[132:133], v[30:31] neg_lo:[1,0,0] neg_hi:[1,0,0]
	ds_read_b128 v[42:45], v33 offset:33664
	v_pk_fma_f32 v[22:23], v[46:47], v[134:135], v[22:23] neg_lo:[1,0,0] neg_hi:[1,0,0]
	v_pk_fma_f32 v[30:31], v[48:49], v[136:137], v[30:31] neg_lo:[1,0,0] neg_hi:[1,0,0]
	ds_read_b128 v[46:49], v33 offset:33680
	s_waitcnt lgkmcnt(15)
	v_pk_fma_f32 v[22:23], v[50:51], v[138:139], v[22:23] neg_lo:[1,0,0] neg_hi:[1,0,0]
	v_pk_fma_f32 v[30:31], v[52:53], v[140:141], v[30:31] neg_lo:[1,0,0] neg_hi:[1,0,0]
	ds_read_b128 v[50:53], v33 offset:33696
	v_pk_fma_f32 v[22:23], v[54:55], v[142:143], v[22:23] neg_lo:[1,0,0] neg_hi:[1,0,0]
	v_pk_fma_f32 v[30:31], v[56:57], v[162:163], v[30:31] neg_lo:[1,0,0] neg_hi:[1,0,0]
	ds_read_b128 v[54:57], v33 offset:33712
	s_waitcnt lgkmcnt(15)
	v_pk_fma_f32 v[22:23], v[58:59], v[164:165], v[22:23] neg_lo:[1,0,0] neg_hi:[1,0,0]
	v_pk_fma_f32 v[30:31], v[60:61], v[166:167], v[30:31] neg_lo:[1,0,0] neg_hi:[1,0,0]
	ds_read_b128 v[58:61], v33 offset:33728
	v_pk_fma_f32 v[22:23], v[62:63], v[168:169], v[22:23] neg_lo:[1,0,0] neg_hi:[1,0,0]
	v_pk_fma_f32 v[30:31], v[64:65], v[170:171], v[30:31] neg_lo:[1,0,0] neg_hi:[1,0,0]
	ds_read_b128 v[62:65], v33 offset:33744
	s_waitcnt lgkmcnt(15)
	v_pk_fma_f32 v[22:23], v[66:67], v[172:173], v[22:23] neg_lo:[1,0,0] neg_hi:[1,0,0]
	v_pk_fma_f32 v[30:31], v[68:69], v[174:175], v[30:31] neg_lo:[1,0,0] neg_hi:[1,0,0]
	ds_read_b128 v[66:69], v33 offset:33760
	v_pk_fma_f32 v[22:23], v[70:71], v[176:177], v[22:23] neg_lo:[1,0,0] neg_hi:[1,0,0]
	v_pk_fma_f32 v[30:31], v[72:73], v[178:179], v[30:31] neg_lo:[1,0,0] neg_hi:[1,0,0]
	ds_read_b128 v[70:73], v33 offset:33776
	v_cmp_eq_u32_e32 vcc, 63, v152
	v_pk_add_f32 v[82:83], v[22:23], v[30:31]
	v_add_f32_e32 v178, v82, v83
	v_cvt_pk_bf16_f32 v25, v178, v178
	ds_write_b16 v84, v25 offset:8928
	v_cndmask_b32_e64 v192, 0, 1.0, vcc
	s_waitcnt lgkmcnt(15)
	v_pk_fma_f32 v[22:23], v[0:1], v[98:99], v[192:193] neg_lo:[1,0,0] neg_hi:[1,0,0]
	v_pk_fma_f32 v[30:31], v[2:3], v[100:101], 0 neg_lo:[1,0,0] neg_hi:[1,0,0]
	v_pk_fma_f32 v[22:23], v[4:5], v[102:103], v[22:23] neg_lo:[1,0,0] neg_hi:[1,0,0]
	v_pk_fma_f32 v[30:31], v[6:7], v[104:105], v[30:31] neg_lo:[1,0,0] neg_hi:[1,0,0]
	s_waitcnt lgkmcnt(13)
	v_pk_fma_f32 v[22:23], v[8:9], v[106:107], v[22:23] neg_lo:[1,0,0] neg_hi:[1,0,0]
	v_pk_fma_f32 v[30:31], v[10:11], v[108:109], v[30:31] neg_lo:[1,0,0] neg_hi:[1,0,0]
	v_pk_fma_f32 v[22:23], v[12:13], v[110:111], v[22:23] neg_lo:[1,0,0] neg_hi:[1,0,0]
	v_pk_fma_f32 v[30:31], v[14:15], v[112:113], v[30:31] neg_lo:[1,0,0] neg_hi:[1,0,0]
	s_waitcnt lgkmcnt(11)
	v_pk_fma_f32 v[22:23], v[16:17], v[114:115], v[22:23] neg_lo:[1,0,0] neg_hi:[1,0,0]
	v_pk_fma_f32 v[30:31], v[18:19], v[116:117], v[30:31] neg_lo:[1,0,0] neg_hi:[1,0,0]
	v_pk_fma_f32 v[22:23], v[26:27], v[118:119], v[22:23] neg_lo:[1,0,0] neg_hi:[1,0,0]
	v_pk_fma_f32 v[30:31], v[28:29], v[120:121], v[30:31] neg_lo:[1,0,0] neg_hi:[1,0,0]
	s_waitcnt lgkmcnt(9)
	v_pk_fma_f32 v[22:23], v[34:35], v[122:123], v[22:23] neg_lo:[1,0,0] neg_hi:[1,0,0]
	v_pk_fma_f32 v[30:31], v[36:37], v[124:125], v[30:31] neg_lo:[1,0,0] neg_hi:[1,0,0]
	v_pk_fma_f32 v[22:23], v[38:39], v[126:127], v[22:23] neg_lo:[1,0,0] neg_hi:[1,0,0]
	v_pk_fma_f32 v[30:31], v[40:41], v[128:129], v[30:31] neg_lo:[1,0,0] neg_hi:[1,0,0]
	s_waitcnt lgkmcnt(7)
	v_pk_fma_f32 v[22:23], v[42:43], v[130:131], v[22:23] neg_lo:[1,0,0] neg_hi:[1,0,0]
	v_pk_fma_f32 v[30:31], v[44:45], v[132:133], v[30:31] neg_lo:[1,0,0] neg_hi:[1,0,0]
	v_pk_fma_f32 v[22:23], v[46:47], v[134:135], v[22:23] neg_lo:[1,0,0] neg_hi:[1,0,0]
	v_pk_fma_f32 v[30:31], v[48:49], v[136:137], v[30:31] neg_lo:[1,0,0] neg_hi:[1,0,0]
	s_waitcnt lgkmcnt(5)
	v_pk_fma_f32 v[22:23], v[50:51], v[138:139], v[22:23] neg_lo:[1,0,0] neg_hi:[1,0,0]
	v_pk_fma_f32 v[30:31], v[52:53], v[140:141], v[30:31] neg_lo:[1,0,0] neg_hi:[1,0,0]
	v_pk_fma_f32 v[22:23], v[54:55], v[142:143], v[22:23] neg_lo:[1,0,0] neg_hi:[1,0,0]
	v_pk_fma_f32 v[30:31], v[56:57], v[162:163], v[30:31] neg_lo:[1,0,0] neg_hi:[1,0,0]
	s_waitcnt lgkmcnt(3)
	v_pk_fma_f32 v[22:23], v[58:59], v[164:165], v[22:23] neg_lo:[1,0,0] neg_hi:[1,0,0]
	v_pk_fma_f32 v[30:31], v[60:61], v[166:167], v[30:31] neg_lo:[1,0,0] neg_hi:[1,0,0]
	v_pk_fma_f32 v[22:23], v[62:63], v[168:169], v[22:23] neg_lo:[1,0,0] neg_hi:[1,0,0]
	v_pk_fma_f32 v[30:31], v[64:65], v[170:171], v[30:31] neg_lo:[1,0,0] neg_hi:[1,0,0]
	s_waitcnt lgkmcnt(1)
	v_pk_fma_f32 v[22:23], v[66:67], v[172:173], v[22:23] neg_lo:[1,0,0] neg_hi:[1,0,0]
	v_pk_fma_f32 v[30:31], v[68:69], v[174:175], v[30:31] neg_lo:[1,0,0] neg_hi:[1,0,0]
	v_pk_fma_f32 v[22:23], v[70:71], v[176:177], v[22:23] neg_lo:[1,0,0] neg_hi:[1,0,0]
	v_pk_fma_f32 v[30:31], v[72:73], v[178:179], v[30:31] neg_lo:[1,0,0] neg_hi:[1,0,0]
	v_pk_add_f32 v[82:83], v[22:23], v[30:31]
	v_add_f32_e32 v179, v82, v83
	v_cvt_pk_bf16_f32 v25, v179, v179
	ds_write_b16 v84, v25 offset:9072
	s_branch .LBB0_227

.LBB0_362:
	v_readlane_b32 s4, v242, 8
	s_waitcnt lgkmcnt(0)
	s_barrier
	v_mbcnt_lo_u32_b32 v0, -1, 0
	v_mbcnt_hi_u32_b32 v0, -1, v0
	s_add_u32 s26, s92, 0x513600
	s_addc_u32 s27, s93, 0
	v_mov_b32_e32 v30, 0
	global_load_dword v32, v30, s[26:27] offset:0 sc1
	global_load_dword v33, v30, s[26:27] offset:256 sc1
	global_load_dword v34, v30, s[26:27] offset:512 sc1
	global_load_dword v35, v30, s[26:27] offset:768 sc1
	global_load_dword v36, v30, s[26:27] offset:1024 sc1
	global_load_dword v37, v30, s[26:27] offset:1280 sc1
	global_load_dword v38, v30, s[26:27] offset:1536 sc1
	global_load_dword v39, v30, s[26:27] offset:1792 sc1
	s_waitcnt vmcnt(0)
	v_mov_b32_e32 v26, -1
	v_mov_b32_e32 v27, 0
	v_min_u32_e32 v26, v26, v32
	v_add_u32_e32 v28, -1, v32
	v_and_b32_e32 v28, v28, v32
	v_or_b32_e32 v27, v27, v28
	v_min_u32_e32 v26, v26, v33
	v_add_u32_e32 v28, -1, v33
	v_and_b32_e32 v28, v28, v33
	v_or_b32_e32 v27, v27, v28
	v_min_u32_e32 v26, v26, v34
	v_add_u32_e32 v28, -1, v34
	v_and_b32_e32 v28, v28, v34
	v_or_b32_e32 v27, v27, v28
	v_min_u32_e32 v26, v26, v35
	v_add_u32_e32 v28, -1, v35
	v_and_b32_e32 v28, v28, v35
	v_or_b32_e32 v27, v27, v28
	v_min_u32_e32 v26, v26, v36
	v_add_u32_e32 v28, -1, v36
	v_and_b32_e32 v28, v28, v36
	v_or_b32_e32 v27, v27, v28
	v_min_u32_e32 v26, v26, v37
	v_add_u32_e32 v28, -1, v37
	v_and_b32_e32 v28, v28, v37
	v_or_b32_e32 v27, v27, v28
	v_min_u32_e32 v26, v26, v38
	v_add_u32_e32 v28, -1, v38
	v_and_b32_e32 v28, v28, v38
	v_or_b32_e32 v27, v27, v28
	v_min_u32_e32 v26, v26, v39
	v_add_u32_e32 v28, -1, v39
	v_and_b32_e32 v28, v28, v39
	v_or_b32_e32 v27, v27, v28
	v_cmp_ne_u32_e32 vcc, 0, v26
	s_nop 1
	v_cndmask_b32_e64 v26, 0, 1, vcc
	v_cmp_eq_u32_e32 vcc, 0, v27
	s_nop 1
	v_cndmask_b32_e32 v26, 0, v26, vcc
	v_mov_b32_e32 v27, 0x23ff8
	ds_write_b32 v27, v26
	v_mov_b32_e32 v28, 0
	ds_write_b32 v27, v28 offset:4
	s_mov_b32 s4, s40
	s_mov_b32 s5, s77
	v_and_b32_e32 v1, 15, v0
	v_lshrrev_b32_e32 v2, 4, v0
	s_lshr_b32 s38, s5, 1
	s_and_b32 s39, s5, 1
	s_lshr_b32 s7, s4, 2
	s_lshl_b32 s7, s7, 5
	s_and_b32 s8, s4, 3
	s_lshl_b32 s9, s7, 14
	s_add_u32 s10, s92, 0x9000000
	s_addc_u32 s11, s93, 0
	s_add_u32 s10, s10, s9
	s_addc_u32 s11, s11, 0
	s_add_u32 s12, s92, 0xb000000
	s_addc_u32 s13, s93, 0
	s_add_u32 s12, s12, s9
	s_addc_u32 s13, s13, 0
	s_add_u32 s14, s92, 0xd000000
	s_addc_u32 s15, s93, 0
	s_add_u32 s14, s14, s9
	s_addc_u32 s15, s15, 0
	s_lshl_b32 s26, s7, 13
	s_add_u32 s18, s92, 0xf000000
	s_addc_u32 s19, s93, 0
	s_add_u32 s18, s18, s26
	s_addc_u32 s19, s19, 0
	s_add_u32 s24, s90, 0x2000000
	s_addc_u32 s25, s91, 0
	s_add_u32 s24, s24, s9
	s_addc_u32 s25, s25, 0
	s_lshl_b32 s26, s8, 6
	s_add_u32 s24, s24, s26
	s_addc_u32 s25, s25, 0
	s_add_u32 s42, s92, 0x500000
	s_addc_u32 s43, s93, 0
	v_and_b32_e32 v26, 31, v0
	v_add_u32_e32 v26, s7, v26
	v_lshlrev_b32_e32 v26, 2, v26
	global_load_dword v24, v26, s[42:43]
	v_mov_b32_e32 v30, 0
	s_lshl_b32 s30, s5, 11
	s_lshl_b32 s31, s5, 10
	s_and_b32 s32, s5, 3
	s_lshl_b32 s32, s32, 10
	s_lshl_b32 s7, s5, 3
	v_add_u32_e32 v26, s7, v2
	v_and_b32_e32 v27, 15, v26
	v_xor_b32_e32 v27, v27, v1
	v_lshlrev_b32_e32 v27, 4, v27
	v_lshl_add_u32 v3, v26, 8, v27
	s_lshl_b32 s7, s5, 3
	s_add_u32 s7, s7, 4
	v_add_u32_e32 v26, s7, v2
	v_and_b32_e32 v27, 15, v26
	v_xor_b32_e32 v27, v27, v1
	v_lshlrev_b32_e32 v27, 4, v27
	v_lshl_add_u32 v4, v26, 8, v27
	v_lshrrev_b32_e32 v28, 3, v0
	v_and_b32_e32 v29, 7, v0
	s_lshl_b32 s7, s5, 4
	v_add_u32_e32 v26, s7, v28
	v_bfe_u32 v27, v26, 1, 3
	v_xor_b32_e32 v27, v27, v29
	v_lshlrev_b32_e32 v27, 4, v27
	v_lshl_add_u32 v5, v26, 7, v27
	s_lshl_b32 s7, s5, 4
	s_add_u32 s7, s7, 8
	v_add_u32_e32 v26, s7, v28
	v_bfe_u32 v27, v26, 1, 3
	v_xor_b32_e32 v27, v27, v29
	v_lshlrev_b32_e32 v27, 4, v27
	v_lshl_add_u32 v6, v26, 7, v27
	s_lshl_b32 s7, s5, 3
	v_add_u32_e32 v26, s7, v28
	v_bfe_u32 v27, v26, 1, 3
	v_xor_b32_e32 v27, v27, v29
	v_lshlrev_b32_e32 v27, 4, v27
	v_lshl_add_u32 v7, v26, 7, v27
	s_and_b32 s7, s5, 3
	s_lshl_b32 s7, s7, 4
	v_lshrrev_b32_e32 v26, 2, v0
	v_add_u32_e32 v26, s7, v26
	v_and_b32_e32 v27, 3, v0
	v_lshlrev_b32_e32 v27, 4, v27
	v_lshl_add_u32 v8, v26, 8, v27
	s_lshl_b32 s7, s39, 4
	v_add_u32_e32 v26, s7, v1
	s_lshl_b32 s8, s38, 4
	v_add_u32_e32 v27, s8, v1
	v_lshlrev_b32_e32 v28, 4, v2
	s_movk_i32 s9, 0x110
	v_mul_lo_u32 v29, v26, s9
	v_add_u32_e32 v10, v29, v28
	v_add_u32_e32 v10, 0x1c000, v10
	v_lshlrev_b32_e32 v31, 3, v2
	s_lshl_b32 s9, s38, 6
	v_add3_u32 v21, v29, v31, s9
	v_add_u32_e32 v21, 0x1c000, v21
	s_movk_i32 s9, 0x90
	v_mul_lo_u32 v29, v26, s9
	v_add_u32_e32 v19, v29, v28
	v_add_u32_e32 v19, 0x1e200, v19
	s_lshl_b32 s9, s38, 5
	v_add3_u32 v20, v29, v31, s9
	v_add_u32_e32 v20, 0x1e200, v20
	v_add_u32_e32 v29, 0, v2
	v_xor_b32_e32 v29, v29, v1
	v_lshlrev_b32_e32 v29, 4, v29
	v_lshl_add_u32 v11, v27, 8, v29
	v_add_u32_e32 v29, 4, v2
	v_xor_b32_e32 v29, v29, v1
	v_lshlrev_b32_e32 v29, 4, v29
	v_lshl_add_u32 v12, v27, 8, v29
	v_add_u32_e32 v29, 8, v2
	v_xor_b32_e32 v29, v29, v1
	v_lshlrev_b32_e32 v29, 4, v29
	v_lshl_add_u32 v13, v27, 8, v29
	v_add_u32_e32 v29, 12, v2
	v_xor_b32_e32 v29, v29, v1
	v_lshlrev_b32_e32 v29, 4, v29
	v_lshl_add_u32 v14, v27, 8, v29
	v_lshrrev_b32_e32 v31, 1, v1
	s_lshl_b32 s9, s38, 5
	v_add_u32_e32 v26, s9, v1
	v_add_u32_e32 v29, 0, v2
	v_xor_b32_e32 v29, v29, v31
	v_lshlrev_b32_e32 v29, 4, v29
	v_lshl_add_u32 v15, v26, 7, v29
	v_add_u32_e32 v15, 0x10000, v15
	v_lshl_add_u32 v17, v27, 7, v29
	v_add_u32_e32 v17, 0x18000, v17
	v_add_u32_e32 v29, 4, v2
	v_xor_b32_e32 v29, v29, v31
	v_lshlrev_b32_e32 v29, 4, v29
	v_lshl_add_u32 v16, v26, 7, v29
	v_add_u32_e32 v16, 0x10000, v16
	v_lshl_add_u32 v18, v27, 7, v29
	v_add_u32_e32 v18, 0x18000, v18
	s_lshl_b32 s9, s38, 10
	v_lshlrev_b32_e32 v29, 8, v2
	v_add_u32_e32 v29, s9, v29
	s_lshl_b32 s9, s39, 5
	v_lshl_add_u32 v29, v1, 1, v29
	v_add_u32_e32 v29, s9, v29
	v_add_u32_e32 v22, 0x1f400, v29
	v_lshlrev_b32_e32 v29, 3, v2
	v_lshl_add_u32 v29, v27, 8, v29
	v_add_u32_e32 v9, s9, v29
	v_mov_b32_e32 v32, 0
	v_mov_b32_e32 v33, 0
	v_mov_b32_e32 v34, 0
	v_mov_b32_e32 v35, 0
	v_lshl_add_u32 v26, s5, 6, v0
	v_lshlrev_b32_e32 v27, 4, v26
	v_add_u32_e32 v27, 0x1c000, v27
	ds_write_b128 v27, v[32:35]
	v_and_b32_e32 v26, 31, v26
	v_lshlrev_b32_e32 v27, 4, v26
	v_add_u32_e32 v27, 0x1e000, v27
	ds_write_b128 v27, v[32:35]
	v_mov_b32_e32 v92, 0
	v_mov_b32_e32 v93, 0
	v_mov_b32_e32 v94, 0
	v_mov_b32_e32 v95, 0
	v_mov_b32_e32 v96, 0
	v_mov_b32_e32 v97, 0
	v_mov_b32_e32 v98, 0
	v_mov_b32_e32 v99, 0
	s_mov_b32 s6, 0
	global_load_dword v25, v30, s[42:43]
	global_load_dword v25, v30, s[42:43]
	global_load_dword v25, v30, s[42:43]
	s_add_i32 m0, s32, 0x1f400
	s_nop 0
	global_load_lds_dwordx4 v8, s[24:25]
	s_add_i32 m0, s30, 0x0
	s_nop 0
	global_load_lds_dwordx4 v3, s[10:11]
	s_add_i32 m0, s30, 0x400
	s_nop 0
	global_load_lds_dwordx4 v4, s[10:11]
	s_add_i32 m0, s30, 0x8000
	s_nop 0
	global_load_lds_dwordx4 v3, s[12:13]
	s_add_i32 m0, s30, 0x8400
	s_nop 0
	global_load_lds_dwordx4 v4, s[12:13]
	global_load_dword v25, v30, s[42:43]
	s_add_i32 m0, s30, 0x10000
	s_nop 0
	global_load_lds_dwordx4 v5, s[14:15]
	s_add_i32 m0, s30, 0x10400
	s_nop 0
	global_load_lds_dwordx4 v6, s[14:15]
	s_add_i32 m0, s31, 0x18000
	s_nop 0
	global_load_lds_dwordx4 v7, s[18:19]
	s_add_u32 s26, s24, 0x4000
	s_addc_u32 s27, s25, 0
	s_add_i32 m0, s32, 0x20400
	s_nop 0
	global_load_lds_dwordx4 v8, s[26:27]
	s_add_u32 s26, s10, 0x4000
	s_addc_u32 s27, s11, 0
	s_add_i32 m0, s30, 0x4000
	s_nop 0
	global_load_lds_dwordx4 v3, s[26:27]
	s_add_i32 m0, s30, 0x4400
	s_nop 0
	global_load_lds_dwordx4 v4, s[26:27]
	s_add_u32 s26, s12, 0x4000
	s_addc_u32 s27, s13, 0
	s_add_i32 m0, s30, 0xc000
	s_nop 0
	global_load_lds_dwordx4 v3, s[26:27]
	s_add_i32 m0, s30, 0xc400
	s_nop 0
	global_load_lds_dwordx4 v4, s[26:27]
	global_load_dword v25, v30, s[42:43]
	s_waitcnt vmcnt(10) lgkmcnt(0)
	s_barrier

.LBB0_689:
	s_waitcnt vmcnt(0)
	v_readfirstlane_b32 s3, v194
	s_cmp_gt_u32 s3, 63
	s_waitcnt lgkmcnt(0)
	s_barrier
	s_cbranch_scc1 .LBB0_743
	v_mbcnt_lo_u32_b32 v0, -1, 0
	v_mbcnt_hi_u32_b32 v0, -1, v0
	s_nop 0
	v_cmp_eq_u32_e32 vcc, 0, v0
	s_and_saveexec_b64 s[6:7], vcc
	s_cbranch_execz .LBB0_742
	v_mov_b32_e32 v20, 0x23ff0
	s_waitcnt vmcnt(0) lgkmcnt(0)
	ds_read_b128 v[20:23], v20
	s_waitcnt lgkmcnt(0)
	v_readfirstlane_b32 s3, v22
	s_nop 0
	s_cmp_eq_u32 s3, 0
	s_cbranch_scc1 .Lfb_slow_0
	v_add_u32_e32 v23, 1, v23
	v_mov_b32_e32 v24, 0x23ffc
	ds_write_b32 v24, v23
	v_mul_lo_u32 v25, v23, v20
	s_getreg_b32 s3, hwreg(HW_REG_XCC_ID, 0, 4)
	s_and_b32 s3, s3, 7
	s_lshl_b32 s3, s3, 8
	s_add_u32 s3, s3, 0x3680
	s_add_u32 s4, s92, 0x510000
	s_addc_u32 s5, s93, 0
	v_mov_b32_e32 v26, s3
	v_mov_b32_e32 v27, 1
	global_atomic_add v26, v27, s[4:5]
	s_mov_b32 s8, 0
.Lfb_spin_0:
	global_load_dword v28, v26, s[4:5] sc1
	s_waitcnt vmcnt(0)
	v_cmp_ge_u32_e32 vcc, v28, v25
	s_cbranch_vccnz .Lfb_done_0
	s_sleep 1
	s_add_u32 s8, s8, 1
	s_cmp_lt_u32 s8, 0x40000
	s_cbranch_scc1 .Lfb_spin_0
.Lfb_done_0:
	buffer_inv sc1
	s_waitcnt vmcnt(0) lgkmcnt(0)
	s_branch .LBB0_742
.Lfb_slow_0:
	s_add_i32 s3, 0, 0x23ff0
	v_mov_b32_e32 v0, s3
	s_waitcnt vmcnt(0) expcnt(0) lgkmcnt(0)
	ds_read_b32 v2, v0
	s_add_i32 s3, 0, 0x23ff4
	v_mov_b32_e32 v0, s3
	ds_read_b32 v0, v0
	s_waitcnt lgkmcnt(1)
	v_cmp_ne_u32_e32 vcc, 0, v2
	s_cbranch_vccnz .LBB0_706
	s_mov_b32 s3, 1
	v_mov_b32_e32 v16, 0
	s_branch .LBB0_694

.LBB0_772:
	s_waitcnt vmcnt(0)
	v_readfirstlane_b32 s0, v194
	s_cmp_gt_u32 s0, 63
	s_waitcnt vmcnt(0)
	s_barrier
	s_cbranch_scc1 .LBB0_826
	v_mbcnt_lo_u32_b32 v0, -1, 0
	v_mbcnt_hi_u32_b32 v0, -1, v0
	s_nop 0
	v_cmp_eq_u32_e32 vcc, 0, v0
	s_and_saveexec_b64 s[0:1], vcc
	s_cbranch_execz .LBB0_825
	v_mov_b32_e32 v20, 0x23ff0
	s_waitcnt vmcnt(0) lgkmcnt(0)
	ds_read_b128 v[20:23], v20
	s_waitcnt lgkmcnt(0)
	v_readfirstlane_b32 s3, v22
	s_nop 0
	s_cmp_eq_u32 s3, 0
	s_cbranch_scc1 .Lfb_slow_1
	v_add_u32_e32 v23, 1, v23
	v_mov_b32_e32 v24, 0x23ffc
	ds_write_b32 v24, v23
	v_mul_lo_u32 v25, v23, v20
	s_getreg_b32 s3, hwreg(HW_REG_XCC_ID, 0, 4)
	s_and_b32 s3, s3, 7
	s_lshl_b32 s3, s3, 8
	s_add_u32 s3, s3, 0x3680
	s_add_u32 s4, s92, 0x510000
	s_addc_u32 s5, s93, 0
	v_mov_b32_e32 v26, s3
	v_mov_b32_e32 v27, 1
	global_atomic_add v26, v27, s[4:5]
	s_mov_b32 s8, 0

.LBB0_1157:
	s_waitcnt vmcnt(0)
	v_readfirstlane_b32 s0, v194
	v_readlane_b32 s62, v241, 5
	s_cmp_gt_u32 s0, 63
	v_readlane_b32 s63, v241, 6
	s_waitcnt lgkmcnt(0)
	s_barrier
	s_cbranch_scc1 .LBB0_1211
	v_mbcnt_lo_u32_b32 v0, -1, 0
	v_mbcnt_hi_u32_b32 v0, -1, v0
	s_nop 0
	v_cmp_eq_u32_e32 vcc, 0, v0
	s_and_saveexec_b64 s[0:1], vcc
	s_cbranch_execz .LBB0_1210
	v_mov_b32_e32 v20, 0x23ff0
	s_waitcnt vmcnt(0) lgkmcnt(0)
	ds_read_b128 v[20:23], v20
	s_waitcnt lgkmcnt(0)
	v_readfirstlane_b32 s3, v22
	s_nop 0
	s_cmp_eq_u32 s3, 0
	s_cbranch_scc1 .Lfb_slow_4
	v_add_u32_e32 v23, 1, v23
	v_mov_b32_e32 v24, 0x23ffc
	ds_write_b32 v24, v23
	v_mul_lo_u32 v25, v23, v20
	s_getreg_b32 s3, hwreg(HW_REG_XCC_ID, 0, 4)
	s_and_b32 s3, s3, 7
	s_lshl_b32 s3, s3, 8
	s_add_u32 s3, s3, 0x3680
	s_add_u32 s4, s92, 0x510000
	s_addc_u32 s5, s93, 0
	v_mov_b32_e32 v26, s3
	v_mov_b32_e32 v27, 1
	global_atomic_add v26, v27, s[4:5]
	s_mov_b32 s8, 0
